# stack1: counted lgkmcnt in GEMM K-loops + residual epilogue loads issued 4 at a time (out-proj, ff2) + gMLP unit loads hoisted with counted vmcnt
# speedup vs baseline: 1.0160x; 1.0091x over previous
; #define WAIT_V0() asm volatile("s_waitcnt vmcnt(0)" ::: "memory")
; #define G_STAGE_A(Ap, buf, kt) do { const char* ab_ = (const char*)(Ap) + (size_t)(kt) * 128; \
;       _Pragma("unroll") for (int i = 0; i < 4; ++i) \
;         __builtin_amdgcn_global_load_lds((const unsigned*)(ab_ + soff[i]), (LDSP unsigned*)(G_SA(buf) + wid * 1024 + i * 8192), 16, 0, 0); } while (0)
; #define G_RDA(AF, buf, ks, mh) do { _Pragma("unroll") for (int m = 0; m < 4; ++m) AF[m] = *(const LDSP bf16x8*)(G_SA(buf) + aoff + ((mh) * 4 + m) * 2048 + (ks) * 1024); } while (0)
; #define G_RDB(BF, buf, ks) do { _Pragma("unroll") for (int n = 0; n < 4; ++n) BF[n] = *(const LDSP bf16x8*)(G_SB(buf) + boff + n * 2048 + (ks) * 1024); } while (0)
; #define G_MMA(AF, BF, mh) do { __builtin_amdgcn_s_setprio(1); \
;             _Pragma("unroll") for (int m = 0; m < 4; ++m) _Pragma("unroll") for (int n = 0; n < 4; ++n) \
;                 acc[(mh) * 4 + m][n] = __builtin_amdgcn_mfma_f32_16x16x32_bf16(BF[n], AF[m], acc[(mh) * 4 + m][n], 0, 0, 0); \
;             __builtin_amdgcn_s_setprio(0); } while (0)
; #define G_SB0() __builtin_amdgcn_sched_barrier(0)
; template <int EK>
; DI void gemm_stream(const Params& p, int l, const bf16_t* __restrict__ A, const bf16_t* __restrict__ Bt, int M, int N, int K, ldsp_t shm) {
;     ...
;             if (t > 0) G_MMA(Ab_, Bk1, 1);
;             G_SB0();
;             if (t + 1 < nt) G_STAGE_A(Ab, cur ^ 1, t + 1);
;             else if (has_next) G_STAGE_A(Ab2, cur ^ 1, 0);
;             G_RDA(Ab_, cur, 0, 1);
;             G_MMA(Aa, Bk0, 0); G_SB0();
;             G_RDA(Aa, cur, 1, 0); G_RDB(Bk1, cur, 1);
;             G_MMA(Ab_, Bk0, 1); G_SB0();
;             G_RDA(Ab_, cur, 1, 1);
;             G_MMA(Aa, Bk1, 0); G_SB0();
;             asm volatile("s_waitcnt lgkmcnt(0)" ::: "memory");
;             WAIT_V0(); __syncthreads();
.LBB0_137:
	v_add_u32_e32 v80, 0x12000, v218
	v_add_u32_e32 v84, 0x12800, v218
	v_add_u32_e32 v88, 0x13000, v218
	v_add_u32_e32 v92, 0x13800, v218
	ds_read_b128 v[80:83], v80
	ds_read_b128 v[84:87], v84
	ds_read_b128 v[88:91], v88
	ds_read_b128 v[92:95], v92
	s_setprio 1
	s_waitcnt lgkmcnt(0)
	v_mfma_f32_16x16x32_bf16 v[0:3], v[160:163], v[188:191], v[0:3]
	v_mfma_f32_16x16x32_bf16 v[4:7], v[164:167], v[188:191], v[4:7]
	v_mfma_f32_16x16x32_bf16 v[8:11], v[168:171], v[188:191], v[8:11]
	v_mfma_f32_16x16x32_bf16 v[12:15], v[172:175], v[188:191], v[12:15]
	v_mfma_f32_16x16x32_bf16 v[16:19], v[160:163], v[180:183], v[16:19]
	v_mfma_f32_16x16x32_bf16 v[20:23], v[164:167], v[180:183], v[20:23]
	v_mfma_f32_16x16x32_bf16 v[24:27], v[168:171], v[180:183], v[24:27]
	v_mfma_f32_16x16x32_bf16 v[28:31], v[172:175], v[180:183], v[28:31]
	v_mfma_f32_16x16x32_bf16 v[32:35], v[160:163], v[184:187], v[32:35]
	v_mfma_f32_16x16x32_bf16 v[36:39], v[164:167], v[184:187], v[36:39]
	v_mfma_f32_16x16x32_bf16 v[40:43], v[168:171], v[184:187], v[40:43]
	v_mfma_f32_16x16x32_bf16 v[44:47], v[172:175], v[184:187], v[44:47]
	v_mfma_f32_16x16x32_bf16 v[48:51], v[160:163], v[176:179], v[48:51]
	v_mfma_f32_16x16x32_bf16 v[52:55], v[164:167], v[176:179], v[52:55]
	v_mfma_f32_16x16x32_bf16 v[56:59], v[168:171], v[176:179], v[56:59]
	v_mfma_f32_16x16x32_bf16 v[60:63], v[172:175], v[176:179], v[60:63]
	s_setprio 0
	v_add_u32_e32 v144, 0x10400, v218
	v_add_u32_e32 v148, 0x10c00, v218
	v_add_u32_e32 v152, 0x11400, v218
	v_add_u32_e32 v156, 0x11c00, v218
	v_add_u32_e32 v176, 0x18400, v219
	v_add_u32_e32 v180, 0x18c00, v219
	v_add_u32_e32 v184, 0x19400, v219
	v_add_u32_e32 v188, 0x19c00, v219
	ds_read_b128 v[144:147], v144
	ds_read_b128 v[148:151], v148
	ds_read_b128 v[152:155], v152
	ds_read_b128 v[156:159], v156
	ds_read_b128 v[176:179], v176
	ds_read_b128 v[180:183], v180
	ds_read_b128 v[184:187], v184
	ds_read_b128 v[188:191], v188
	s_setprio 1
	v_mfma_f32_16x16x32_bf16 v[194:197], v[160:163], v[80:83], v[140:143]
	v_mfma_f32_16x16x32_bf16 v[198:201], v[164:167], v[80:83], v[136:139]
	v_mfma_f32_16x16x32_bf16 v[204:207], v[168:171], v[80:83], v[132:135]
	v_mfma_f32_16x16x32_bf16 v[210:213], v[172:175], v[80:83], v[128:131]
	v_mfma_f32_16x16x32_bf16 v[214:217], v[160:163], v[84:87], v[124:127]
	v_mfma_f32_16x16x32_bf16 v[220:223], v[164:167], v[84:87], v[120:123]
	v_mfma_f32_16x16x32_bf16 v[224:227], v[168:171], v[84:87], v[116:119]
	v_mfma_f32_16x16x32_bf16 v[228:231], v[172:175], v[84:87], v[112:115]
	v_mfma_f32_16x16x32_bf16 v[232:235], v[160:163], v[88:91], v[108:111]
	v_mfma_f32_16x16x32_bf16 v[236:239], v[164:167], v[88:91], v[104:107]
	v_mfma_f32_16x16x32_bf16 v[240:243], v[168:171], v[88:91], v[100:103]
	v_mfma_f32_16x16x32_bf16 v[244:247], v[172:175], v[88:91], v[96:99]
	v_mfma_f32_16x16x32_bf16 v[160:163], v[160:163], v[92:95], v[64:67]
	v_mfma_f32_16x16x32_bf16 v[164:167], v[164:167], v[92:95], v[68:71]
	v_mfma_f32_16x16x32_bf16 v[168:171], v[168:171], v[92:95], v[72:75]
	v_mfma_f32_16x16x32_bf16 v[172:175], v[172:175], v[92:95], v[76:79]
	s_setprio 0
	v_add_u32_e32 v64, 0x12400, v218
	v_add_u32_e32 v68, 0x12c00, v218
	ds_read_b128 v[64:67], v64
	ds_read_b128 v[248:251], v68
	v_add_u32_e32 v68, 0x13400, v218
	v_add_u32_e32 v72, 0x13c00, v218
	ds_read_b128 v[68:71], v68
	ds_read_b128 v[72:75], v72
	s_setprio 1
	s_waitcnt lgkmcnt(0)
	v_mfma_f32_16x16x32_bf16 v[140:143], v[176:179], v[144:147], v[0:3]
	v_mfma_f32_16x16x32_bf16 v[136:139], v[180:183], v[144:147], v[4:7]
	v_mfma_f32_16x16x32_bf16 v[132:135], v[184:187], v[144:147], v[8:11]
	v_mfma_f32_16x16x32_bf16 v[128:131], v[188:191], v[144:147], v[12:15]
	v_mfma_f32_16x16x32_bf16 v[124:127], v[176:179], v[148:151], v[16:19]
	v_mfma_f32_16x16x32_bf16 v[120:123], v[180:183], v[148:151], v[20:23]
	v_mfma_f32_16x16x32_bf16 v[116:119], v[184:187], v[148:151], v[24:27]
	v_mfma_f32_16x16x32_bf16 v[112:115], v[188:191], v[148:151], v[28:31]
	v_mfma_f32_16x16x32_bf16 v[108:111], v[176:179], v[152:155], v[32:35]
	v_mfma_f32_16x16x32_bf16 v[104:107], v[180:183], v[152:155], v[36:39]
	v_mfma_f32_16x16x32_bf16 v[100:103], v[184:187], v[152:155], v[40:43]
	v_mfma_f32_16x16x32_bf16 v[96:99], v[188:191], v[152:155], v[44:47]
	v_mfma_f32_16x16x32_bf16 v[92:95], v[176:179], v[156:159], v[48:51]
	v_mfma_f32_16x16x32_bf16 v[88:91], v[180:183], v[156:159], v[52:55]
	v_mfma_f32_16x16x32_bf16 v[84:87], v[184:187], v[156:159], v[56:59]
	v_mfma_f32_16x16x32_bf16 v[80:83], v[188:191], v[156:159], v[60:63]
	s_setprio 0
	s_waitcnt lgkmcnt(0)
	s_waitcnt vmcnt(0)
	s_waitcnt vmcnt(0)
	s_barrier
;     static DI void run(const f32x4 (&acc)[8][4], const TileCtx& tc, const Params& p, ldsp_t wb) {
;     ...
;         const int cond = tc.brow < NLAT ? (tc.brow >> 12) : 4;
;         const float* gate = p.mod + ((size_t)tc.l * 5 + cond) * 6144 + GI * DM;
;         const int col0 = tc.bcol + tc.wc * 64 + tc.fq * 4;
;         const bool has_next = EK == 1 || tc.l + 1 < DEPTH;
;         const int ln = EK == 1 ? tc.l : (has_next ? tc.l + 1 : tc.l);
;         const float* gnx = (EK == 1 ? p.norm2_g : p.norm1_g) + (size_t)ln * DM + col0;
;         const float* scn = p.mod + ((size_t)ln * 5 + cond) * 6144 + (EK == 1 ? 4 : 1) * DM + col0;
;         float* ssp = p.ss + (size_t)(ln * 2 + (EK == 1 ? 1 : 0)) * NTOK * 16 + (tc.bcol >> 8) * 4 + tc.wc;
;         f32x4 gv[4], av[4];
; #pragma unroll
;         for (int n = 0; n < 4; ++n) {
;             gv[n] = *(const f32x4*)(gate + col0 + n * 16);
;             const f32x4 g1 = *(const f32x4*)(gnx + n * 16), s1 = *(const f32x4*)(scn + n * 16);
;             av[n] = g1 * (1.f + s1);
;         }
; #pragma unroll
;         for (int h = 0; h < 2; ++h) {
; #pragma unroll
;             for (int mm = 0; mm < 4; ++mm) { __builtin_amdgcn_sched_barrier(0);
;                 const int m = h * 4 + mm;
;                 const int row = tc.brow + tc.wr * 128 + m * 16 + tc.fr;
;                 float* xr = xrow_ptr(p, row) + col0;
;                 const float* xs = (EK == 1 && tc.l == 0) ? p.x + (size_t)row * DM + col0 : xr;
;                 float part = 0.f;
; #pragma unroll
;                 for (int n = 0; n < 4; ++n) {
;                     f32x4 xv = *(const f32x4*)(xs + n * 16);
;                     xv += gv[n] * acc[m][n];
;                     *(f32x4*)(xr + n * 16) = xv;
	s_setprio 1
	v_mfma_f32_16x16x32_bf16 v[76:79], v[176:179], v[64:67], v[194:197]
	v_mfma_f32_16x16x32_bf16 v[198:201], v[180:183], v[64:67], v[198:201]
	v_mfma_f32_16x16x32_bf16 v[194:197], v[184:187], v[64:67], v[204:207]
	v_mfma_f32_16x16x32_bf16 v[64:67], v[188:191], v[64:67], v[210:213]
	v_mfma_f32_16x16x32_bf16 v[60:63], v[176:179], v[248:251], v[214:217]
	v_mfma_f32_16x16x32_bf16 v[56:59], v[180:183], v[248:251], v[220:223]
	v_mfma_f32_16x16x32_bf16 v[52:55], v[184:187], v[248:251], v[224:227]
	v_mfma_f32_16x16x32_bf16 v[48:51], v[188:191], v[248:251], v[228:231]
	v_mfma_f32_16x16x32_bf16 v[44:47], v[176:179], v[68:71], v[232:235]
	v_mfma_f32_16x16x32_bf16 v[40:43], v[180:183], v[68:71], v[236:239]
	v_mfma_f32_16x16x32_bf16 v[36:39], v[184:187], v[68:71], v[240:243]
	v_mfma_f32_16x16x32_bf16 v[32:35], v[188:191], v[68:71], v[244:247]
	v_mfma_f32_16x16x32_bf16 v[16:19], v[176:179], v[72:75], v[160:163]
	v_mfma_f32_16x16x32_bf16 v[12:15], v[180:183], v[72:75], v[164:167]
	v_mfma_f32_16x16x32_bf16 v[8:11], v[184:187], v[72:75], v[168:171]
	v_mfma_f32_16x16x32_bf16 v[0:3], v[188:191], v[72:75], v[172:175]
	s_setprio 0
	v_mov_b32_e32 v177, v252
	s_lshl_b32 s41, s88, 8
	s_min_i32 s6, s41, 0x4000
	s_ashr_i32 s6, s6, 12
	v_readlane_b32 s8, v255, 10
	s_lshl_b32 s38, s87, 8
	s_ashr_i32 s7, s6, 31
	s_mul_i32 s39, s8, 5
	s_add_u32 s6, s39, s6
	s_mul_hi_i32 s39, s8, 5
	v_ashrrev_i32_e32 v144, 6, v177
	s_addc_u32 s7, s39, s7
	v_mov_b64_e32 v[4:5], s[66:67]
	v_mov_b32_e32 v6, 0x6000
	v_and_b32_e32 v145, 3, v144
	s_mul_i32 s39, s7, 0x6000
	v_mad_u64_u32 v[4:5], s[6:7], s6, v6, v[4:5]
	v_lshrrev_b32_e32 v6, 2, v177
	v_lshlrev_b32_e32 v172, 6, v145
	v_and_b32_e32 v6, 12, v6
	v_or3_b32 v6, v6, s38, v172
	v_ashrrev_i32_e32 v7, 31, v6
	v_add_u32_e32 v5, s39, v5
	v_lshlrev_b64 v[150:151], 2, v[6:7]
	v_lshl_add_u64 v[4:5], v[4:5], 0, v[150:151]
	v_add_co_u32_e32 v20, vcc, s33, v4
	s_mov_b64 s[6:7], 0x4000
	s_nop 0
	v_addc_co_u32_e32 v21, vcc, 0, v5, vcc
	global_load_dwordx4 v[68:71], v[20:21], off
	v_lshl_add_u64 v[20:21], v[4:5], 0, s[6:7]
	s_movk_i32 s6, 0x2000
	v_lshl_add_u64 v[6:7], s[34:35], 0, v[150:151]
	global_load_dwordx4 v[72:75], v[20:21], off offset:64
	global_load_dwordx4 v[146:149], v[6:7], off
	global_load_dwordx4 v[152:155], v[20:21], off offset:128
	global_load_dwordx4 v[156:159], v[20:21], off offset:192
	v_add_co_u32_e32 v20, vcc, s6, v4
	s_mov_b64 s[6:7], 0x2000
	s_nop 0
	v_addc_co_u32_e32 v21, vcc, 0, v5, vcc
	global_load_dwordx4 v[164:167], v[6:7], off offset:64
	global_load_dwordx4 v[28:31], v[20:21], off
	global_load_dwordx4 v[178:181], v[6:7], off offset:128
	v_lshl_add_u64 v[4:5], v[4:5], 0, s[6:7]
	global_load_dwordx4 v[182:185], v[6:7], off offset:192
	global_load_dwordx4 v[24:27], v[4:5], off offset:64
	global_load_dwordx4 v[20:23], v[4:5], off offset:128
	s_nop 0
	global_load_dwordx4 v[4:7], v[4:5], off offset:192
	s_lshl_b32 s6, s87, 2
	v_xor_b32_e32 v230, 16, v202
	s_ashr_i32 s7, s6, 31
	v_cmp_lt_i32_e32 vcc, v230, v203
	s_lshl_b64 s[6:7], s[6:7], 2
	s_add_u32 s6, s31, s6
	v_cndmask_b32_e32 v160, v202, v230, vcc
	v_cmp_lt_i32_e32 vcc, v209, v203
	v_lshlrev_b32_e32 v170, 2, v160
	v_mov_b32_e32 v160, 0x10000
	v_cndmask_b32_e32 v171, v202, v209, vcc
	v_lshlrev_b32_e32 v192, 2, v145
	s_addc_u32 s7, s45, s7
	v_and_b32_e32 v175, 63, v177
	v_and_b32_e32 v173, 15, v177
	v_lshl_add_u32 v176, v144, 13, v160
	v_lshl_add_u64 v[144:145], s[6:7], 0, v[192:193]
	v_lshlrev_b32_e32 v171, 2, v171
	v_readlane_b32 s9, v255, 11
	s_waitcnt vmcnt(11)
	v_pk_add_f32 v[70:71], v[70:71], 1.0 op_sel_hi:[1,0]
	v_pk_add_f32 v[68:69], v[68:69], 1.0 op_sel_hi:[1,0]
	s_waitcnt vmcnt(10)
	v_pk_add_f32 v[74:75], v[74:75], 1.0 op_sel_hi:[1,0]
	v_pk_add_f32 v[72:73], v[72:73], 1.0 op_sel_hi:[1,0]
	s_waitcnt vmcnt(8)
	v_pk_add_f32 v[154:155], v[154:155], 1.0 op_sel_hi:[1,0]
	v_pk_add_f32 v[168:169], v[152:153], 1.0 op_sel_hi:[1,0]
	s_waitcnt vmcnt(7)
	v_pk_add_f32 v[186:187], v[158:159], 1.0 op_sel_hi:[1,0]
	v_pk_add_f32 v[188:189], v[156:157], 1.0 op_sel_hi:[1,0]
	v_pk_mul_f32 v[160:161], v[148:149], v[70:71]
	v_pk_mul_f32 v[162:163], v[146:147], v[68:69]
	s_waitcnt vmcnt(6)
	v_pk_mul_f32 v[156:157], v[166:167], v[74:75]
	v_pk_mul_f32 v[158:159], v[164:165], v[72:73]
	s_waitcnt vmcnt(4)
	v_pk_mul_f32 v[152:153], v[180:181], v[154:155]
	v_pk_mul_f32 v[154:155], v[178:179], v[168:169]
	s_waitcnt vmcnt(3)
	v_pk_mul_f32 v[146:147], v[184:185], v[186:187]
	v_pk_mul_f32 v[148:149], v[182:183], v[188:189]
	v_ashrrev_i32_e32 v68, 1, v177
	v_and_b32_e32 v174, 0xffffff80, v68
	v_add_u32_e32 v164, s41, v174
	v_or_b32_e32 v166, v164, v173
	v_cmp_gt_i32_e32 vcc, s33, v166
	v_add_u32_e32 v68, 0xffffc000, v166
	v_ashrrev_i32_e32 v167, 31, v166
	v_mov_b32_e32 v70, s71
	v_mov_b32_e32 v71, s55
	v_cndmask_b32_e32 v69, 0, v167, vcc
	v_cndmask_b32_e32 v68, v68, v166, vcc
	v_cndmask_b32_e32 v71, v70, v71, vcc
	v_mov_b32_e32 v70, s70
	v_mov_b32_e32 v72, s54
	v_cndmask_b32_e32 v70, v70, v72, vcc
	v_lshlrev_b64 v[68:69], 12, v[68:69]
	v_readlane_b32 s8, v254, 50
	v_lshl_add_u64 v[68:69], v[70:71], 0, v[68:69]
	v_lshlrev_b64 v[70:71], 12, v[166:167]
	v_readlane_b32 s9, v254, 51
	v_lshl_add_u64 v[168:169], v[68:69], 0, v[150:151]
	v_bfe_u32 v75, v177, 5, 1
	v_lshl_add_u64 v[70:71], s[8:9], 0, v[70:71]
	v_cndmask_b32_e64 v69, v69, v71, s[4:5]
	v_cndmask_b32_e64 v68, v68, v70, s[4:5]
	v_lshl_add_u64 v[72:73], v[68:69], 0, v[150:151]
	global_load_dwordx4 v[68:71], v[72:73], off
	global_load_dwordx4 v[232:235], v[72:73], off offset:64
	global_load_dwordx4 v[236:239], v[72:73], off offset:128
	global_load_dwordx4 v[240:243], v[72:73], off offset:192
	v_cmp_gt_u32_e32 vcc, 16, v175
	v_readlane_b32 s10, v254, 52
	v_readlane_b32 s11, v254, 53
	v_readlane_b32 s12, v254, 54
	v_readlane_b32 s13, v254, 55
	v_readlane_b32 s14, v254, 56
	v_readlane_b32 s15, v254, 57
	v_readlane_b32 s16, v254, 58
	v_readlane_b32 s17, v254, 59
	v_readlane_b32 s18, v254, 60
	v_readlane_b32 s19, v254, 61
	v_readlane_b32 s20, v254, 62
	v_readlane_b32 s21, v254, 63
	v_readlane_b32 s22, v255, 0
	v_readlane_b32 s23, v255, 1
	s_waitcnt vmcnt(3)
; DI unsigned pk2(float a, float b) { f32x2 v = {a, b}; bf2_t r = __builtin_convertvector(v, bf2_t); return __builtin_bit_cast(unsigned, r); }
;     static DI void run(const f32x4 (&acc)[8][4], const TileCtx& tc, const Params& p, ldsp_t wb) {
;     ...
;                 const int row = tc.brow + tc.wr * 128 + m * 16 + tc.fr;
;                 float* xr = xrow_ptr(p, row) + col0;
;                 const float* xs = (EK == 1 && tc.l == 0) ? p.x + (size_t)row * DM + col0 : xr;
;                 float part = 0.f;
; #pragma unroll
;                 for (int n = 0; n < 4; ++n) {
;                     f32x4 xv = *(const f32x4*)(xs + n * 16);
;                     xv += gv[n] * acc[m][n];
;                     *(f32x4*)(xr + n * 16) = xv;
;                     if (has_next) {
;                         part += xv[0] * xv[0] + xv[1] * xv[1] + xv[2] * xv[2] + xv[3] * xv[3];
;                         const f32x4 hv = xv * av[n];
;                         u32x2 w; w[0] = pk2(hv[0], hv[1]); w[1] = pk2(hv[2], hv[3]);
;                         wave_put(wb, mm * 16 + tc.fr, n, tc.fq, w);
;                     }
;                 }
;                 if (has_next) {
;                     part += __shfl_xor(part, 16);
;                     part += __shfl_xor(part, 32);
;                     if (tc.fq == 0) ssp[(size_t)row * 16] = part;
	v_pk_fma_f32 v[68:69], v[140:141], v[28:29], v[68:69]
	s_nop 0
	v_mul_f32_e32 v74, v69, v69
	v_pk_fma_f32 v[70:71], v[142:143], v[30:31], v[70:71]
	v_fmac_f32_e32 v74, v68, v68
	v_fmac_f32_e32 v74, v70, v70
	global_store_dwordx4 v[168:169], v[68:71], off
	v_fmac_f32_e32 v74, v71, v71
	v_lshl_or_b32 v142, v173, 7, v176
	v_pk_mul_f32 v[70:71], v[160:161], v[70:71]
	v_pk_mul_f32 v[68:69], v[162:163], v[68:69]
	v_and_b32_e32 v143, 7, v177
	v_cvt_pk_bf16_f32 v68, v68, v69
	v_cvt_pk_bf16_f32 v69, v70, v71
	v_bitop3_b32 v70, v75, v177, 7 bitop3:0x78
	v_lshl_or_b32 v141, v70, 4, v142
	v_lshrrev_b32_e32 v70, 1, v177
	v_and_b32_e32 v140, 8, v70
	v_or_b32_e32 v70, v141, v140
	ds_write_b64 v70, v[68:69]
	s_nop 1
	s_waitcnt vmcnt(3)
	v_pk_fma_f32 v[68:69], v[136:137], v[24:25], v[232:233]
	s_nop 0
	v_mul_f32_e32 v136, v69, v69
	v_pk_fma_f32 v[70:71], v[138:139], v[26:27], v[234:235]
	v_fmac_f32_e32 v136, v68, v68
	v_fmac_f32_e32 v136, v70, v70
	global_store_dwordx4 v[168:169], v[68:71], off offset:64
	v_fmac_f32_e32 v136, v71, v71
	v_add_f32_e32 v74, v74, v136
	v_pk_mul_f32 v[70:71], v[156:157], v[70:71]
	v_pk_mul_f32 v[68:69], v[158:159], v[68:69]
	s_nop 0
	v_cvt_pk_bf16_f32 v68, v68, v69
	v_cvt_pk_bf16_f32 v69, v70, v71
	v_bitop3_b32 v70, v75, v143, 2 bitop3:0x36
	v_lshl_or_b32 v136, v70, 4, v142
	v_or_b32_e32 v70, v136, v140
	ds_write_b64 v70, v[68:69]
	s_nop 1
	s_waitcnt vmcnt(3)
	v_pk_fma_f32 v[68:69], v[132:133], v[20:21], v[236:237]
	s_nop 0
	v_mul_f32_e32 v132, v69, v69
	v_pk_fma_f32 v[70:71], v[134:135], v[22:23], v[238:239]
	v_fmac_f32_e32 v132, v68, v68
	v_fmac_f32_e32 v132, v70, v70
	global_store_dwordx4 v[168:169], v[68:71], off offset:128
	v_fmac_f32_e32 v132, v71, v71
	v_add_f32_e32 v74, v74, v132
	v_pk_mul_f32 v[70:71], v[152:153], v[70:71]
	v_pk_mul_f32 v[68:69], v[154:155], v[68:69]
	s_nop 0
	v_cvt_pk_bf16_f32 v68, v68, v69
	v_cvt_pk_bf16_f32 v69, v70, v71
	v_bitop3_b32 v70, v75, v143, 4 bitop3:0x36
	v_lshl_or_b32 v133, v70, 4, v142
	v_or_b32_e32 v70, v133, v140
	ds_write_b64 v70, v[68:69]
	s_nop 1
	s_waitcnt vmcnt(3)
	v_pk_fma_f32 v[68:69], v[128:129], v[4:5], v[240:241]
	s_nop 0
	v_mul_f32_e32 v72, v69, v69
	v_pk_fma_f32 v[70:71], v[130:131], v[6:7], v[242:243]
	v_fmac_f32_e32 v72, v68, v68
	v_fmac_f32_e32 v72, v70, v70
	global_store_dwordx4 v[168:169], v[68:71], off offset:192
	v_fmac_f32_e32 v72, v71, v71
	v_add_f32_e32 v72, v74, v72
	v_pk_mul_f32 v[70:71], v[146:147], v[70:71]
	v_pk_mul_f32 v[68:69], v[148:149], v[68:69]
	s_nop 0
	v_cvt_pk_bf16_f32 v68, v68, v69
	v_cvt_pk_bf16_f32 v69, v70, v71
	v_bitop3_b32 v70, v75, v143, 6 bitop3:0x36
	v_lshl_or_b32 v134, v70, 4, v142
	v_or_b32_e32 v70, v134, v140
	ds_write_b64 v70, v[68:69]
	ds_bpermute_b32 v68, v170, v72
	s_waitcnt lgkmcnt(0)
	v_add_f32_e32 v128, v72, v68
	ds_bpermute_b32 v129, v171, v128
	s_and_saveexec_b64 s[6:7], vcc
	s_cbranch_execz .LBB0_139
	v_lshlrev_b64 v[68:69], 6, v[166:167]
	s_waitcnt lgkmcnt(0)
	v_add_f32_e32 v70, v128, v129
	v_lshl_add_u64 v[68:69], v[144:145], 0, v[68:69]
	global_store_dword v[68:69], v70, off
.LBB0_139:
	s_or_b64 exec, exec, s[6:7]
	v_or_b32_e32 v68, s41, v173
	v_add_u32_e32 v132, v174, v68
	v_add_u32_e32 v128, 16, v132
	v_cmp_gt_i32_e64 s[6:7], s33, v128
	v_add_u32_e32 v68, 0xffffc010, v132
	s_waitcnt lgkmcnt(0)
	v_ashrrev_i32_e32 v129, 31, v128
	v_mov_b32_e32 v70, s71
	v_mov_b32_e32 v71, s55
	v_cndmask_b32_e64 v69, 0, v129, s[6:7]
	v_cndmask_b32_e64 v68, v68, v128, s[6:7]
	v_cndmask_b32_e64 v71, v70, v71, s[6:7]
	v_mov_b32_e32 v70, s70
	v_mov_b32_e32 v72, s54
	v_cndmask_b32_e64 v70, v70, v72, s[6:7]
	v_lshlrev_b64 v[68:69], 12, v[68:69]
	v_readlane_b32 s8, v254, 50
	v_lshl_add_u64 v[68:69], v[70:71], 0, v[68:69]
	v_lshlrev_b64 v[70:71], 12, v[128:129]
	v_readlane_b32 s9, v254, 51
	v_lshl_add_u64 v[130:131], v[68:69], 0, v[150:151]
	v_readlane_b32 s10, v254, 52
	v_lshl_add_u64 v[70:71], s[8:9], 0, v[70:71]
	v_cndmask_b32_e64 v69, v69, v71, s[4:5]
	v_cndmask_b32_e64 v68, v68, v70, s[4:5]
	v_lshl_add_u64 v[72:73], v[68:69], 0, v[150:151]
	global_load_dwordx4 v[68:71], v[72:73], off
	global_load_dwordx4 v[232:235], v[72:73], off offset:64
	global_load_dwordx4 v[236:239], v[72:73], off offset:128
	global_load_dwordx4 v[240:243], v[72:73], off offset:192
	v_readlane_b32 s11, v254, 53
	v_readlane_b32 s12, v254, 54
	v_readlane_b32 s13, v254, 55
	v_readlane_b32 s14, v254, 56
	v_readlane_b32 s15, v254, 57
	v_readlane_b32 s16, v254, 58
	v_readlane_b32 s17, v254, 59
	v_readlane_b32 s18, v254, 60
	v_readlane_b32 s19, v254, 61
	v_readlane_b32 s20, v254, 62
	v_readlane_b32 s21, v254, 63
	v_readlane_b32 s22, v255, 0
	v_readlane_b32 s23, v255, 1
	s_waitcnt vmcnt(3)
	v_pk_fma_f32 v[68:69], v[124:125], v[28:29], v[68:69]
	s_nop 0
	v_mul_f32_e32 v74, v69, v69
	v_pk_fma_f32 v[70:71], v[126:127], v[30:31], v[70:71]
	v_fmac_f32_e32 v74, v68, v68
	v_fmac_f32_e32 v74, v70, v70
	global_store_dwordx4 v[130:131], v[68:71], off
	v_fmac_f32_e32 v74, v71, v71
	v_add_u32_e32 v124, v141, v140
	v_pk_mul_f32 v[70:71], v[160:161], v[70:71]
	v_pk_mul_f32 v[68:69], v[162:163], v[68:69]
	s_nop 0
	v_cvt_pk_bf16_f32 v68, v68, v69
	v_cvt_pk_bf16_f32 v69, v70, v71
	ds_write_b64 v124, v[68:69] offset:2048
	s_nop 1
	s_waitcnt vmcnt(3)
	v_pk_fma_f32 v[68:69], v[120:121], v[24:25], v[232:233]
	s_nop 0
	v_mul_f32_e32 v75, v69, v69
	v_pk_fma_f32 v[70:71], v[122:123], v[26:27], v[234:235]
	v_fmac_f32_e32 v75, v68, v68
	v_fmac_f32_e32 v75, v70, v70
	global_store_dwordx4 v[130:131], v[68:71], off offset:64
	v_fmac_f32_e32 v75, v71, v71
	v_add_u32_e32 v120, v136, v140
	v_pk_mul_f32 v[70:71], v[156:157], v[70:71]
	v_pk_mul_f32 v[68:69], v[158:159], v[68:69]
	v_add_f32_e32 v74, v74, v75
	v_cvt_pk_bf16_f32 v68, v68, v69
	v_cvt_pk_bf16_f32 v69, v70, v71
	ds_write_b64 v120, v[68:69] offset:2048
	s_nop 1
	s_waitcnt vmcnt(3)
; DI unsigned pk2(float a, float b) { f32x2 v = {a, b}; bf2_t r = __builtin_convertvector(v, bf2_t); return __builtin_bit_cast(unsigned, r); }
;     static DI void run(const f32x4 (&acc)[8][4], const TileCtx& tc, const Params& p, ldsp_t wb) {
;     ...
;                 const int row = tc.brow + tc.wr * 128 + m * 16 + tc.fr;
;                 float* xr = xrow_ptr(p, row) + col0;
;                 const float* xs = (EK == 1 && tc.l == 0) ? p.x + (size_t)row * DM + col0 : xr;
;                 float part = 0.f;
; #pragma unroll
;                 for (int n = 0; n < 4; ++n) {
;                     f32x4 xv = *(const f32x4*)(xs + n * 16);
;                     xv += gv[n] * acc[m][n];
;                     *(f32x4*)(xr + n * 16) = xv;
;                     if (has_next) {
;                         part += xv[0] * xv[0] + xv[1] * xv[1] + xv[2] * xv[2] + xv[3] * xv[3];
;                         const f32x4 hv = xv * av[n];
;                         u32x2 w; w[0] = pk2(hv[0], hv[1]); w[1] = pk2(hv[2], hv[3]);
;                         wave_put(wb, mm * 16 + tc.fr, n, tc.fq, w);
;                     }
;                 }
;                 if (has_next) {
;                     part += __shfl_xor(part, 16);
;                     part += __shfl_xor(part, 32);
;                     if (tc.fq == 0) ssp[(size_t)row * 16] = part;
	v_pk_fma_f32 v[68:69], v[116:117], v[20:21], v[236:237]
	s_nop 0
	v_mul_f32_e32 v75, v69, v69
	v_pk_fma_f32 v[70:71], v[118:119], v[22:23], v[238:239]
	v_fmac_f32_e32 v75, v68, v68
	v_fmac_f32_e32 v75, v70, v70
	global_store_dwordx4 v[130:131], v[68:71], off offset:128
	v_fmac_f32_e32 v75, v71, v71
	v_add_u32_e32 v116, v133, v140
	v_pk_mul_f32 v[70:71], v[152:153], v[70:71]
	v_pk_mul_f32 v[68:69], v[154:155], v[68:69]
	v_add_f32_e32 v74, v74, v75
	v_cvt_pk_bf16_f32 v68, v68, v69
	v_cvt_pk_bf16_f32 v69, v70, v71
	ds_write_b64 v116, v[68:69] offset:2048
	s_nop 1
	v_add_u32_e32 v117, v134, v140
	s_waitcnt vmcnt(3)
	v_pk_fma_f32 v[68:69], v[112:113], v[4:5], v[240:241]
	s_nop 0
	v_mul_f32_e32 v72, v69, v69
	v_pk_fma_f32 v[70:71], v[114:115], v[6:7], v[242:243]
	v_fmac_f32_e32 v72, v68, v68
	v_fmac_f32_e32 v72, v70, v70
	global_store_dwordx4 v[130:131], v[68:71], off offset:192
	v_fmac_f32_e32 v72, v71, v71
	v_add_f32_e32 v72, v74, v72
	v_pk_mul_f32 v[70:71], v[146:147], v[70:71]
	v_pk_mul_f32 v[68:69], v[148:149], v[68:69]
	s_nop 0
	v_cvt_pk_bf16_f32 v68, v68, v69
	v_cvt_pk_bf16_f32 v69, v70, v71
	ds_write_b64 v117, v[68:69] offset:2048
	ds_bpermute_b32 v68, v170, v72
	s_waitcnt lgkmcnt(0)
	v_add_f32_e32 v112, v72, v68
	ds_bpermute_b32 v113, v171, v112
	s_and_saveexec_b64 s[6:7], vcc
	s_cbranch_execz .LBB0_141
	v_lshlrev_b64 v[68:69], 6, v[128:129]
	s_waitcnt lgkmcnt(0)
	v_add_f32_e32 v70, v112, v113
	v_lshl_add_u64 v[68:69], v[144:145], 0, v[68:69]
	global_store_dword v[68:69], v70, off
.LBB0_141:
	s_or_b64 exec, exec, s[6:7]
	v_add_u32_e32 v112, 32, v132
	v_cmp_gt_i32_e64 s[6:7], s33, v112
	v_add_u32_e32 v68, 0xffffc020, v132
	s_waitcnt lgkmcnt(0)
	v_ashrrev_i32_e32 v113, 31, v112
	v_mov_b32_e32 v70, s71
	v_mov_b32_e32 v71, s55
	v_cndmask_b32_e64 v69, 0, v113, s[6:7]
	v_cndmask_b32_e64 v68, v68, v112, s[6:7]
	v_cndmask_b32_e64 v71, v70, v71, s[6:7]
	v_mov_b32_e32 v70, s70
	v_mov_b32_e32 v72, s54
	v_cndmask_b32_e64 v70, v70, v72, s[6:7]
	v_lshlrev_b64 v[68:69], 12, v[68:69]
	v_readlane_b32 s8, v254, 50
	v_lshl_add_u64 v[68:69], v[70:71], 0, v[68:69]
	v_lshlrev_b64 v[70:71], 12, v[112:113]
	v_readlane_b32 s9, v254, 51
	v_lshl_add_u64 v[114:115], v[68:69], 0, v[150:151]
	v_readlane_b32 s10, v254, 52
	v_lshl_add_u64 v[70:71], s[8:9], 0, v[70:71]
	v_cndmask_b32_e64 v69, v69, v71, s[4:5]
	v_cndmask_b32_e64 v68, v68, v70, s[4:5]
	v_lshl_add_u64 v[72:73], v[68:69], 0, v[150:151]
	global_load_dwordx4 v[68:71], v[72:73], off
	global_load_dwordx4 v[232:235], v[72:73], off offset:64
	global_load_dwordx4 v[236:239], v[72:73], off offset:128
	global_load_dwordx4 v[240:243], v[72:73], off offset:192
	v_readlane_b32 s11, v254, 53
	v_readlane_b32 s12, v254, 54
	v_readlane_b32 s13, v254, 55
	v_readlane_b32 s14, v254, 56
	v_readlane_b32 s15, v254, 57
	v_readlane_b32 s16, v254, 58
	v_readlane_b32 s17, v254, 59
	v_readlane_b32 s18, v254, 60
	v_readlane_b32 s19, v254, 61
	v_readlane_b32 s20, v254, 62
	v_readlane_b32 s21, v254, 63
	v_readlane_b32 s22, v255, 0
	v_readlane_b32 s23, v255, 1
	s_waitcnt vmcnt(3)
	v_pk_fma_f32 v[68:69], v[108:109], v[28:29], v[68:69]
	s_nop 0
	v_mul_f32_e32 v74, v69, v69
	v_pk_fma_f32 v[70:71], v[110:111], v[30:31], v[70:71]
	v_fmac_f32_e32 v74, v68, v68
	v_fmac_f32_e32 v74, v70, v70
	global_store_dwordx4 v[114:115], v[68:71], off
	v_fmac_f32_e32 v74, v71, v71
	s_nop 0
	v_pk_mul_f32 v[70:71], v[160:161], v[70:71]
	v_pk_mul_f32 v[68:69], v[162:163], v[68:69]
	s_nop 0
	v_cvt_pk_bf16_f32 v68, v68, v69
	v_cvt_pk_bf16_f32 v69, v70, v71
	ds_write_b64 v124, v[68:69] offset:4096
	s_nop 1
	s_waitcnt vmcnt(3)
	v_pk_fma_f32 v[68:69], v[104:105], v[24:25], v[232:233]
	s_nop 0
	v_mul_f32_e32 v75, v69, v69
	v_pk_fma_f32 v[70:71], v[106:107], v[26:27], v[234:235]
	v_fmac_f32_e32 v75, v68, v68
	v_fmac_f32_e32 v75, v70, v70
	global_store_dwordx4 v[114:115], v[68:71], off offset:64
	v_fmac_f32_e32 v75, v71, v71
	v_add_f32_e32 v74, v74, v75
	v_pk_mul_f32 v[70:71], v[156:157], v[70:71]
	v_pk_mul_f32 v[68:69], v[158:159], v[68:69]
	s_nop 0
	v_cvt_pk_bf16_f32 v68, v68, v69
	v_cvt_pk_bf16_f32 v69, v70, v71
	ds_write_b64 v120, v[68:69] offset:4096
	s_nop 1
	s_waitcnt vmcnt(3)
	v_pk_fma_f32 v[68:69], v[100:101], v[20:21], v[236:237]
	s_nop 0
	v_mul_f32_e32 v75, v69, v69
	v_pk_fma_f32 v[70:71], v[102:103], v[22:23], v[238:239]
	v_fmac_f32_e32 v75, v68, v68
	v_fmac_f32_e32 v75, v70, v70
	global_store_dwordx4 v[114:115], v[68:71], off offset:128
	v_fmac_f32_e32 v75, v71, v71
	v_add_f32_e32 v74, v74, v75
	v_pk_mul_f32 v[70:71], v[152:153], v[70:71]
	v_pk_mul_f32 v[68:69], v[154:155], v[68:69]
	s_nop 0
	v_cvt_pk_bf16_f32 v68, v68, v69
	v_cvt_pk_bf16_f32 v69, v70, v71
	ds_write_b64 v116, v[68:69] offset:4096
	s_nop 1
	s_waitcnt vmcnt(3)
	v_pk_fma_f32 v[68:69], v[96:97], v[4:5], v[240:241]
	s_nop 0
	v_mul_f32_e32 v72, v69, v69
	v_pk_fma_f32 v[70:71], v[98:99], v[6:7], v[242:243]
	v_fmac_f32_e32 v72, v68, v68
	v_fmac_f32_e32 v72, v70, v70
	global_store_dwordx4 v[114:115], v[68:71], off offset:192
	v_fmac_f32_e32 v72, v71, v71
	v_add_f32_e32 v72, v74, v72
	v_pk_mul_f32 v[70:71], v[146:147], v[70:71]
	v_pk_mul_f32 v[68:69], v[148:149], v[68:69]
	s_nop 0
	v_cvt_pk_bf16_f32 v68, v68, v69
	v_cvt_pk_bf16_f32 v69, v70, v71
	ds_write_b64 v117, v[68:69] offset:4096
	ds_bpermute_b32 v68, v170, v72
	s_waitcnt lgkmcnt(0)
	v_add_f32_e32 v96, v72, v68
	ds_bpermute_b32 v97, v171, v96
	s_and_saveexec_b64 s[6:7], vcc
	s_cbranch_execz .LBB0_143
	v_lshlrev_b64 v[68:69], 6, v[112:113]
	s_waitcnt lgkmcnt(0)
	v_add_f32_e32 v70, v96, v97
	v_lshl_add_u64 v[68:69], v[144:145], 0, v[68:69]
	global_store_dword v[68:69], v70, off
; #define LDSP __attribute__((address_space(3)))
; DI unsigned pk2(float a, float b) { f32x2 v = {a, b}; bf2_t r = __builtin_convertvector(v, bf2_t); return __builtin_bit_cast(unsigned, r); }
; DI void wave_rows_store(ldsp_t wb, int lane, bf16_t* dst0, size_t ld) {
; #pragma unroll
;     for (int i = 0; i < 8; ++i) {
;         const int row = i * 8 + (lane >> 3), ch = lane & 7;
;         const u32x4 v = *(const LDSP u32x4*)(wb + row * 128 + ((ch ^ (row & 7)) << 4));
;         *(u32x4*)(dst0 + (size_t)row * ld + ch * 8) = v;
;     }
;     static DI void run(const f32x4 (&acc)[8][4], const TileCtx& tc, const Params& p, ldsp_t wb) {
;     ...
;                 const int row = tc.brow + tc.wr * 128 + m * 16 + tc.fr;
;                 float* xr = xrow_ptr(p, row) + col0;
;                 const float* xs = (EK == 1 && tc.l == 0) ? p.x + (size_t)row * DM + col0 : xr;
;                 float part = 0.f;
; #pragma unroll
;                 for (int n = 0; n < 4; ++n) {
;                     f32x4 xv = *(const f32x4*)(xs + n * 16);
;                     xv += gv[n] * acc[m][n];
;                     *(f32x4*)(xr + n * 16) = xv;
;                     if (has_next) {
;                         part += xv[0] * xv[0] + xv[1] * xv[1] + xv[2] * xv[2] + xv[3] * xv[3];
;                         const f32x4 hv = xv * av[n];
;                         u32x2 w; w[0] = pk2(hv[0], hv[1]); w[1] = pk2(hv[2], hv[3]);
;                         wave_put(wb, mm * 16 + tc.fr, n, tc.fq, w);
;                     }
;                 }
;                 if (has_next) {
;                     part += __shfl_xor(part, 16);
;                     part += __shfl_xor(part, 32);
;                     if (tc.fq == 0) ssp[(size_t)row * 16] = part;
;                 }
;             }
;             if (has_next) wave_rows_store(wb, tc.lane, p.H + (size_t)(tc.brow + tc.wr * 128 + h * 64) * DM + tc.bcol + tc.wc * 64, DM);
.LBB0_143:
	s_or_b64 exec, exec, s[6:7]
	v_add_u32_e32 v96, 48, v132
	v_cmp_gt_i32_e64 s[6:7], s33, v96
	v_add_u32_e32 v68, 0xffffc030, v132
	s_waitcnt lgkmcnt(0)
	v_ashrrev_i32_e32 v97, 31, v96
	v_mov_b32_e32 v70, s71
	v_mov_b32_e32 v71, s55
	v_cndmask_b32_e64 v69, 0, v97, s[6:7]
	v_cndmask_b32_e64 v68, v68, v96, s[6:7]
	v_cndmask_b32_e64 v71, v70, v71, s[6:7]
	v_mov_b32_e32 v70, s70
	v_mov_b32_e32 v72, s54
	v_cndmask_b32_e64 v70, v70, v72, s[6:7]
	v_lshlrev_b64 v[68:69], 12, v[68:69]
	v_readlane_b32 s8, v254, 50
	v_lshl_add_u64 v[68:69], v[70:71], 0, v[68:69]
	v_lshlrev_b64 v[70:71], 12, v[96:97]
	v_readlane_b32 s9, v254, 51
	v_lshl_add_u64 v[98:99], v[68:69], 0, v[150:151]
	v_readlane_b32 s10, v254, 52
	v_lshl_add_u64 v[70:71], s[8:9], 0, v[70:71]
	v_cndmask_b32_e64 v69, v69, v71, s[4:5]
	v_cndmask_b32_e64 v68, v68, v70, s[4:5]
	v_lshl_add_u64 v[72:73], v[68:69], 0, v[150:151]
	global_load_dwordx4 v[68:71], v[72:73], off
	global_load_dwordx4 v[232:235], v[72:73], off offset:64
	global_load_dwordx4 v[236:239], v[72:73], off offset:128
	global_load_dwordx4 v[240:243], v[72:73], off offset:192
	v_readlane_b32 s11, v254, 53
	v_readlane_b32 s12, v254, 54
	v_readlane_b32 s13, v254, 55
	v_readlane_b32 s14, v254, 56
	v_readlane_b32 s15, v254, 57
	v_readlane_b32 s16, v254, 58
	v_readlane_b32 s17, v254, 59
	v_readlane_b32 s18, v254, 60
	v_readlane_b32 s19, v254, 61
	v_readlane_b32 s20, v254, 62
	v_readlane_b32 s21, v254, 63
	v_readlane_b32 s22, v255, 0
	v_readlane_b32 s23, v255, 1
	s_waitcnt vmcnt(3)
	v_pk_fma_f32 v[68:69], v[92:93], v[28:29], v[68:69]
	s_nop 0
	v_mul_f32_e32 v74, v69, v69
	v_pk_fma_f32 v[70:71], v[94:95], v[30:31], v[70:71]
	v_fmac_f32_e32 v74, v68, v68
	v_fmac_f32_e32 v74, v70, v70
	global_store_dwordx4 v[98:99], v[68:71], off
	v_fmac_f32_e32 v74, v71, v71
	s_nop 0
	v_pk_mul_f32 v[70:71], v[160:161], v[70:71]
	v_pk_mul_f32 v[68:69], v[162:163], v[68:69]
	s_nop 0
	v_cvt_pk_bf16_f32 v68, v68, v69
	v_cvt_pk_bf16_f32 v69, v70, v71
	ds_write_b64 v124, v[68:69] offset:6144
	s_nop 1
	s_waitcnt vmcnt(3)
	v_pk_fma_f32 v[68:69], v[88:89], v[24:25], v[232:233]
	s_nop 0
	v_mul_f32_e32 v75, v69, v69
	v_pk_fma_f32 v[70:71], v[90:91], v[26:27], v[234:235]
	v_fmac_f32_e32 v75, v68, v68
	v_fmac_f32_e32 v75, v70, v70
	global_store_dwordx4 v[98:99], v[68:71], off offset:64
	v_fmac_f32_e32 v75, v71, v71
	v_add_f32_e32 v74, v74, v75
	v_pk_mul_f32 v[70:71], v[156:157], v[70:71]
	v_pk_mul_f32 v[68:69], v[158:159], v[68:69]
	s_nop 0
	v_cvt_pk_bf16_f32 v68, v68, v69
	v_cvt_pk_bf16_f32 v69, v70, v71
	ds_write_b64 v120, v[68:69] offset:6144
	s_nop 1
	s_waitcnt vmcnt(3)
	v_pk_fma_f32 v[68:69], v[84:85], v[20:21], v[236:237]
	s_nop 0
	v_mul_f32_e32 v75, v69, v69
	v_pk_fma_f32 v[70:71], v[86:87], v[22:23], v[238:239]
	v_fmac_f32_e32 v75, v68, v68
	v_fmac_f32_e32 v75, v70, v70
	global_store_dwordx4 v[98:99], v[68:71], off offset:128
	v_fmac_f32_e32 v75, v71, v71
	v_add_f32_e32 v74, v74, v75
	v_pk_mul_f32 v[70:71], v[152:153], v[70:71]
	v_pk_mul_f32 v[68:69], v[154:155], v[68:69]
	s_nop 0
	v_cvt_pk_bf16_f32 v68, v68, v69
	v_cvt_pk_bf16_f32 v69, v70, v71
	ds_write_b64 v116, v[68:69] offset:6144
	s_nop 1
	s_waitcnt vmcnt(3)
	v_pk_fma_f32 v[68:69], v[80:81], v[4:5], v[240:241]
	s_nop 0
	v_mul_f32_e32 v72, v69, v69
	v_pk_fma_f32 v[70:71], v[82:83], v[6:7], v[242:243]
	v_fmac_f32_e32 v72, v68, v68
	v_fmac_f32_e32 v72, v70, v70
	global_store_dwordx4 v[98:99], v[68:71], off offset:192
	v_fmac_f32_e32 v72, v71, v71
	v_add_f32_e32 v72, v74, v72
	v_pk_mul_f32 v[70:71], v[146:147], v[70:71]
	v_pk_mul_f32 v[68:69], v[148:149], v[68:69]
	s_nop 0
	v_cvt_pk_bf16_f32 v68, v68, v69
	v_cvt_pk_bf16_f32 v69, v70, v71
	ds_write_b64 v117, v[68:69] offset:6144
	ds_bpermute_b32 v68, v170, v72
	s_waitcnt lgkmcnt(0)
	v_add_f32_e32 v80, v72, v68
	ds_bpermute_b32 v81, v171, v80
	s_and_saveexec_b64 s[6:7], vcc
	s_cbranch_execz .LBB0_145
	v_lshlrev_b64 v[68:69], 6, v[96:97]
	s_waitcnt lgkmcnt(0)
	v_add_f32_e32 v70, v80, v81
	v_lshl_add_u64 v[68:69], v[144:145], 0, v[68:69]
	global_store_dword v[68:69], v70, off
.LBB0_145:
	s_or_b64 exec, exec, s[6:7]
	v_lshrrev_b32_e32 v80, 3, v175
	v_xor_b32_e32 v70, v80, v175
	v_ashrrev_i32_e32 v165, 31, v164
	v_lshlrev_b32_e32 v70, 4, v70
	v_lshlrev_b64 v[68:69], 11, v[164:165]
	v_and_b32_e32 v70, 0x70, v70
	v_lshl_add_u64 v[68:69], s[82:83], 0, v[68:69]
	s_ashr_i32 s39, s38, 31
	s_waitcnt lgkmcnt(0)
	v_add_u32_e32 v81, v176, v70
	v_lshlrev_b32_e32 v70, 3, v175
	v_lshl_add_u64 v[68:69], s[38:39], 1, v[68:69]
	v_lshlrev_b32_e32 v88, 1, v172
	v_mov_b32_e32 v89, v193
	v_and_b32_e32 v70, 56, v70
	v_lshl_add_u64 v[68:69], v[68:69], 0, v[88:89]
	v_lshlrev_b32_e32 v96, 1, v70
	v_mov_b32_e32 v97, v193
	v_lshl_add_u64 v[72:73], v[68:69], 0, v[96:97]
	v_lshlrev_b32_e32 v68, 7, v80
	v_add_u32_e32 v111, v81, v68
	ds_read_b128 v[68:71], v111
	v_lshlrev_b32_e32 v192, 11, v80
	v_lshl_add_u64 v[74:75], v[72:73], 0, v[192:193]
	v_mov_b32_e32 v95, v193
	v_mov_b32_e32 v93, v193
	s_waitcnt lgkmcnt(0)
	global_store_dwordx4 v[74:75], v[68:71], off
	v_or_b32_e32 v74, 8, v80
	v_lshlrev_b32_e32 v94, 11, v74
	v_lshlrev_b32_e32 v68, 7, v74
	v_add_u32_e32 v110, v81, v68
	ds_read_b128 v[68:71], v110
	v_lshl_add_u64 v[74:75], v[72:73], 0, v[94:95]
	v_mov_b32_e32 v91, v193
	v_mov_b32_e32 v83, v193
	v_mov_b32_e32 v87, v193
	s_waitcnt lgkmcnt(0)
	global_store_dwordx4 v[74:75], v[68:71], off
	v_or_b32_e32 v74, 16, v80
	v_lshlrev_b32_e32 v92, 11, v74
	v_lshlrev_b32_e32 v68, 7, v74
	v_add_u32_e32 v109, v81, v68
	ds_read_b128 v[68:71], v109
	v_lshl_add_u64 v[74:75], v[72:73], 0, v[92:93]
	v_mov_b32_e32 v85, v193
	s_waitcnt lgkmcnt(0)
; #define LDSP __attribute__((address_space(3)))
; DI unsigned pk2(float a, float b) { f32x2 v = {a, b}; bf2_t r = __builtin_convertvector(v, bf2_t); return __builtin_bit_cast(unsigned, r); }
; DI void wave_rows_store(ldsp_t wb, int lane, bf16_t* dst0, size_t ld) {
; #pragma unroll
;     for (int i = 0; i < 8; ++i) {
;         const int row = i * 8 + (lane >> 3), ch = lane & 7;
;         const u32x4 v = *(const LDSP u32x4*)(wb + row * 128 + ((ch ^ (row & 7)) << 4));
;         *(u32x4*)(dst0 + (size_t)row * ld + ch * 8) = v;
;     }
;     static DI void run(const f32x4 (&acc)[8][4], const TileCtx& tc, const Params& p, ldsp_t wb) {
;     ...
;                 const int row = tc.brow + tc.wr * 128 + m * 16 + tc.fr;
;                 float* xr = xrow_ptr(p, row) + col0;
;                 const float* xs = (EK == 1 && tc.l == 0) ? p.x + (size_t)row * DM + col0 : xr;
;                 float part = 0.f;
; #pragma unroll
;                 for (int n = 0; n < 4; ++n) {
;                     f32x4 xv = *(const f32x4*)(xs + n * 16);
;                     xv += gv[n] * acc[m][n];
;                     *(f32x4*)(xr + n * 16) = xv;
;                     if (has_next) {
;                         part += xv[0] * xv[0] + xv[1] * xv[1] + xv[2] * xv[2] + xv[3] * xv[3];
;                         const f32x4 hv = xv * av[n];
;                         u32x2 w; w[0] = pk2(hv[0], hv[1]); w[1] = pk2(hv[2], hv[3]);
;                         wave_put(wb, mm * 16 + tc.fr, n, tc.fq, w);
;                     }
;                 }
;                 if (has_next) {
;                     part += __shfl_xor(part, 16);
;                     part += __shfl_xor(part, 32);
;                     if (tc.fq == 0) ssp[(size_t)row * 16] = part;
	global_store_dwordx4 v[74:75], v[68:71], off
	v_or_b32_e32 v74, 24, v80
	s_nop 0
	v_lshlrev_b32_e32 v68, 7, v74
	v_add_u32_e32 v108, v81, v68
	ds_read_b128 v[68:71], v108
	v_lshlrev_b32_e32 v90, 11, v74
	v_lshl_add_u64 v[74:75], v[72:73], 0, v[90:91]
	s_waitcnt lgkmcnt(0)
	global_store_dwordx4 v[74:75], v[68:71], off
	v_or_b32_e32 v74, 32, v80
	s_nop 0
	v_lshlrev_b32_e32 v68, 7, v74
	v_add_u32_e32 v104, v81, v68
	ds_read_b128 v[68:71], v104
	v_lshlrev_b32_e32 v82, 11, v74
	v_lshl_add_u64 v[74:75], v[72:73], 0, v[82:83]
	s_waitcnt lgkmcnt(0)
	global_store_dwordx4 v[74:75], v[68:71], off
	v_or_b32_e32 v74, 40, v80
	s_nop 0
	v_lshlrev_b32_e32 v68, 7, v74
	v_add_u32_e32 v105, v81, v68
	ds_read_b128 v[68:71], v105
	v_lshlrev_b32_e32 v86, 11, v74
	v_lshl_add_u64 v[74:75], v[72:73], 0, v[86:87]
	s_waitcnt lgkmcnt(0)
	global_store_dwordx4 v[74:75], v[68:71], off
	v_or_b32_e32 v74, 48, v80
	s_nop 0
	v_lshlrev_b32_e32 v68, 7, v74
	v_add_u32_e32 v106, v81, v68
	ds_read_b128 v[68:71], v106
	v_lshlrev_b32_e32 v84, 11, v74
	v_lshl_add_u64 v[74:75], v[72:73], 0, v[84:85]
	s_waitcnt lgkmcnt(0)
	global_store_dwordx4 v[74:75], v[68:71], off
	v_or_b32_e32 v74, 56, v80
	s_nop 0
	v_lshlrev_b32_e32 v68, 7, v74
	v_add_u32_e32 v107, v81, v68
	ds_read_b128 v[68:71], v107
	v_lshlrev_b32_e32 v80, 11, v74
	v_mov_b32_e32 v81, v193
	v_lshl_add_u64 v[72:73], v[72:73], 0, v[80:81]
	s_waitcnt lgkmcnt(0)
	global_store_dwordx4 v[72:73], v[68:71], off
	v_add3_u32 v98, v174, s41, 64
	v_or_b32_e32 v100, v98, v173
	v_cmp_gt_i32_e64 s[6:7], s33, v100
	v_add_u32_e32 v68, 0xffffc000, v100
	v_ashrrev_i32_e32 v101, 31, v100
	v_mov_b32_e32 v70, s71
	v_mov_b32_e32 v71, s55
	v_cndmask_b32_e64 v69, 0, v101, s[6:7]
	v_cndmask_b32_e64 v68, v68, v100, s[6:7]
	v_cndmask_b32_e64 v71, v70, v71, s[6:7]
	v_mov_b32_e32 v70, s70
	v_mov_b32_e32 v72, s54
	v_cndmask_b32_e64 v70, v70, v72, s[6:7]
	v_lshlrev_b64 v[68:69], 12, v[68:69]
	v_readlane_b32 s8, v254, 50
	v_lshl_add_u64 v[68:69], v[70:71], 0, v[68:69]
	v_lshlrev_b64 v[70:71], 12, v[100:101]
	v_readlane_b32 s9, v254, 51
	v_lshl_add_u64 v[102:103], v[68:69], 0, v[150:151]
	v_readlane_b32 s10, v254, 52
	v_lshl_add_u64 v[70:71], s[8:9], 0, v[70:71]
	v_cndmask_b32_e64 v69, v69, v71, s[4:5]
	v_cndmask_b32_e64 v68, v68, v70, s[4:5]
	v_lshl_add_u64 v[72:73], v[68:69], 0, v[150:151]
	global_load_dwordx4 v[68:71], v[72:73], off
	global_load_dwordx4 v[232:235], v[72:73], off offset:64
	global_load_dwordx4 v[236:239], v[72:73], off offset:128
	global_load_dwordx4 v[240:243], v[72:73], off offset:192
	v_readlane_b32 s11, v254, 53
	v_readlane_b32 s12, v254, 54
	v_readlane_b32 s13, v254, 55
	v_readlane_b32 s14, v254, 56
	v_readlane_b32 s15, v254, 57
	v_readlane_b32 s16, v254, 58
	v_readlane_b32 s17, v254, 59
	v_readlane_b32 s18, v254, 60
	v_readlane_b32 s19, v254, 61
	v_readlane_b32 s20, v254, 62
	v_readlane_b32 s21, v254, 63
	v_readlane_b32 s22, v255, 0
	v_readlane_b32 s23, v255, 1
	s_waitcnt vmcnt(3)
	v_pk_fma_f32 v[68:69], v[76:77], v[28:29], v[68:69]
	s_nop 0
	v_mul_f32_e32 v74, v69, v69
	v_pk_fma_f32 v[70:71], v[78:79], v[30:31], v[70:71]
	v_fmac_f32_e32 v74, v68, v68
	v_fmac_f32_e32 v74, v70, v70
	global_store_dwordx4 v[102:103], v[68:71], off
	v_fmac_f32_e32 v74, v71, v71
	s_nop 0
	v_pk_mul_f32 v[70:71], v[160:161], v[70:71]
	v_pk_mul_f32 v[68:69], v[162:163], v[68:69]
	s_nop 0
	v_cvt_pk_bf16_f32 v68, v68, v69
	v_cvt_pk_bf16_f32 v69, v70, v71
	ds_write_b64 v124, v[68:69]
	s_nop 1
	s_waitcnt vmcnt(3)
	v_pk_fma_f32 v[68:69], v[198:199], v[24:25], v[232:233]
	s_nop 0
	v_mul_f32_e32 v75, v69, v69
	v_pk_fma_f32 v[70:71], v[200:201], v[26:27], v[234:235]
	v_fmac_f32_e32 v75, v68, v68
	v_fmac_f32_e32 v75, v70, v70
	global_store_dwordx4 v[102:103], v[68:71], off offset:64
	v_fmac_f32_e32 v75, v71, v71
	v_add_f32_e32 v74, v74, v75
	v_pk_mul_f32 v[70:71], v[156:157], v[70:71]
	v_pk_mul_f32 v[68:69], v[158:159], v[68:69]
	s_nop 0
	v_cvt_pk_bf16_f32 v68, v68, v69
	v_cvt_pk_bf16_f32 v69, v70, v71
	ds_write_b64 v120, v[68:69]
	s_nop 1
	s_waitcnt vmcnt(3)
	v_pk_fma_f32 v[68:69], v[194:195], v[20:21], v[236:237]
	s_nop 0
	v_mul_f32_e32 v75, v69, v69
	v_pk_fma_f32 v[70:71], v[196:197], v[22:23], v[238:239]
	v_fmac_f32_e32 v75, v68, v68
	v_fmac_f32_e32 v75, v70, v70
	global_store_dwordx4 v[102:103], v[68:71], off offset:128
	v_fmac_f32_e32 v75, v71, v71
	v_add_f32_e32 v74, v74, v75
	v_pk_mul_f32 v[70:71], v[152:153], v[70:71]
	v_pk_mul_f32 v[68:69], v[154:155], v[68:69]
	s_nop 0
	v_cvt_pk_bf16_f32 v68, v68, v69
	v_cvt_pk_bf16_f32 v69, v70, v71
	ds_write_b64 v116, v[68:69]
	s_nop 1
	s_waitcnt vmcnt(3)
	v_pk_fma_f32 v[64:65], v[64:65], v[4:5], v[240:241]
	s_nop 0
	v_mul_f32_e32 v68, v65, v65
	v_pk_fma_f32 v[66:67], v[66:67], v[6:7], v[242:243]
	v_fmac_f32_e32 v68, v64, v64
	v_fmac_f32_e32 v68, v66, v66
	global_store_dwordx4 v[102:103], v[64:67], off offset:192
	v_fmac_f32_e32 v68, v67, v67
	v_add_f32_e32 v68, v74, v68
	v_pk_mul_f32 v[66:67], v[146:147], v[66:67]
	v_pk_mul_f32 v[64:65], v[148:149], v[64:65]
	s_nop 0
	v_cvt_pk_bf16_f32 v64, v64, v65
	v_cvt_pk_bf16_f32 v65, v66, v67
	ds_write_b64 v117, v[64:65]
	ds_bpermute_b32 v64, v170, v68
	s_waitcnt lgkmcnt(0)
	v_add_f32_e32 v64, v68, v64
	ds_bpermute_b32 v65, v171, v64
	s_and_saveexec_b64 s[6:7], vcc
	s_cbranch_execz .LBB0_147
	s_waitcnt lgkmcnt(0)
	v_add_f32_e32 v66, v64, v65
	v_lshlrev_b64 v[64:65], 6, v[100:101]
	v_lshl_add_u64 v[64:65], v[144:145], 0, v[64:65]
	global_store_dword v[64:65], v66, off
; DI unsigned pk2(float a, float b) { f32x2 v = {a, b}; bf2_t r = __builtin_convertvector(v, bf2_t); return __builtin_bit_cast(unsigned, r); }
;     static DI void run(const f32x4 (&acc)[8][4], const TileCtx& tc, const Params& p, ldsp_t wb) {
;     ...
;                 const int row = tc.brow + tc.wr * 128 + m * 16 + tc.fr;
;                 float* xr = xrow_ptr(p, row) + col0;
;                 const float* xs = (EK == 1 && tc.l == 0) ? p.x + (size_t)row * DM + col0 : xr;
;                 float part = 0.f;
; #pragma unroll
;                 for (int n = 0; n < 4; ++n) {
;                     f32x4 xv = *(const f32x4*)(xs + n * 16);
;                     xv += gv[n] * acc[m][n];
;                     *(f32x4*)(xr + n * 16) = xv;
;                     if (has_next) {
;                         part += xv[0] * xv[0] + xv[1] * xv[1] + xv[2] * xv[2] + xv[3] * xv[3];
;                         const f32x4 hv = xv * av[n];
;                         u32x2 w; w[0] = pk2(hv[0], hv[1]); w[1] = pk2(hv[2], hv[3]);
;                         wave_put(wb, mm * 16 + tc.fr, n, tc.fq, w);
;                     }
;                 }
;                 if (has_next) {
;                     part += __shfl_xor(part, 16);
;                     part += __shfl_xor(part, 32);
;                     if (tc.fq == 0) ssp[(size_t)row * 16] = part;
.LBB0_147:
	s_or_b64 exec, exec, s[6:7]
	v_add_u32_e32 v64, 0x50, v132
	v_cmp_gt_i32_e64 s[6:7], s33, v64
	v_add_u32_e32 v66, 0xffffc050, v132
	s_waitcnt lgkmcnt(0)
	v_ashrrev_i32_e32 v65, 31, v64
	v_mov_b32_e32 v68, s71
	v_mov_b32_e32 v69, s55
	v_cndmask_b32_e64 v67, 0, v65, s[6:7]
	v_cndmask_b32_e64 v66, v66, v64, s[6:7]
	v_cndmask_b32_e64 v69, v68, v69, s[6:7]
	v_mov_b32_e32 v68, s70
	v_mov_b32_e32 v70, s54
	v_readlane_b32 s8, v254, 50
	v_cndmask_b32_e64 v68, v68, v70, s[6:7]
	v_lshlrev_b64 v[66:67], 12, v[66:67]
	v_lshlrev_b64 v[70:71], 12, v[64:65]
	v_readlane_b32 s9, v254, 51
	v_lshl_add_u64 v[68:69], v[68:69], 0, v[66:67]
	v_lshl_add_u64 v[66:67], v[68:69], 0, v[150:151]
	v_lshl_add_u64 v[70:71], s[8:9], 0, v[70:71]
	v_cndmask_b32_e64 v69, v69, v71, s[4:5]
	v_cndmask_b32_e64 v68, v68, v70, s[4:5]
	v_lshl_add_u64 v[72:73], v[68:69], 0, v[150:151]
	global_load_dwordx4 v[68:71], v[72:73], off
	global_load_dwordx4 v[232:235], v[72:73], off offset:64
	global_load_dwordx4 v[236:239], v[72:73], off offset:128
	global_load_dwordx4 v[240:243], v[72:73], off offset:192
	v_readlane_b32 s10, v254, 52
	v_readlane_b32 s11, v254, 53
	v_readlane_b32 s12, v254, 54
	v_readlane_b32 s13, v254, 55
	v_readlane_b32 s14, v254, 56
	v_readlane_b32 s15, v254, 57
	v_readlane_b32 s16, v254, 58
	v_readlane_b32 s17, v254, 59
	v_readlane_b32 s18, v254, 60
	v_readlane_b32 s19, v254, 61
	v_readlane_b32 s20, v254, 62
	v_readlane_b32 s21, v254, 63
	v_readlane_b32 s22, v255, 0
	v_readlane_b32 s23, v255, 1
	s_waitcnt vmcnt(3)
	v_pk_fma_f32 v[60:61], v[60:61], v[28:29], v[68:69]
	s_nop 0
	v_mul_f32_e32 v68, v61, v61
	v_pk_fma_f32 v[62:63], v[62:63], v[30:31], v[70:71]
	v_fmac_f32_e32 v68, v60, v60
	v_fmac_f32_e32 v68, v62, v62
	global_store_dwordx4 v[66:67], v[60:63], off
	v_fmac_f32_e32 v68, v63, v63
	s_nop 0
	v_pk_mul_f32 v[62:63], v[160:161], v[62:63]
	v_pk_mul_f32 v[60:61], v[162:163], v[60:61]
	s_nop 0
	v_cvt_pk_bf16_f32 v60, v60, v61
	v_cvt_pk_bf16_f32 v61, v62, v63
	ds_write_b64 v124, v[60:61] offset:2048
	s_nop 1
	s_waitcnt vmcnt(3)
	v_pk_fma_f32 v[56:57], v[56:57], v[24:25], v[232:233]
	s_nop 0
	v_mul_f32_e32 v60, v57, v57
	v_pk_fma_f32 v[58:59], v[58:59], v[26:27], v[234:235]
	v_fmac_f32_e32 v60, v56, v56
	v_fmac_f32_e32 v60, v58, v58
	global_store_dwordx4 v[66:67], v[56:59], off offset:64
	v_fmac_f32_e32 v60, v59, v59
	v_add_f32_e32 v60, v68, v60
	v_pk_mul_f32 v[58:59], v[156:157], v[58:59]
	v_pk_mul_f32 v[56:57], v[158:159], v[56:57]
	s_nop 0
	v_cvt_pk_bf16_f32 v56, v56, v57
	v_cvt_pk_bf16_f32 v57, v58, v59
	ds_write_b64 v120, v[56:57] offset:2048
	s_nop 1
	s_waitcnt vmcnt(3)
	v_pk_fma_f32 v[52:53], v[52:53], v[20:21], v[236:237]
	s_nop 0
	v_mul_f32_e32 v56, v53, v53
	v_pk_fma_f32 v[54:55], v[54:55], v[22:23], v[238:239]
	v_fmac_f32_e32 v56, v52, v52
	v_fmac_f32_e32 v56, v54, v54
	global_store_dwordx4 v[66:67], v[52:55], off offset:128
	v_fmac_f32_e32 v56, v55, v55
	v_add_f32_e32 v56, v60, v56
	v_pk_mul_f32 v[54:55], v[152:153], v[54:55]
	v_pk_mul_f32 v[52:53], v[154:155], v[52:53]
	s_nop 0
	v_cvt_pk_bf16_f32 v52, v52, v53
	v_cvt_pk_bf16_f32 v53, v54, v55
	ds_write_b64 v116, v[52:53] offset:2048
	s_nop 1
	s_waitcnt vmcnt(3)
	v_pk_fma_f32 v[48:49], v[48:49], v[4:5], v[240:241]
	s_nop 0
	v_mul_f32_e32 v52, v49, v49
	v_pk_fma_f32 v[50:51], v[50:51], v[6:7], v[242:243]
	v_fmac_f32_e32 v52, v48, v48
	v_fmac_f32_e32 v52, v50, v50
	global_store_dwordx4 v[66:67], v[48:51], off offset:192
	v_fmac_f32_e32 v52, v51, v51
	v_add_f32_e32 v52, v56, v52
	v_pk_mul_f32 v[50:51], v[146:147], v[50:51]
	v_pk_mul_f32 v[48:49], v[148:149], v[48:49]
	s_nop 0
	v_cvt_pk_bf16_f32 v48, v48, v49
	v_cvt_pk_bf16_f32 v49, v50, v51
	ds_write_b64 v117, v[48:49] offset:2048
	ds_bpermute_b32 v48, v170, v52
	s_waitcnt lgkmcnt(0)
	v_add_f32_e32 v48, v52, v48
	ds_bpermute_b32 v49, v171, v48
	s_and_saveexec_b64 s[6:7], vcc
	s_cbranch_execz .LBB0_149
	s_waitcnt lgkmcnt(0)
	v_add_f32_e32 v50, v48, v49
	v_lshlrev_b64 v[48:49], 6, v[64:65]
	v_lshl_add_u64 v[48:49], v[144:145], 0, v[48:49]
	global_store_dword v[48:49], v50, off
.LBB0_149:
	s_or_b64 exec, exec, s[6:7]
	v_add_u32_e32 v48, 0x60, v132
	v_cmp_gt_i32_e64 s[6:7], s33, v48
	v_add_u32_e32 v50, 0xffffc060, v132
	s_waitcnt lgkmcnt(0)
	v_ashrrev_i32_e32 v49, 31, v48
	v_mov_b32_e32 v52, s71
	v_mov_b32_e32 v53, s55
	v_cndmask_b32_e64 v51, 0, v49, s[6:7]
	v_cndmask_b32_e64 v50, v50, v48, s[6:7]
	v_cndmask_b32_e64 v53, v52, v53, s[6:7]
	v_mov_b32_e32 v52, s70
	v_mov_b32_e32 v54, s54
	v_readlane_b32 s8, v254, 50
	v_cndmask_b32_e64 v52, v52, v54, s[6:7]
	v_lshlrev_b64 v[50:51], 12, v[50:51]
	v_lshlrev_b64 v[54:55], 12, v[48:49]
	v_readlane_b32 s9, v254, 51
	v_lshl_add_u64 v[52:53], v[52:53], 0, v[50:51]
	v_lshl_add_u64 v[50:51], v[52:53], 0, v[150:151]
	v_lshl_add_u64 v[54:55], s[8:9], 0, v[54:55]
	v_cndmask_b32_e64 v53, v53, v55, s[4:5]
	v_cndmask_b32_e64 v52, v52, v54, s[4:5]
	v_lshl_add_u64 v[56:57], v[52:53], 0, v[150:151]
	global_load_dwordx4 v[52:55], v[56:57], off
	global_load_dwordx4 v[232:235], v[56:57], off offset:64
	global_load_dwordx4 v[236:239], v[56:57], off offset:128
	global_load_dwordx4 v[240:243], v[56:57], off offset:192
	v_readlane_b32 s10, v254, 52
	v_readlane_b32 s11, v254, 53
	v_readlane_b32 s12, v254, 54
	v_readlane_b32 s13, v254, 55
	v_readlane_b32 s14, v254, 56
	v_readlane_b32 s15, v254, 57
	v_readlane_b32 s16, v254, 58
	v_readlane_b32 s17, v254, 59
	v_readlane_b32 s18, v254, 60
	v_readlane_b32 s19, v254, 61
	v_readlane_b32 s20, v254, 62
	v_readlane_b32 s21, v254, 63
	v_readlane_b32 s22, v255, 0
	v_readlane_b32 s23, v255, 1
	s_waitcnt vmcnt(3)
; DI unsigned pk2(float a, float b) { f32x2 v = {a, b}; bf2_t r = __builtin_convertvector(v, bf2_t); return __builtin_bit_cast(unsigned, r); }
;     static DI void run(const f32x4 (&acc)[8][4], const TileCtx& tc, const Params& p, ldsp_t wb) {
;     ...
;                 const int row = tc.brow + tc.wr * 128 + m * 16 + tc.fr;
;                 float* xr = xrow_ptr(p, row) + col0;
;                 const float* xs = (EK == 1 && tc.l == 0) ? p.x + (size_t)row * DM + col0 : xr;
;                 float part = 0.f;
; #pragma unroll
;                 for (int n = 0; n < 4; ++n) {
;                     f32x4 xv = *(const f32x4*)(xs + n * 16);
;                     xv += gv[n] * acc[m][n];
;                     *(f32x4*)(xr + n * 16) = xv;
;                     if (has_next) {
;                         part += xv[0] * xv[0] + xv[1] * xv[1] + xv[2] * xv[2] + xv[3] * xv[3];
;                         const f32x4 hv = xv * av[n];
;                         u32x2 w; w[0] = pk2(hv[0], hv[1]); w[1] = pk2(hv[2], hv[3]);
;                         wave_put(wb, mm * 16 + tc.fr, n, tc.fq, w);
;                     }
;                 }
;                 if (has_next) {
;                     part += __shfl_xor(part, 16);
;                     part += __shfl_xor(part, 32);
;                     if (tc.fq == 0) ssp[(size_t)row * 16] = part;
	v_pk_fma_f32 v[44:45], v[44:45], v[28:29], v[52:53]
	s_nop 0
	v_mul_f32_e32 v52, v45, v45
	v_pk_fma_f32 v[46:47], v[46:47], v[30:31], v[54:55]
	v_fmac_f32_e32 v52, v44, v44
	v_fmac_f32_e32 v52, v46, v46
	global_store_dwordx4 v[50:51], v[44:47], off
	v_fmac_f32_e32 v52, v47, v47
	s_nop 0
	v_pk_mul_f32 v[46:47], v[160:161], v[46:47]
	v_pk_mul_f32 v[44:45], v[162:163], v[44:45]
	s_nop 0
	v_cvt_pk_bf16_f32 v44, v44, v45
	v_cvt_pk_bf16_f32 v45, v46, v47
	ds_write_b64 v124, v[44:45] offset:4096
	s_nop 1
	s_waitcnt vmcnt(3)
	v_pk_fma_f32 v[40:41], v[40:41], v[24:25], v[232:233]
	s_nop 0
	v_mul_f32_e32 v44, v41, v41
	v_pk_fma_f32 v[42:43], v[42:43], v[26:27], v[234:235]
	v_fmac_f32_e32 v44, v40, v40
	v_fmac_f32_e32 v44, v42, v42
	global_store_dwordx4 v[50:51], v[40:43], off offset:64
	v_fmac_f32_e32 v44, v43, v43
	v_add_f32_e32 v44, v52, v44
	v_pk_mul_f32 v[42:43], v[156:157], v[42:43]
	v_pk_mul_f32 v[40:41], v[158:159], v[40:41]
	s_nop 0
	v_cvt_pk_bf16_f32 v40, v40, v41
	v_cvt_pk_bf16_f32 v41, v42, v43
	ds_write_b64 v120, v[40:41] offset:4096
	s_nop 1
	s_waitcnt vmcnt(3)
	v_pk_fma_f32 v[36:37], v[36:37], v[20:21], v[236:237]
	s_nop 0
	v_mul_f32_e32 v40, v37, v37
	v_pk_fma_f32 v[38:39], v[38:39], v[22:23], v[238:239]
	v_fmac_f32_e32 v40, v36, v36
	v_fmac_f32_e32 v40, v38, v38
	global_store_dwordx4 v[50:51], v[36:39], off offset:128
	v_fmac_f32_e32 v40, v39, v39
	v_add_f32_e32 v40, v44, v40
	v_pk_mul_f32 v[38:39], v[152:153], v[38:39]
	v_pk_mul_f32 v[36:37], v[154:155], v[36:37]
	s_nop 0
	v_cvt_pk_bf16_f32 v36, v36, v37
	v_cvt_pk_bf16_f32 v37, v38, v39
	ds_write_b64 v116, v[36:37] offset:4096
	s_nop 1
	s_waitcnt vmcnt(3)
	v_pk_fma_f32 v[32:33], v[32:33], v[4:5], v[240:241]
	s_nop 0
	v_mul_f32_e32 v36, v33, v33
	v_pk_fma_f32 v[34:35], v[34:35], v[6:7], v[242:243]
	v_fmac_f32_e32 v36, v32, v32
	v_fmac_f32_e32 v36, v34, v34
	global_store_dwordx4 v[50:51], v[32:35], off offset:192
	v_fmac_f32_e32 v36, v35, v35
	v_add_f32_e32 v36, v40, v36
	v_pk_mul_f32 v[34:35], v[146:147], v[34:35]
	v_pk_mul_f32 v[32:33], v[148:149], v[32:33]
	s_nop 0
	v_cvt_pk_bf16_f32 v32, v32, v33
	v_cvt_pk_bf16_f32 v33, v34, v35
	ds_write_b64 v117, v[32:33] offset:4096
	ds_bpermute_b32 v32, v170, v36
	s_waitcnt lgkmcnt(0)
	v_add_f32_e32 v32, v36, v32
	ds_bpermute_b32 v33, v171, v32
	s_and_saveexec_b64 s[6:7], vcc
	s_cbranch_execz .LBB0_151
	s_waitcnt lgkmcnt(0)
	v_add_f32_e32 v34, v32, v33
	v_lshlrev_b64 v[32:33], 6, v[48:49]
	v_lshl_add_u64 v[32:33], v[144:145], 0, v[32:33]
	global_store_dword v[32:33], v34, off
.LBB0_151:
	s_or_b64 exec, exec, s[6:7]
	v_add_u32_e32 v32, 0x70, v132
	v_cmp_gt_i32_e64 s[6:7], s33, v32
	v_add_u32_e32 v34, 0xffffc070, v132
	s_waitcnt lgkmcnt(0)
	v_ashrrev_i32_e32 v33, 31, v32
	v_mov_b32_e32 v36, s71
	v_mov_b32_e32 v37, s55
	v_cndmask_b32_e64 v35, 0, v33, s[6:7]
	v_cndmask_b32_e64 v34, v34, v32, s[6:7]
	v_cndmask_b32_e64 v37, v36, v37, s[6:7]
	v_mov_b32_e32 v36, s70
	v_mov_b32_e32 v38, s54
	v_readlane_b32 s8, v254, 50
	v_cndmask_b32_e64 v36, v36, v38, s[6:7]
	v_lshlrev_b64 v[34:35], 12, v[34:35]
	v_lshlrev_b64 v[38:39], 12, v[32:33]
	v_readlane_b32 s9, v254, 51
	v_lshl_add_u64 v[36:37], v[36:37], 0, v[34:35]
	v_lshl_add_u64 v[34:35], v[36:37], 0, v[150:151]
	v_lshl_add_u64 v[38:39], s[8:9], 0, v[38:39]
	v_cndmask_b32_e64 v37, v37, v39, s[4:5]
	v_cndmask_b32_e64 v36, v36, v38, s[4:5]
	v_lshl_add_u64 v[40:41], v[36:37], 0, v[150:151]
	global_load_dwordx4 v[36:39], v[40:41], off
	global_load_dwordx4 v[232:235], v[40:41], off offset:64
	global_load_dwordx4 v[236:239], v[40:41], off offset:128
	global_load_dwordx4 v[240:243], v[40:41], off offset:192
	v_readlane_b32 s10, v254, 52
	v_readlane_b32 s11, v254, 53
	v_readlane_b32 s12, v254, 54
	v_readlane_b32 s13, v254, 55
	v_readlane_b32 s14, v254, 56
	v_readlane_b32 s15, v254, 57
	v_readlane_b32 s16, v254, 58
	v_readlane_b32 s17, v254, 59
	v_readlane_b32 s18, v254, 60
	v_readlane_b32 s19, v254, 61
	v_readlane_b32 s20, v254, 62
	v_readlane_b32 s21, v254, 63
	v_readlane_b32 s22, v255, 0
	v_readlane_b32 s23, v255, 1
	s_waitcnt vmcnt(3)
	v_pk_fma_f32 v[16:17], v[16:17], v[28:29], v[36:37]
	s_nop 0
	v_mul_f32_e32 v28, v17, v17
	v_pk_fma_f32 v[18:19], v[18:19], v[30:31], v[38:39]
	v_fmac_f32_e32 v28, v16, v16
	v_fmac_f32_e32 v28, v18, v18
	global_store_dwordx4 v[34:35], v[16:19], off
	v_fmac_f32_e32 v28, v19, v19
	s_nop 0
	v_pk_mul_f32 v[18:19], v[160:161], v[18:19]
	v_pk_mul_f32 v[16:17], v[162:163], v[16:17]
	s_nop 0
	v_cvt_pk_bf16_f32 v16, v16, v17
	v_cvt_pk_bf16_f32 v17, v18, v19
	ds_write_b64 v124, v[16:17] offset:6144
	s_nop 1
	s_waitcnt vmcnt(3)
	v_pk_fma_f32 v[12:13], v[12:13], v[24:25], v[232:233]
	s_nop 0
	v_mul_f32_e32 v16, v13, v13
	v_pk_fma_f32 v[14:15], v[14:15], v[26:27], v[234:235]
	v_fmac_f32_e32 v16, v12, v12
	v_fmac_f32_e32 v16, v14, v14
	global_store_dwordx4 v[34:35], v[12:15], off offset:64
	v_fmac_f32_e32 v16, v15, v15
	v_add_f32_e32 v16, v28, v16
	v_pk_mul_f32 v[14:15], v[156:157], v[14:15]
	v_pk_mul_f32 v[12:13], v[158:159], v[12:13]
	s_nop 0
	v_cvt_pk_bf16_f32 v12, v12, v13
	v_cvt_pk_bf16_f32 v13, v14, v15
	ds_write_b64 v120, v[12:13] offset:6144
	s_nop 1
	s_waitcnt vmcnt(3)
	v_pk_fma_f32 v[8:9], v[8:9], v[20:21], v[236:237]
	s_nop 0
	v_mul_f32_e32 v12, v9, v9
	v_pk_fma_f32 v[10:11], v[10:11], v[22:23], v[238:239]
	v_fmac_f32_e32 v12, v8, v8
	v_fmac_f32_e32 v12, v10, v10
	global_store_dwordx4 v[34:35], v[8:11], off offset:128
	v_fmac_f32_e32 v12, v11, v11
	v_add_f32_e32 v12, v16, v12
	v_pk_mul_f32 v[10:11], v[152:153], v[10:11]
	v_pk_mul_f32 v[8:9], v[154:155], v[8:9]
	s_nop 0
	v_cvt_pk_bf16_f32 v8, v8, v9
	v_cvt_pk_bf16_f32 v9, v10, v11
	ds_write_b64 v116, v[8:9] offset:6144
	s_nop 1
	s_waitcnt vmcnt(3)
	v_pk_fma_f32 v[0:1], v[0:1], v[4:5], v[240:241]
	s_nop 0
	v_mul_f32_e32 v4, v1, v1
	v_pk_fma_f32 v[2:3], v[2:3], v[6:7], v[242:243]
	v_fmac_f32_e32 v4, v0, v0
	v_fmac_f32_e32 v4, v2, v2
	global_store_dwordx4 v[34:35], v[0:3], off offset:192
	v_fmac_f32_e32 v4, v3, v3
	v_add_f32_e32 v4, v12, v4
	v_pk_mul_f32 v[2:3], v[146:147], v[2:3]
	v_pk_mul_f32 v[0:1], v[148:149], v[0:1]
	s_nop 0
	v_cvt_pk_bf16_f32 v0, v0, v1
	v_cvt_pk_bf16_f32 v1, v2, v3
	ds_write_b64 v117, v[0:1] offset:6144
	ds_bpermute_b32 v0, v170, v4
	s_waitcnt lgkmcnt(0)
	v_add_f32_e32 v0, v4, v0
	ds_bpermute_b32 v1, v171, v0
	s_and_saveexec_b64 s[6:7], vcc
	s_cbranch_execz .LBB0_124
	s_waitcnt lgkmcnt(0)
	v_add_f32_e32 v2, v0, v1
	v_lshlrev_b64 v[0:1], 6, v[32:33]
	v_lshl_add_u64 v[0:1], v[144:145], 0, v[0:1]
	global_store_dword v[0:1], v2, off
	s_branch .LBB0_124

; DI void gmlp_unit(const Params& p, int l, int T, int g, ldsp_t smem) {
;     ...
;     {
;         const int q = tid >> 2, part = tid & 3;
;         const bf16_t* src = p.U + (size_t)(T * 128 + q) * 1024 + 512 + g * 128 + part * 32;
;         u32x4 raw[4];
; #pragma unroll
;         for (int i = 0; i < 4; ++i) raw[i] = *(const u32x4*)(src + i * 8);
;         float a = 0.f, b = 0.f;
; #pragma unroll
;         for (int i = 0; i < 4; ++i)
; #pragma unroll
;             for (int j = 0; j < 4; ++j) {
;                 const float lo = __uint_as_float(raw[i][j] << 16), hi = __uint_as_float(raw[i][j] & 0xffff0000u);
;                 a += lo + hi; b += lo * lo + hi * hi;
;             }
;         a += __shfl_xor(a, 1); a += __shfl_xor(a, 2);
;         b += __shfl_xor(b, 1); b += __shfl_xor(b, 2);
;         const float mean = a * (1.f / 128.f);
;         const float rstd = rsqrtf(fmaxf(b * (1.f / 128.f) - mean * mean, 0.f) + EPS);
;         const float* gn = p.gmlp_norm_g + l * 512 + g * 128 + part * 32;
; #pragma unroll
;         for (int i = 0; i < 4; ++i)
; #pragma unroll
;             for (int j = 0; j < 4; ++j) {
;                 const int c0 = part * 32 + i * 8 + j * 2;
;                 const float lo = __uint_as_float(raw[i][j] << 16), hi = __uint_as_float(raw[i][j] & 0xffff0000u);
;                 const unsigned w = pk2((lo - mean) * rstd * gn[i * 8 + j * 2], (hi - mean) * rstd * gn[i * 8 + j * 2 + 1]);
;                 *(LDSP bf16_t*)(smem + c0 * 256 + (((q >> 3) ^ (c0 & 15)) << 4) + (q & 7) * 2) = (bf16_t)(w & 0xffffu);
;                 *(LDSP bf16_t*)(smem + (c0 + 1) * 256 + (((q >> 3) ^ ((c0 + 1) & 15)) << 4) + (q & 7) * 2) = (bf16_t)(w >> 16);
;             }
;     }
;     __syncthreads();
;     const int prow = wid * 16 + fr;
;     const bf16_t* wsp = p.ws_bf + ((size_t)(l * 4 + g) * 128 + prow) * 128 + fq * 8;
;     bf16x8 a[4];
; #pragma unroll
;     for (int ks = 0; ks < 4; ++ks) a[ks] = *(const bf16x8*)(wsp + ks * 32);
;     f32x4 acc[8];
; #pragma unroll
;     for (int n = 0; n < 8; ++n) {
;         acc[n] = (f32x4){0.f, 0.f, 0.f, 0.f};
;         const int c = n * 16 + fr;
; #pragma unroll
;         for (int ks = 0; ks < 4; ++ks) {
;             const bf16x8 bq = *(const LDSP bf16x8*)(smem + c * 256 + (((ks * 4 + fq) ^ (c & 15)) << 4));
;             acc[n] = __builtin_amdgcn_mfma_f32_16x16x32_bf16(bq, a[ks], acc[n], 0, 0, 0);
;         }
;     }
.LBB0_174:
	v_mov_b32_e32 v46, v252
	s_lshl_b32 s4, s11, 5
	s_and_b32 s31, s4, 0xffffff80
	v_ashrrev_i32_e32 v47, 2, v46
	v_add_u32_e32 v0, s31, v47
	v_ashrrev_i32_e32 v1, 31, v0
	s_and_b32 s34, s11, 3
	v_lshlrev_b64 v[0:1], 11, v[0:1]
	v_lshlrev_b32_e32 v2, 5, v46
	v_lshl_add_u64 v[0:1], s[16:17], 0, v[0:1]
	s_lshl_b32 s98, s34, 8
	v_and_b32_e32 v36, 0x60, v2
	v_lshl_add_u64 v[0:1], v[0:1], 0, s[98:99]
	v_lshlrev_b32_e32 v192, 1, v36
	s_waitcnt lgkmcnt(0)
	v_lshl_add_u64 v[4:5], v[0:1], 0, v[192:193]
	global_load_dwordx4 v[0:3], v[4:5], off offset:1072
	global_load_dwordx4 v[10:13], v[4:5], off offset:1056
	global_load_dwordx4 v[22:25], v[4:5], off offset:1040
	global_load_dwordx4 v[38:41], v[4:5], off offset:1024
	v_cmp_lt_i32_e32 vcc, v134, v203
	v_lshlrev_b32_e32 v64, 2, v36
	v_lshlrev_b32_e32 v57, 8, v36
	v_ashrrev_i32_e32 v36, 1, v46
	v_and_b32_e32 v58, -16, v36
	v_add_u32_e32 v36, v57, v58
	s_lshl_b32 s4, s34, 9
	s_add_u32 s4, s9, s4
	s_addc_u32 s5, s10, 0
	s_movk_i32 s35, 0x50
	s_brev_b32 s36, 60
	v_lshrrev_b32_e32 v44, 4, v46
	v_and_b32_e32 v45, 15, v46
	s_waitcnt vmcnt(3)
	v_lshlrev_b32_e32 v4, 16, v2
	v_and_b32_e32 v26, 0xffff0000, v2
	v_lshlrev_b32_e32 v5, 16, v3
	v_and_b32_e32 v27, 0xffff0000, v3
	v_mov_b32_e32 v28, v4
	v_mov_b32_e32 v29, v26
	v_mul_f32_e32 v2, v26, v26
	v_pk_fma_f32 v[30:31], v[28:29], v[28:29], v[2:3] op_sel_hi:[1,1,0]
	v_pk_add_f32 v[2:3], v[4:5], v[26:27]
	v_mov_b32_e32 v26, v5
	v_mul_f32_e32 v4, v27, v27
	v_pk_fma_f32 v[32:33], v[26:27], v[26:27], v[4:5] op_sel_hi:[1,1,0]
	v_cndmask_b32_e32 v4, v202, v134, vcc
	v_cmp_lt_i32_e32 vcc, v135, v203
	v_lshlrev_b32_e32 v62, 2, v4
	s_waitcnt vmcnt(0)
	v_and_b32_e32 v5, 0xffff0000, v38
	v_cndmask_b32_e32 v4, v202, v135, vcc
	v_lshlrev_b32_e32 v63, 2, v4
	v_lshlrev_b32_e32 v4, 1, v47
	v_and_b32_e32 v56, 14, v4
	v_or_b32_e32 v65, v36, v56
	v_xad_u32 v36, v58, 16, v57
	v_lshlrev_b32_e32 v34, 16, v38
	v_and_b32_e32 v4, s0, v38
	v_mov_b32_e32 v35, v5
	v_or_b32_e32 v66, v36, v56
	v_lshlrev_b32_e32 v36, 16, v39
	v_and_b32_e32 v37, 0xffff0000, v39
	v_pk_add_f32 v[42:43], v[34:35], v[4:5] op_sel_hi:[0,1]
	v_pk_mul_f32 v[38:39], v[36:37], v[36:37]
	v_pk_mul_f32 v[48:49], v[34:35], v[34:35]
	v_mov_b32_e32 v42, v38
	v_mov_b32_e32 v192, v39
	v_pk_add_f32 v[38:39], v[42:43], v[192:193]
	v_mov_b32_e32 v42, v48
	v_mov_b32_e32 v43, v36
	v_mov_b32_e32 v48, v49
	v_mov_b32_e32 v49, v37
	v_mov_b32_e32 v31, v2
	v_mov_b32_e32 v33, v3
	global_load_dwordx4 v[2:5], v64, s[4:5] offset:48
	global_load_dwordx4 v[6:9], v64, s[4:5] offset:32
	global_load_dwordx4 v[14:17], v64, s[4:5] offset:16
	global_load_dwordx4 v[18:21], v64, s[4:5]
	global_load_dwordx4 v[84:87], v64, s[4:5] offset:112
	global_load_dwordx4 v[88:91], v64, s[4:5] offset:96
	global_load_dwordx4 v[92:95], v64, s[4:5] offset:80
	global_load_dwordx4 v[96:99], v64, s[4:5] offset:64
	s_or_b32 s100, s34, s7
	s_lshl_b32 s100, s100, 7
	v_lshrrev_b32_e32 v116, 2, v252
	v_bfi_b32 v116, -16, v116, v252
	v_add_u32_e32 v117, s100, v116
	v_bfe_u32 v118, v252, 4, 2
	v_lshlrev_b32_e32 v119, 8, v117
	v_lshl_add_u32 v119, v118, 4, v119
	global_load_dwordx4 v[140:143], v119, s[64:65]
	global_load_dwordx4 v[144:147], v119, s[64:65] offset:64
	global_load_dwordx4 v[148:151], v119, s[64:65] offset:128
	global_load_dwordx4 v[152:155], v119, s[64:65] offset:192
	v_add_u32_e32 v120, s31, v116
	v_lshlrev_b32_e32 v120, 11, v120
	v_lshl_add_u32 v120, v118, 3, v120
	v_add_u32_e32 v120, s98, v120
	v_lshlrev_b32_e32 v117, 2, v117
	v_readlane_b32 s100, v253, 11
	v_readlane_b32 s101, v253, 12
	s_nop 4
	global_load_dword v156, v117, s[100:101]
	global_load_dwordx2 v[100:101], v120, s[16:17]
	global_load_dwordx2 v[102:103], v120, s[16:17] offset:32
	global_load_dwordx2 v[104:105], v120, s[16:17] offset:64
	global_load_dwordx2 v[106:107], v120, s[16:17] offset:96
	global_load_dwordx2 v[108:109], v120, s[16:17] offset:128
	global_load_dwordx2 v[110:111], v120, s[16:17] offset:160
	global_load_dwordx2 v[112:113], v120, s[16:17] offset:192
	global_load_dwordx2 v[114:115], v120, s[16:17] offset:224
	v_pk_add_f32 v[42:43], v[42:43], v[48:49]
	s_nop 0
	v_pk_add_f32 v[42:43], v[42:43], v[38:39]
	v_xad_u32 v38, v58, 32, v57
	v_or_b32_e32 v67, v38, v56
	v_xad_u32 v38, v58, 48, v57
	v_or_b32_e32 v68, v38, v56
	v_lshlrev_b32_e32 v38, 16, v40
	v_and_b32_e32 v39, 0xffff0000, v40
	v_pk_mul_f32 v[48:49], v[38:39], v[38:39]
	v_xad_u32 v40, v58, 64, v57
	v_mov_b32_e32 v50, v48
	v_mov_b32_e32 v51, v38
	v_mov_b32_e32 v48, v49
	v_mov_b32_e32 v49, v39
	v_or_b32_e32 v69, v40, v56
	v_xad_u32 v40, v58, s35, v57
	v_pk_add_f32 v[48:49], v[50:51], v[48:49]
	v_or_b32_e32 v70, v40, v56
	v_lshlrev_b32_e32 v40, 16, v41
	v_and_b32_e32 v41, 0xffff0000, v41
	v_pk_add_f32 v[42:43], v[48:49], v[42:43]
	v_pk_mul_f32 v[48:49], v[40:41], v[40:41]
	v_mov_b32_e32 v51, v40
	v_mov_b32_e32 v50, v48
	v_mov_b32_e32 v48, v49
	v_mov_b32_e32 v49, v41
	v_pk_add_f32 v[48:49], v[50:51], v[48:49]
	s_movk_i32 s35, 0x60
	v_pk_add_f32 v[48:49], v[48:49], v[42:43]
	v_xad_u32 v42, v58, s35, v57
	v_or_b32_e32 v71, v42, v56
	v_xad_u32 v42, v58, s14, v57
	v_or_b32_e32 v72, v42, v56
	v_lshlrev_b32_e32 v42, 16, v22
	v_and_b32_e32 v43, 0xffff0000, v22
	v_pk_mul_f32 v[50:51], v[42:43], v[42:43]
	v_xad_u32 v22, v58, s8, v57
	s_movk_i32 s35, 0x90
	v_mov_b32_e32 v52, v50
	v_mov_b32_e32 v53, v42
	v_mov_b32_e32 v50, v51
	v_mov_b32_e32 v51, v43
	v_or_b32_e32 v73, v22, v56
	v_xad_u32 v22, v58, s35, v57
	v_pk_add_f32 v[50:51], v[52:53], v[50:51]
	v_or_b32_e32 v74, v22, v56
	v_lshlrev_b32_e32 v22, 16, v23
	v_and_b32_e32 v23, 0xffff0000, v23
	v_pk_add_f32 v[48:49], v[50:51], v[48:49]
	v_pk_mul_f32 v[50:51], v[22:23], v[22:23]
; #define LDSP __attribute__((address_space(3)))
; DI unsigned pk2(float a, float b) { f32x2 v = {a, b}; bf2_t r = __builtin_convertvector(v, bf2_t); return __builtin_bit_cast(unsigned, r); }
; DI void gmlp_unit(const Params& p, int l, int T, int g, ldsp_t smem) {
;     ...
;         float a = 0.f, b = 0.f;
; #pragma unroll
;         for (int i = 0; i < 4; ++i)
; #pragma unroll
;             for (int j = 0; j < 4; ++j) {
;                 const float lo = __uint_as_float(raw[i][j] << 16), hi = __uint_as_float(raw[i][j] & 0xffff0000u);
;                 a += lo + hi; b += lo * lo + hi * hi;
;             }
;         a += __shfl_xor(a, 1); a += __shfl_xor(a, 2);
;         b += __shfl_xor(b, 1); b += __shfl_xor(b, 2);
;         const float mean = a * (1.f / 128.f);
;         const float rstd = rsqrtf(fmaxf(b * (1.f / 128.f) - mean * mean, 0.f) + EPS);
;         const float* gn = p.gmlp_norm_g + l * 512 + g * 128 + part * 32;
; #pragma unroll
;         for (int i = 0; i < 4; ++i)
; #pragma unroll
;             for (int j = 0; j < 4; ++j) {
;                 const int c0 = part * 32 + i * 8 + j * 2;
;                 const float lo = __uint_as_float(raw[i][j] << 16), hi = __uint_as_float(raw[i][j] & 0xffff0000u);
;                 const unsigned w = pk2((lo - mean) * rstd * gn[i * 8 + j * 2], (hi - mean) * rstd * gn[i * 8 + j * 2 + 1]);
;                 *(LDSP bf16_t*)(smem + c0 * 256 + (((q >> 3) ^ (c0 & 15)) << 4) + (q & 7) * 2) = (bf16_t)(w & 0xffffu);
;                 *(LDSP bf16_t*)(smem + (c0 + 1) * 256 + (((q >> 3) ^ ((c0 + 1) & 15)) << 4) + (q & 7) * 2) = (bf16_t)(w >> 16);
;             }
	v_mov_b32_e32 v53, v22
	v_mov_b32_e32 v52, v50
	v_mov_b32_e32 v50, v51
	v_mov_b32_e32 v51, v23
	v_pk_add_f32 v[50:51], v[52:53], v[50:51]
	s_movk_i32 s35, 0xa0
	v_pk_add_f32 v[48:49], v[50:51], v[48:49]
	v_xad_u32 v50, v58, s35, v57
	s_movk_i32 s35, 0xb0
	v_or_b32_e32 v75, v50, v56
	v_xad_u32 v50, v58, s35, v57
	v_or_b32_e32 v76, v50, v56
	v_lshlrev_b32_e32 v50, 16, v24
	v_and_b32_e32 v51, 0xffff0000, v24
	v_pk_mul_f32 v[52:53], v[50:51], v[50:51]
	v_xad_u32 v24, v58, s15, v57
	s_movk_i32 s35, 0xd0
	v_mov_b32_e32 v54, v52
	v_mov_b32_e32 v55, v50
	v_mov_b32_e32 v52, v53
	v_mov_b32_e32 v53, v51
	v_or_b32_e32 v77, v24, v56
	v_xad_u32 v24, v58, s35, v57
	v_pk_add_f32 v[52:53], v[54:55], v[52:53]
	v_or_b32_e32 v78, v24, v56
	v_lshlrev_b32_e32 v24, 16, v25
	v_and_b32_e32 v25, 0xffff0000, v25
	v_pk_add_f32 v[48:49], v[52:53], v[48:49]
	v_pk_mul_f32 v[52:53], v[24:25], v[24:25]
	v_mov_b32_e32 v55, v24
	v_mov_b32_e32 v54, v52
	v_mov_b32_e32 v52, v53
	v_mov_b32_e32 v53, v25
	v_pk_add_f32 v[52:53], v[54:55], v[52:53]
	s_movk_i32 s35, 0xe0
	v_pk_add_f32 v[48:49], v[52:53], v[48:49]
	v_xad_u32 v52, v58, s35, v57
	s_movk_i32 s35, 0xf0
	v_or_b32_e32 v79, v52, v56
	v_xad_u32 v52, v58, s35, v57
	v_or_b32_e32 v80, v52, v56
	v_lshlrev_b32_e32 v52, 16, v10
	v_and_b32_e32 v53, 0xffff0000, v10
	v_pk_mul_f32 v[54:55], v[52:53], v[52:53]
	v_mov_b32_e32 v57, v52
	v_mov_b32_e32 v56, v54
	v_mov_b32_e32 v54, v55
	v_mov_b32_e32 v55, v53
	v_pk_add_f32 v[54:55], v[56:57], v[54:55]
	s_nop 0
	v_pk_add_f32 v[48:49], v[54:55], v[48:49]
	v_lshlrev_b32_e32 v54, 16, v11
	v_and_b32_e32 v55, 0xffff0000, v11
	v_pk_mul_f32 v[10:11], v[54:55], v[54:55]
	v_mov_b32_e32 v57, v54
	v_mov_b32_e32 v56, v10
	v_mov_b32_e32 v10, v11
	v_mov_b32_e32 v11, v55
	v_pk_add_f32 v[10:11], v[56:57], v[10:11]
	s_nop 0
	v_pk_add_f32 v[10:11], v[10:11], v[48:49]
	v_lshlrev_b32_e32 v48, 16, v12
	v_and_b32_e32 v49, 0xffff0000, v12
	v_pk_mul_f32 v[56:57], v[48:49], v[48:49]
	v_mov_b32_e32 v59, v48
	v_mov_b32_e32 v58, v56
	v_mov_b32_e32 v56, v57
	v_mov_b32_e32 v57, v49
	v_pk_add_f32 v[56:57], v[58:59], v[56:57]
	s_nop 0
	v_pk_add_f32 v[10:11], v[56:57], v[10:11]
	v_lshlrev_b32_e32 v56, 16, v13
	v_and_b32_e32 v57, 0xffff0000, v13
	v_pk_mul_f32 v[12:13], v[56:57], v[56:57]
	v_mov_b32_e32 v59, v56
	v_mov_b32_e32 v58, v12
	v_mov_b32_e32 v12, v13
	v_mov_b32_e32 v13, v57
	v_pk_add_f32 v[12:13], v[58:59], v[12:13]
	v_lshlrev_b32_e32 v58, 16, v0
	v_and_b32_e32 v59, 0xffff0000, v0
	v_pk_add_f32 v[10:11], v[12:13], v[10:11]
	v_pk_mul_f32 v[12:13], v[58:59], v[58:59]
	v_mov_b32_e32 v61, v58
	v_mov_b32_e32 v60, v12
	v_mov_b32_e32 v12, v13
	v_mov_b32_e32 v13, v59
	v_pk_add_f32 v[12:13], v[60:61], v[12:13]
	v_lshlrev_b32_e32 v60, 16, v1
	v_and_b32_e32 v61, 0xffff0000, v1
	v_pk_mul_f32 v[0:1], v[60:61], v[60:61]
	v_pk_add_f32 v[10:11], v[12:13], v[10:11]
	v_mov_b32_e32 v12, v0
	v_mov_b32_e32 v13, v60
	v_mov_b32_e32 v0, v1
	v_mov_b32_e32 v1, v61
	v_pk_add_f32 v[0:1], v[12:13], v[0:1]
	s_nop 0
	v_pk_add_f32 v[0:1], v[0:1], v[10:11]
	s_nop 0
	v_pk_add_f32 v[0:1], v[30:31], v[0:1]
	s_nop 0
	v_pk_add_f32 v[0:1], v[32:33], v[0:1]
	ds_bpermute_b32 v11, v62, v1
	ds_bpermute_b32 v10, v62, v0
	s_waitcnt lgkmcnt(0)
	v_pk_add_f32 v[0:1], v[0:1], v[10:11]
	ds_bpermute_b32 v11, v63, v1
	ds_bpermute_b32 v10, v63, v0
	s_waitcnt lgkmcnt(0)
	v_pk_add_f32 v[0:1], v[0:1], v[10:11]
	s_nop 0
	v_pk_mul_f32 v[30:31], v[0:1], s[36:37] op_sel_hi:[1,0]
	v_readlane_b32 s36, v253, 3
	v_fma_f32 v0, -v31, v31, v30
	v_max_f32_e32 v0, 0, v0
	v_add_f32_e32 v0, 0x358637bd, v0
	v_cmp_gt_f32_e32 vcc, s92, v0
	v_mul_f32_e32 v1, 0x4b800000, v0
	v_readlane_b32 s44, v253, 11
	v_cndmask_b32_e32 v0, v0, v1, vcc
	v_rsq_f32_e32 v0, v0
	v_readlane_b32 s45, v253, 12
	v_readlane_b32 s37, v253, 4
	v_readlane_b32 s38, v253, 5
	v_mul_f32_e32 v1, 0x45800000, v0
	v_cndmask_b32_e32 v32, v0, v1, vcc
	v_pk_add_f32 v[0:1], v[34:35], v[30:31] op_sel:[0,1] neg_lo:[0,1] neg_hi:[0,1]
	v_bfi_b32 v34, -16, v47, v46
	v_pk_mul_f32 v[0:1], v[0:1], v[32:33] op_sel_hi:[1,0]
	v_ashrrev_i32_e32 v35, 31, v34
	s_waitcnt vmcnt(17)
	v_pk_mul_f32 v[0:1], v[18:19], v[0:1]
	v_readlane_b32 s39, v253, 6
	v_cvt_pk_bf16_f32 v0, v0, v1
	ds_write_b16 v65, v0
	ds_write_b16_d16_hi v66, v0 offset:256
	v_pk_add_f32 v[0:1], v[36:37], v[30:31] op_sel:[0,1] neg_lo:[0,1] neg_hi:[0,1]
	v_readlane_b32 s40, v253, 7
	v_pk_mul_f32 v[0:1], v[0:1], v[32:33] op_sel_hi:[1,0]
	v_readlane_b32 s41, v253, 8
	v_pk_mul_f32 v[0:1], v[20:21], v[0:1]
	v_readlane_b32 s42, v253, 9
	v_cvt_pk_bf16_f32 v0, v0, v1
	ds_write_b16 v67, v0 offset:512
	ds_write_b16_d16_hi v68, v0 offset:768
	v_pk_add_f32 v[0:1], v[38:39], v[30:31] op_sel:[0,1] neg_lo:[0,1] neg_hi:[0,1]
	v_readlane_b32 s43, v253, 10
	v_pk_mul_f32 v[0:1], v[0:1], v[32:33] op_sel_hi:[1,0]
	v_readlane_b32 s46, v253, 13
	v_pk_mul_f32 v[0:1], v[14:15], v[0:1]
	v_readlane_b32 s47, v253, 14
	v_cvt_pk_bf16_f32 v0, v0, v1
	ds_write_b16 v69, v0 offset:1024
	ds_write_b16_d16_hi v70, v0 offset:1280
	v_pk_add_f32 v[0:1], v[40:41], v[30:31] op_sel:[0,1] neg_lo:[0,1] neg_hi:[0,1]
	v_readlane_b32 s48, v253, 15
	v_pk_mul_f32 v[0:1], v[0:1], v[32:33] op_sel_hi:[1,0]
	v_readlane_b32 s49, v253, 16
	v_pk_mul_f32 v[0:1], v[16:17], v[0:1]
	v_readlane_b32 s50, v253, 17
	v_cvt_pk_bf16_f32 v0, v0, v1
	ds_write_b16 v71, v0 offset:1536
	ds_write_b16_d16_hi v72, v0 offset:1792
	v_pk_add_f32 v[0:1], v[42:43], v[30:31] op_sel:[0,1] neg_lo:[0,1] neg_hi:[0,1]
	v_readlane_b32 s51, v253, 18
	v_pk_mul_f32 v[0:1], v[0:1], v[32:33] op_sel_hi:[1,0]
	s_nop 0
	v_pk_mul_f32 v[0:1], v[6:7], v[0:1]
	s_nop 0
	v_cvt_pk_bf16_f32 v0, v0, v1
	ds_write_b16 v73, v0 offset:2048
	ds_write_b16_d16_hi v74, v0 offset:2304
	v_pk_add_f32 v[0:1], v[22:23], v[30:31] op_sel:[0,1] neg_lo:[0,1] neg_hi:[0,1]
	s_nop 0
	v_pk_mul_f32 v[0:1], v[0:1], v[32:33] op_sel_hi:[1,0]
	s_nop 0
	v_pk_mul_f32 v[0:1], v[8:9], v[0:1]
	s_nop 0
	v_cvt_pk_bf16_f32 v0, v0, v1
	ds_write_b16 v75, v0 offset:2560
	ds_write_b16_d16_hi v76, v0 offset:2816
	v_pk_add_f32 v[0:1], v[50:51], v[30:31] op_sel:[0,1] neg_lo:[0,1] neg_hi:[0,1]
	s_nop 0
	v_pk_mul_f32 v[0:1], v[0:1], v[32:33] op_sel_hi:[1,0]
	s_nop 0
	v_pk_mul_f32 v[0:1], v[0:1], v[2:3]
	s_nop 0
	v_cvt_pk_bf16_f32 v0, v0, v1
	ds_write_b16 v77, v0 offset:3072
	ds_write_b16_d16_hi v78, v0 offset:3328
	v_pk_add_f32 v[0:1], v[24:25], v[30:31] op_sel:[0,1] neg_lo:[0,1] neg_hi:[0,1]
	s_nop 0
	v_pk_mul_f32 v[0:1], v[0:1], v[32:33] op_sel_hi:[1,0]
	s_nop 0
	v_pk_mul_f32 v[0:1], v[0:1], v[4:5]
	s_nop 0
	v_cvt_pk_bf16_f32 v0, v0, v1
	ds_write_b16 v79, v0 offset:3584
	ds_write_b16_d16_hi v80, v0 offset:3840
	v_pk_add_f32 v[0:1], v[52:53], v[30:31] op_sel:[0,1] neg_lo:[0,1] neg_hi:[0,1]
	s_nop 0
	v_pk_mul_f32 v[16:17], v[0:1], v[32:33] op_sel_hi:[1,0]
	s_nop 0
	s_nop 0
	s_nop 0
	s_nop 0
	s_or_b32 s4, s34, s7
	s_ashr_i32 s5, s4, 31
	s_lshl_b64 s[4:5], s[4:5], 7
	s_waitcnt vmcnt(13)
; #define LDSP __attribute__((address_space(3)))
; DI unsigned pk2(float a, float b) { f32x2 v = {a, b}; bf2_t r = __builtin_convertvector(v, bf2_t); return __builtin_bit_cast(unsigned, r); }
; DI void gmlp_unit(const Params& p, int l, int T, int g, ldsp_t smem) {
;     ...
;         for (int i = 0; i < 4; ++i)
; #pragma unroll
;             for (int j = 0; j < 4; ++j) {
;                 const int c0 = part * 32 + i * 8 + j * 2;
;                 const float lo = __uint_as_float(raw[i][j] << 16), hi = __uint_as_float(raw[i][j] & 0xffff0000u);
;                 const unsigned w = pk2((lo - mean) * rstd * gn[i * 8 + j * 2], (hi - mean) * rstd * gn[i * 8 + j * 2 + 1]);
;                 *(LDSP bf16_t*)(smem + c0 * 256 + (((q >> 3) ^ (c0 & 15)) << 4) + (q & 7) * 2) = (bf16_t)(w & 0xffffu);
;                 *(LDSP bf16_t*)(smem + (c0 + 1) * 256 + (((q >> 3) ^ ((c0 + 1) & 15)) << 4) + (q & 7) * 2) = (bf16_t)(w >> 16);
;             }
;     }
;     __syncthreads();
;     const int prow = wid * 16 + fr;
;     const bf16_t* wsp = p.ws_bf + ((size_t)(l * 4 + g) * 128 + prow) * 128 + fq * 8;
;     bf16x8 a[4];
; #pragma unroll
;     for (int ks = 0; ks < 4; ++ks) a[ks] = *(const bf16x8*)(wsp + ks * 32);
;     f32x4 acc[8];
; #pragma unroll
;     for (int n = 0; n < 8; ++n) {
;         acc[n] = (f32x4){0.f, 0.f, 0.f, 0.f};
;         const int c = n * 16 + fr;
; #pragma unroll
;         for (int ks = 0; ks < 4; ++ks) {
;             const bf16x8 bq = *(const LDSP bf16x8*)(smem + c * 256 + (((ks * 4 + fq) ^ (c & 15)) << 4));
;             acc[n] = __builtin_amdgcn_mfma_f32_16x16x32_bf16(bq, a[ks], acc[n], 0, 0, 0);
;         }
;     }
;     const float bs = p.b_spatial[(size_t)(l * 4 + g) * 128 + prow];
	v_pk_mul_f32 v[12:13], v[16:17], v[96:97]
	s_nop 0
	v_cvt_pk_bf16_f32 v12, v12, v13
	ds_write_b16 v65, v12 offset:4096
	ds_write_b16_d16_hi v66, v12 offset:4352
	v_pk_add_f32 v[12:13], v[54:55], v[30:31] op_sel:[0,1] neg_lo:[0,1] neg_hi:[0,1]
	s_nop 0
	v_pk_mul_f32 v[12:13], v[12:13], v[32:33] op_sel_hi:[1,0]
	s_nop 0
	v_pk_mul_f32 v[12:13], v[12:13], v[98:99]
	s_nop 0
	v_cvt_pk_bf16_f32 v12, v12, v13
	ds_write_b16 v67, v12 offset:4608
	ds_write_b16_d16_hi v68, v12 offset:4864
	v_pk_add_f32 v[12:13], v[48:49], v[30:31] op_sel:[0,1] neg_lo:[0,1] neg_hi:[0,1]
	s_nop 0
	v_pk_mul_f32 v[12:13], v[12:13], v[32:33] op_sel_hi:[1,0]
	s_nop 0
	v_pk_mul_f32 v[8:9], v[12:13], v[92:93]
	s_nop 0
	v_cvt_pk_bf16_f32 v8, v8, v9
	ds_write_b16 v69, v8 offset:5120
	ds_write_b16_d16_hi v70, v8 offset:5376
	v_pk_add_f32 v[8:9], v[56:57], v[30:31] op_sel:[0,1] neg_lo:[0,1] neg_hi:[0,1]
	s_nop 0
	v_pk_mul_f32 v[8:9], v[8:9], v[32:33] op_sel_hi:[1,0]
	s_nop 0
	v_pk_mul_f32 v[8:9], v[8:9], v[94:95]
	s_nop 0
	v_cvt_pk_bf16_f32 v8, v8, v9
	ds_write_b16 v71, v8 offset:5632
	ds_write_b16_d16_hi v72, v8 offset:5888
	v_pk_add_f32 v[8:9], v[58:59], v[30:31] op_sel:[0,1] neg_lo:[0,1] neg_hi:[0,1]
	s_nop 0
	v_pk_mul_f32 v[8:9], v[8:9], v[32:33] op_sel_hi:[1,0]
	s_nop 0
	v_pk_mul_f32 v[4:5], v[8:9], v[88:89]
	s_nop 0
	v_cvt_pk_bf16_f32 v4, v4, v5
	ds_write_b16 v73, v4 offset:6144
	ds_write_b16_d16_hi v74, v4 offset:6400
	v_pk_add_f32 v[4:5], v[60:61], v[30:31] op_sel:[0,1] neg_lo:[0,1] neg_hi:[0,1]
	s_nop 0
	v_pk_mul_f32 v[4:5], v[4:5], v[32:33] op_sel_hi:[1,0]
	s_nop 0
	v_pk_mul_f32 v[4:5], v[4:5], v[90:91]
	s_nop 0
	v_cvt_pk_bf16_f32 v4, v4, v5
	ds_write_b16 v75, v4 offset:6656
	ds_write_b16_d16_hi v76, v4 offset:6912
	v_pk_add_f32 v[4:5], v[28:29], v[30:31] op_sel:[0,1] neg_lo:[0,1] neg_hi:[0,1]
	s_nop 0
	v_pk_mul_f32 v[4:5], v[4:5], v[32:33] op_sel_hi:[1,0]
	s_nop 0
	v_pk_mul_f32 v[0:1], v[4:5], v[84:85]
	v_bfe_u32 v4, v46, 4, 2
	v_cvt_pk_bf16_f32 v0, v0, v1
	ds_write_b16 v77, v0 offset:7168
	ds_write_b16_d16_hi v78, v0 offset:7424
	v_pk_add_f32 v[0:1], v[26:27], v[30:31] op_sel:[0,1] neg_lo:[0,1] neg_hi:[0,1]
	v_lshlrev_b32_e32 v5, 8, v45
	v_pk_mul_f32 v[0:1], v[0:1], v[32:33] op_sel_hi:[1,0]
	v_lshl_add_u64 v[32:33], s[4:5], 0, v[34:35]
	v_pk_mul_f32 v[0:1], v[0:1], v[86:87]
	v_lshlrev_b32_e32 v2, 4, v4
	v_cvt_pk_bf16_f32 v0, v0, v1
	ds_write_b16 v79, v0 offset:7680
	ds_write_b16_d16_hi v80, v0 offset:7936
	v_lshlrev_b64 v[0:1], 8, v[32:33]
	v_lshl_add_u64 v[0:1], s[64:65], 0, v[0:1]
	v_mov_b32_e32 v3, v193
	v_lshl_add_u64 v[6:7], v[0:1], 0, v[2:3]
	s_waitcnt lgkmcnt(0)
	s_barrier
	s_nop 0
	s_nop 0
	s_nop 0
	s_nop 0
	v_bitop3_b32 v6, v44, v45, 3 bitop3:0x6c
	v_lshl_or_b32 v35, v6, 4, v5
	ds_read_b128 v[6:9], v35
	v_bitop3_b32 v10, v4, v45, 4 bitop3:0x36
	v_lshl_or_b32 v44, v10, 4, v5
	ds_read_b128 v[10:13], v44
	s_waitcnt vmcnt(12) lgkmcnt(1)
	v_mfma_f32_16x16x32_bf16 v[6:9], v[6:9], v[140:143], 0
	v_lshlrev_b32_e32 v192, 3, v4
	ds_read_b128 v[50:53], v44 offset:24576
	v_add_u32_e32 v34, s31, v34
	s_waitcnt vmcnt(11) lgkmcnt(1)
	v_mfma_f32_16x16x32_bf16 v[6:9], v[10:13], v[144:147], v[6:9]
	v_bitop3_b32 v10, v4, v45, 8 bitop3:0x36
	v_lshl_or_b32 v54, v10, 4, v5
	ds_read_b128 v[10:13], v54
	v_bitop3_b32 v4, v4, v45, 12 bitop3:0x36
	v_lshl_or_b32 v45, v4, 4, v5
	s_waitcnt vmcnt(9) lgkmcnt(0)
	v_mfma_f32_16x16x32_bf16 v[6:9], v[10:13], v[148:151], v[6:9]
	ds_read_b128 v[10:13], v45
	v_lshl_add_u64 v[32:33], v[32:33], 2, s[44:45]
	s_nop 0
	s_waitcnt vmcnt(9) lgkmcnt(0)
	v_mfma_f32_16x16x32_bf16 v[28:31], v[10:13], v[152:155], v[6:9]
	s_nop 2
	ds_read_b128 v[4:7], v35 offset:4096
	ds_read_b128 v[8:11], v44 offset:4096
	s_waitcnt vmcnt(8)
	v_mov_b32_e32 v32, v156
	s_nop 1
	v_pk_add_f32 v[28:29], v[28:29], v[32:33] op_sel_hi:[1,0]
	s_waitcnt lgkmcnt(1)
	v_mfma_f32_16x16x32_bf16 v[4:7], v[4:7], v[140:143], 0
	v_add_f32_e64 v30, v30, v32
	v_add_f32_e64 v31, v31, v32
	s_waitcnt lgkmcnt(0)
	v_mfma_f32_16x16x32_bf16 v[4:7], v[8:11], v[144:147], v[4:7]
	ds_read_b128 v[8:11], v54 offset:4096
	s_waitcnt lgkmcnt(0)
	v_mfma_f32_16x16x32_bf16 v[4:7], v[8:11], v[148:151], v[4:7]
	ds_read_b128 v[8:11], v45 offset:4096
	s_waitcnt lgkmcnt(0)
	v_mfma_f32_16x16x32_bf16 v[24:27], v[8:11], v[152:155], v[4:7]
	s_nop 4
	ds_read_b128 v[4:7], v35 offset:8192
	ds_read_b128 v[8:11], v44 offset:8192
	s_nop 0
	v_pk_add_f32 v[24:25], v[24:25], v[32:33] op_sel_hi:[1,0]
	s_waitcnt lgkmcnt(1)
	v_mfma_f32_16x16x32_bf16 v[4:7], v[4:7], v[140:143], 0
	v_add_f32_e64 v26, v26, v32
	v_add_f32_e64 v27, v27, v32
	s_waitcnt lgkmcnt(0)
	v_mfma_f32_16x16x32_bf16 v[4:7], v[8:11], v[144:147], v[4:7]
	ds_read_b128 v[8:11], v54 offset:8192
	s_waitcnt lgkmcnt(0)
	v_mfma_f32_16x16x32_bf16 v[4:7], v[8:11], v[148:151], v[4:7]
	ds_read_b128 v[8:11], v45 offset:8192
	s_waitcnt lgkmcnt(0)
	v_mfma_f32_16x16x32_bf16 v[20:23], v[8:11], v[152:155], v[4:7]
	s_nop 4
	ds_read_b128 v[4:7], v35 offset:12288
	ds_read_b128 v[8:11], v44 offset:12288
	s_nop 0
	v_pk_add_f32 v[20:21], v[20:21], v[32:33] op_sel_hi:[1,0]
	s_waitcnt lgkmcnt(1)
	v_mfma_f32_16x16x32_bf16 v[4:7], v[4:7], v[140:143], 0
	v_add_f32_e64 v22, v22, v32
	v_add_f32_e64 v23, v23, v32
	s_waitcnt lgkmcnt(0)
	v_mfma_f32_16x16x32_bf16 v[4:7], v[8:11], v[144:147], v[4:7]
	ds_read_b128 v[8:11], v54 offset:12288
	s_waitcnt lgkmcnt(0)
	v_mfma_f32_16x16x32_bf16 v[4:7], v[8:11], v[148:151], v[4:7]
	ds_read_b128 v[8:11], v45 offset:12288
	s_waitcnt lgkmcnt(0)
	v_mfma_f32_16x16x32_bf16 v[16:19], v[8:11], v[152:155], v[4:7]
	s_nop 4
	ds_read_b128 v[4:7], v35 offset:16384
	ds_read_b128 v[8:11], v44 offset:16384
	s_nop 0
	v_pk_add_f32 v[16:17], v[16:17], v[32:33] op_sel_hi:[1,0]
	s_waitcnt lgkmcnt(1)
; #define LDSP __attribute__((address_space(3)))
; DI unsigned pk2(float a, float b) { f32x2 v = {a, b}; bf2_t r = __builtin_convertvector(v, bf2_t); return __builtin_bit_cast(unsigned, r); }
; DI void gmlp_unit(const Params& p, int l, int T, int g, ldsp_t smem) {
;     ...
;     for (int n = 0; n < 8; ++n) {
;         acc[n] = (f32x4){0.f, 0.f, 0.f, 0.f};
;         const int c = n * 16 + fr;
; #pragma unroll
;         for (int ks = 0; ks < 4; ++ks) {
;             const bf16x8 bq = *(const LDSP bf16x8*)(smem + c * 256 + (((ks * 4 + fq) ^ (c & 15)) << 4));
;             acc[n] = __builtin_amdgcn_mfma_f32_16x16x32_bf16(bq, a[ks], acc[n], 0, 0, 0);
;         }
;     }
;     const float bs = p.b_spatial[(size_t)(l * 4 + g) * 128 + prow];
;     const int row = T * 128 + prow;
;     const bf16_t* up = p.U + (size_t)row * 1024 + g * 128 + fq * 4;
;     bf16_t* mp = p.MIX + (size_t)row * DM + 512 + g * 128 + fq * 4;
; #pragma unroll
;     for (int n = 0; n < 8; ++n) {
;         const u32x2 uu = *(const u32x2*)(up + n * 16);
;         const float u0 = __uint_as_float(uu[0] << 16), u1 = __uint_as_float(uu[0] & 0xffff0000u), u2 = __uint_as_float(uu[1] << 16), u3 = __uint_as_float(uu[1] & 0xffff0000u);
;         u32x2 w; w[0] = pk2((acc[n][0] + bs) * u0, (acc[n][1] + bs) * u1); w[1] = pk2((acc[n][2] + bs) * u2, (acc[n][3] + bs) * u3);
;         *(u32x2*)(mp + n * 16) = w;
;     }
;     __syncthreads();
; }
; DI void mixer_phase(const Params& p, int l, ldsp_t smem) {
;     const bool last = l == DEPTH - 1;
;     for (int u = blockIdx.x; u < 512; u += gridDim.x) attn_unit(p, l, (u & 7) >> 1, u & 1, u >> 3, false, smem);
;     if (!last)
;         for (int u = blockIdx.x; u < 32; u += gridDim.x) attn_unit(p, l, (u & 7) >> 1, u & 1, u >> 3, true, smem);
;     const int nT = last ? 128 : 136;
;     for (int u = blockIdx.x; u < nT * 4; u += gridDim.x) gmlp_unit(p, l, u >> 2, u & 3, smem);
	v_mfma_f32_16x16x32_bf16 v[4:7], v[4:7], v[140:143], 0
	v_add_f32_e64 v18, v18, v32
	v_add_f32_e64 v19, v19, v32
	s_waitcnt lgkmcnt(0)
	v_mfma_f32_16x16x32_bf16 v[4:7], v[8:11], v[144:147], v[4:7]
	ds_read_b128 v[8:11], v54 offset:16384
	s_waitcnt lgkmcnt(0)
	v_mfma_f32_16x16x32_bf16 v[4:7], v[8:11], v[148:151], v[4:7]
	ds_read_b128 v[8:11], v45 offset:16384
	s_waitcnt lgkmcnt(0)
	v_mfma_f32_16x16x32_bf16 v[12:15], v[8:11], v[152:155], v[4:7]
	s_nop 4
	ds_read_b128 v[4:7], v35 offset:20480
	ds_read_b128 v[8:11], v44 offset:20480
	s_nop 0
	v_pk_add_f32 v[12:13], v[12:13], v[32:33] op_sel_hi:[1,0]
	s_waitcnt lgkmcnt(1)
	v_mfma_f32_16x16x32_bf16 v[4:7], v[4:7], v[140:143], 0
	v_add_f32_e64 v14, v14, v32
	v_add_f32_e64 v15, v15, v32
	s_waitcnt lgkmcnt(0)
	v_mfma_f32_16x16x32_bf16 v[4:7], v[8:11], v[144:147], v[4:7]
	ds_read_b128 v[8:11], v54 offset:20480
	s_waitcnt lgkmcnt(0)
	v_mfma_f32_16x16x32_bf16 v[4:7], v[8:11], v[148:151], v[4:7]
	ds_read_b128 v[8:11], v45 offset:20480
	s_waitcnt lgkmcnt(0)
	v_mfma_f32_16x16x32_bf16 v[8:11], v[8:11], v[152:155], v[4:7]
	s_nop 4
	ds_read_b128 v[4:7], v35 offset:24576
	s_nop 1
	v_pk_add_f32 v[8:9], v[8:9], v[32:33] op_sel_hi:[1,0]
	s_waitcnt lgkmcnt(0)
	v_mfma_f32_16x16x32_bf16 v[4:7], v[4:7], v[140:143], 0
	v_add_f32_e64 v10, v10, v32
	v_add_f32_e64 v11, v11, v32
	v_mfma_f32_16x16x32_bf16 v[4:7], v[50:53], v[144:147], v[4:7]
	ds_read_b128 v[50:53], v54 offset:24576
	s_waitcnt lgkmcnt(0)
	v_mfma_f32_16x16x32_bf16 v[4:7], v[50:53], v[148:151], v[4:7]
	ds_read_b128 v[50:53], v45 offset:24576
	s_waitcnt lgkmcnt(0)
	v_mfma_f32_16x16x32_bf16 v[4:7], v[50:53], v[152:155], v[4:7]
	ds_read_b128 v[50:53], v35 offset:28672
	v_ashrrev_i32_e32 v35, 31, v34
	s_nop 5
	v_pk_add_f32 v[4:5], v[4:5], v[32:33] op_sel_hi:[1,0]
	s_waitcnt lgkmcnt(0)
	v_mfma_f32_16x16x32_bf16 v[0:3], v[50:53], v[140:143], 0
	ds_read_b128 v[50:53], v44 offset:28672
	v_pk_add_f32 v[6:7], v[6:7], v[32:33] op_sel_hi:[1,0]
	s_waitcnt lgkmcnt(0)
	v_mfma_f32_16x16x32_bf16 v[0:3], v[50:53], v[144:147], v[0:3]
	ds_read_b128 v[36:39], v54 offset:28672
	s_waitcnt lgkmcnt(0)
	v_mfma_f32_16x16x32_bf16 v[0:3], v[36:39], v[148:151], v[0:3]
	ds_read_b128 v[36:39], v45 offset:28672
	s_waitcnt lgkmcnt(0)
	v_mfma_f32_16x16x32_bf16 v[0:3], v[36:39], v[152:155], v[0:3]
	v_lshlrev_b64 v[36:37], 11, v[34:35]
	v_lshl_add_u64 v[34:35], s[16:17], 0, v[36:37]
	v_lshl_add_u64 v[34:35], v[34:35], 0, s[98:99]
	v_lshl_add_u64 v[34:35], v[34:35], 0, v[192:193]
	s_nop 0
	v_lshl_add_u64 v[36:37], s[18:19], 0, v[36:37]
	v_lshl_add_u64 v[36:37], v[36:37], 0, s[98:99]
	v_lshl_add_u64 v[36:37], v[36:37], 0, v[192:193]
	v_pk_add_f32 v[0:1], v[0:1], v[32:33] op_sel_hi:[1,0]
	v_pk_add_f32 v[2:3], v[2:3], v[32:33] op_sel_hi:[1,0]
	s_waitcnt vmcnt(7)
	v_lshlrev_b32_e32 v40, 16, v100
	v_and_b32_e32 v41, 0xffff0000, v100
	v_lshlrev_b32_e32 v38, 16, v101
	v_and_b32_e32 v39, 0xffff0000, v101
	v_pk_mul_f32 v[28:29], v[28:29], v[40:41]
	v_pk_mul_f32 v[30:31], v[30:31], v[38:39]
	v_cvt_pk_bf16_f32 v28, v28, v29
	v_cvt_pk_bf16_f32 v29, v30, v31
	global_store_dwordx2 v[36:37], v[28:29], off offset:1024
	s_nop 0
	s_waitcnt vmcnt(7)
	v_lshlrev_b32_e32 v30, 16, v102
	v_and_b32_e32 v31, 0xffff0000, v102
	v_lshlrev_b32_e32 v28, 16, v103
	v_and_b32_e32 v29, 0xffff0000, v103
	v_pk_mul_f32 v[24:25], v[24:25], v[30:31]
	v_pk_mul_f32 v[26:27], v[26:27], v[28:29]
	v_cvt_pk_bf16_f32 v24, v24, v25
	v_cvt_pk_bf16_f32 v25, v26, v27
	global_store_dwordx2 v[36:37], v[24:25], off offset:1056
	s_nop 0
	s_waitcnt vmcnt(7)
	v_lshlrev_b32_e32 v26, 16, v104
	v_and_b32_e32 v27, 0xffff0000, v104
	v_lshlrev_b32_e32 v24, 16, v105
	v_and_b32_e32 v25, 0xffff0000, v105
	v_pk_mul_f32 v[20:21], v[20:21], v[26:27]
	v_pk_mul_f32 v[22:23], v[22:23], v[24:25]
	v_cvt_pk_bf16_f32 v20, v20, v21
	v_cvt_pk_bf16_f32 v21, v22, v23
	global_store_dwordx2 v[36:37], v[20:21], off offset:1088
	s_nop 0
	s_waitcnt vmcnt(7)
	v_lshlrev_b32_e32 v22, 16, v106
	v_and_b32_e32 v23, 0xffff0000, v106
	v_lshlrev_b32_e32 v20, 16, v107
	v_and_b32_e32 v21, 0xffff0000, v107
	v_pk_mul_f32 v[16:17], v[16:17], v[22:23]
	v_pk_mul_f32 v[18:19], v[18:19], v[20:21]
	v_cvt_pk_bf16_f32 v16, v16, v17
	v_cvt_pk_bf16_f32 v17, v18, v19
	global_store_dwordx2 v[36:37], v[16:17], off offset:1120
	s_nop 0
	s_waitcnt vmcnt(7)
	v_lshlrev_b32_e32 v18, 16, v108
	v_and_b32_e32 v19, 0xffff0000, v108
	v_lshlrev_b32_e32 v16, 16, v109
	v_and_b32_e32 v17, 0xffff0000, v109
	v_pk_mul_f32 v[12:13], v[12:13], v[18:19]
	v_pk_mul_f32 v[14:15], v[14:15], v[16:17]
	v_cvt_pk_bf16_f32 v12, v12, v13
	v_cvt_pk_bf16_f32 v13, v14, v15
	global_store_dwordx2 v[36:37], v[12:13], off offset:1152
	s_nop 0
	s_waitcnt vmcnt(7)
	v_lshlrev_b32_e32 v14, 16, v110
	v_and_b32_e32 v15, 0xffff0000, v110
	v_lshlrev_b32_e32 v12, 16, v111
	v_and_b32_e32 v13, 0xffff0000, v111
	v_pk_mul_f32 v[8:9], v[8:9], v[14:15]
	v_pk_mul_f32 v[10:11], v[10:11], v[12:13]
	v_cvt_pk_bf16_f32 v8, v8, v9
	v_cvt_pk_bf16_f32 v9, v10, v11
	global_store_dwordx2 v[36:37], v[8:9], off offset:1184
	s_nop 0
	s_waitcnt vmcnt(7)
	v_lshlrev_b32_e32 v10, 16, v112
	v_and_b32_e32 v11, 0xffff0000, v112
	v_lshlrev_b32_e32 v8, 16, v113
	v_and_b32_e32 v9, 0xffff0000, v113
	v_pk_mul_f32 v[4:5], v[4:5], v[10:11]
	v_pk_mul_f32 v[6:7], v[6:7], v[8:9]
	v_cvt_pk_bf16_f32 v4, v4, v5
	v_cvt_pk_bf16_f32 v5, v6, v7
	global_store_dwordx2 v[36:37], v[4:5], off offset:1216
	s_nop 0
	s_waitcnt vmcnt(7)
	v_lshlrev_b32_e32 v6, 16, v114
	v_and_b32_e32 v7, 0xffff0000, v114
	v_lshlrev_b32_e32 v4, 16, v115
	v_and_b32_e32 v5, 0xffff0000, v115
	v_pk_mul_f32 v[0:1], v[0:1], v[6:7]
	v_pk_mul_f32 v[2:3], v[2:3], v[4:5]
	v_cvt_pk_bf16_f32 v0, v0, v1
	v_cvt_pk_bf16_f32 v1, v2, v3
	global_store_dwordx2 v[36:37], v[0:1], off offset:1248
	s_barrier
	s_load_dword s4, s[88:89], 0x0
	s_waitcnt lgkmcnt(0)
	s_add_i32 s11, s4, s11
	s_cmp_ge_i32 s11, s6
	s_cbranch_scc0 .LBB0_174

; #define WAIT_V0() asm volatile("s_waitcnt vmcnt(0)" ::: "memory")
; #define G_STAGE_A(Ap, buf, kt) do { const char* ab_ = (const char*)(Ap) + (size_t)(kt) * 128; \
;       _Pragma("unroll") for (int i = 0; i < 4; ++i) \
;         __builtin_amdgcn_global_load_lds((const unsigned*)(ab_ + soff[i]), (LDSP unsigned*)(G_SA(buf) + wid * 1024 + i * 8192), 16, 0, 0); } while (0)
; #define G_RDA(AF, buf, ks, mh) do { _Pragma("unroll") for (int m = 0; m < 4; ++m) AF[m] = *(const LDSP bf16x8*)(G_SA(buf) + aoff + ((mh) * 4 + m) * 2048 + (ks) * 1024); } while (0)
; #define G_RDB(BF, buf, ks) do { _Pragma("unroll") for (int n = 0; n < 4; ++n) BF[n] = *(const LDSP bf16x8*)(G_SB(buf) + boff + n * 2048 + (ks) * 1024); } while (0)
; #define G_MMA(AF, BF, mh) do { __builtin_amdgcn_s_setprio(1); \
;             _Pragma("unroll") for (int m = 0; m < 4; ++m) _Pragma("unroll") for (int n = 0; n < 4; ++n) \
;                 acc[(mh) * 4 + m][n] = __builtin_amdgcn_mfma_f32_16x16x32_bf16(BF[n], AF[m], acc[(mh) * 4 + m][n], 0, 0, 0); \
;             __builtin_amdgcn_s_setprio(0); } while (0)
; #define G_SB0() __builtin_amdgcn_sched_barrier(0)
; template <int EK>
; DI void gemm_stream(const Params& p, int l, const bf16_t* __restrict__ A, const bf16_t* __restrict__ Bt, int M, int N, int K, ldsp_t shm) {
;     ...
;             if (t > 0) G_MMA(Ab_, Bk1, 1);
;             G_SB0();
;             if (t + 1 < nt) G_STAGE_A(Ab, cur ^ 1, t + 1);
;             else if (has_next) G_STAGE_A(Ab2, cur ^ 1, 0);
;             G_RDA(Ab_, cur, 0, 1);
;             G_MMA(Aa, Bk0, 0); G_SB0();
;             G_RDA(Aa, cur, 1, 0); G_RDB(Bk1, cur, 1);
;             G_MMA(Ab_, Bk0, 1); G_SB0();
;             G_RDA(Ab_, cur, 1, 1);
;             G_MMA(Aa, Bk1, 0); G_SB0();
;             asm volatile("s_waitcnt lgkmcnt(0)" ::: "memory");
;             WAIT_V0(); __syncthreads();
.LBB0_196:
	v_add_u32_e32 v80, 0x12000, v218
	v_add_u32_e32 v84, 0x12800, v218
	v_add_u32_e32 v88, 0x13000, v218
	v_add_u32_e32 v92, 0x13800, v218
	ds_read_b128 v[80:83], v80
	ds_read_b128 v[84:87], v84
	ds_read_b128 v[88:91], v88
	ds_read_b128 v[92:95], v92
	s_setprio 1
	s_waitcnt lgkmcnt(0)
	v_mfma_f32_16x16x32_bf16 v[4:7], v[164:167], v[188:191], v[4:7]
	v_mfma_f32_16x16x32_bf16 v[8:11], v[168:171], v[188:191], v[8:11]
	v_mfma_f32_16x16x32_bf16 v[12:15], v[172:175], v[188:191], v[12:15]
	v_mfma_f32_16x16x32_bf16 v[16:19], v[160:163], v[180:183], v[16:19]
	v_mfma_f32_16x16x32_bf16 v[20:23], v[164:167], v[180:183], v[20:23]
	v_mfma_f32_16x16x32_bf16 v[24:27], v[168:171], v[180:183], v[24:27]
	v_mfma_f32_16x16x32_bf16 v[28:31], v[172:175], v[180:183], v[28:31]
	v_mfma_f32_16x16x32_bf16 v[32:35], v[160:163], v[184:187], v[32:35]
	v_mfma_f32_16x16x32_bf16 v[36:39], v[164:167], v[184:187], v[36:39]
	v_mfma_f32_16x16x32_bf16 v[40:43], v[168:171], v[184:187], v[40:43]
	v_mfma_f32_16x16x32_bf16 v[44:47], v[172:175], v[184:187], v[44:47]
	v_mfma_f32_16x16x32_bf16 v[48:51], v[160:163], v[176:179], v[48:51]
	v_mfma_f32_16x16x32_bf16 v[52:55], v[164:167], v[176:179], v[52:55]
	v_mfma_f32_16x16x32_bf16 v[56:59], v[168:171], v[176:179], v[56:59]
	v_mfma_f32_16x16x32_bf16 v[60:63], v[172:175], v[176:179], v[60:63]
	v_mfma_f32_16x16x32_bf16 v[0:3], v[160:163], v[188:191], v[0:3]
	s_setprio 0
	v_add_u32_e32 v144, 0x10400, v218
	v_add_u32_e32 v148, 0x10c00, v218
	v_add_u32_e32 v152, 0x11400, v218
	v_add_u32_e32 v156, 0x11c00, v218
	v_add_u32_e32 v176, 0x18400, v219
	v_add_u32_e32 v180, 0x18c00, v219
	v_add_u32_e32 v184, 0x19400, v219
	v_add_u32_e32 v188, 0x19c00, v219
	ds_read_b128 v[144:147], v144
	ds_read_b128 v[148:151], v148
	ds_read_b128 v[152:155], v152
	ds_read_b128 v[156:159], v156
	ds_read_b128 v[176:179], v176
	ds_read_b128 v[180:183], v180
	ds_read_b128 v[184:187], v184
	ds_read_b128 v[188:191], v188
	s_setprio 1
	v_mfma_f32_16x16x32_bf16 v[140:143], v[160:163], v[80:83], v[140:143]
	v_mfma_f32_16x16x32_bf16 v[194:197], v[164:167], v[80:83], v[136:139]
	v_mfma_f32_16x16x32_bf16 v[198:201], v[168:171], v[80:83], v[132:135]
	v_mfma_f32_16x16x32_bf16 v[204:207], v[172:175], v[80:83], v[128:131]
	v_mfma_f32_16x16x32_bf16 v[210:213], v[160:163], v[84:87], v[124:127]
	v_mfma_f32_16x16x32_bf16 v[214:217], v[164:167], v[84:87], v[120:123]
	v_mfma_f32_16x16x32_bf16 v[220:223], v[168:171], v[84:87], v[116:119]
	v_mfma_f32_16x16x32_bf16 v[224:227], v[172:175], v[84:87], v[112:115]
	v_mfma_f32_16x16x32_bf16 v[228:231], v[160:163], v[88:91], v[108:111]
	v_mfma_f32_16x16x32_bf16 v[232:235], v[164:167], v[88:91], v[104:107]
	v_mfma_f32_16x16x32_bf16 v[236:239], v[168:171], v[88:91], v[100:103]
	v_mfma_f32_16x16x32_bf16 v[240:243], v[172:175], v[88:91], v[96:99]
	v_mfma_f32_16x16x32_bf16 v[160:163], v[160:163], v[92:95], v[64:67]
	v_mfma_f32_16x16x32_bf16 v[164:167], v[164:167], v[92:95], v[68:71]
	v_mfma_f32_16x16x32_bf16 v[168:171], v[168:171], v[92:95], v[72:75]
	v_mfma_f32_16x16x32_bf16 v[172:175], v[172:175], v[92:95], v[76:79]
	s_setprio 0
	v_add_u32_e32 v64, 0x12400, v218
	v_add_u32_e32 v68, 0x12c00, v218
	ds_read_b128 v[64:67], v64
	ds_read_b128 v[244:247], v68
	v_add_u32_e32 v68, 0x13400, v218
	v_add_u32_e32 v69, 0x13c00, v218
	ds_read_b128 v[248:251], v68
	ds_read_b128 v[68:71], v69
	s_setprio 1
	s_waitcnt lgkmcnt(0)
	v_mfma_f32_16x16x32_bf16 v[136:139], v[180:183], v[144:147], v[4:7]
	v_mfma_f32_16x16x32_bf16 v[132:135], v[184:187], v[144:147], v[8:11]
	v_mfma_f32_16x16x32_bf16 v[128:131], v[188:191], v[144:147], v[12:15]
	v_mfma_f32_16x16x32_bf16 v[124:127], v[176:179], v[148:151], v[16:19]
	v_mfma_f32_16x16x32_bf16 v[120:123], v[180:183], v[148:151], v[20:23]
	v_mfma_f32_16x16x32_bf16 v[116:119], v[184:187], v[148:151], v[24:27]
	v_mfma_f32_16x16x32_bf16 v[112:115], v[188:191], v[148:151], v[28:31]
	v_mfma_f32_16x16x32_bf16 v[108:111], v[176:179], v[152:155], v[32:35]
	v_mfma_f32_16x16x32_bf16 v[104:107], v[180:183], v[152:155], v[36:39]
	v_mfma_f32_16x16x32_bf16 v[100:103], v[184:187], v[152:155], v[40:43]
	v_mfma_f32_16x16x32_bf16 v[96:99], v[188:191], v[152:155], v[44:47]
	v_mfma_f32_16x16x32_bf16 v[92:95], v[176:179], v[156:159], v[48:51]
	v_mfma_f32_16x16x32_bf16 v[88:91], v[180:183], v[156:159], v[52:55]
	v_mfma_f32_16x16x32_bf16 v[84:87], v[184:187], v[156:159], v[56:59]
	v_mfma_f32_16x16x32_bf16 v[80:83], v[188:191], v[156:159], v[60:63]
	v_mfma_f32_16x16x32_bf16 v[0:3], v[176:179], v[144:147], v[0:3]
	s_setprio 0
	s_waitcnt lgkmcnt(0)
	s_waitcnt vmcnt(0)
	s_waitcnt vmcnt(0)
	s_barrier
;     static DI void run(const f32x4 (&acc)[8][4], const TileCtx& tc, const Params& p, ldsp_t wb) {
;     ...
;         const int cond = tc.brow < NLAT ? (tc.brow >> 12) : 4;
;         const float* gate = p.mod + ((size_t)tc.l * 5 + cond) * 6144 + GI * DM;
;         const int col0 = tc.bcol + tc.wc * 64 + tc.fq * 4;
;         const bool has_next = EK == 1 || tc.l + 1 < DEPTH;
;         const int ln = EK == 1 ? tc.l : (has_next ? tc.l + 1 : tc.l);
;         const float* gnx = (EK == 1 ? p.norm2_g : p.norm1_g) + (size_t)ln * DM + col0;
;         const float* scn = p.mod + ((size_t)ln * 5 + cond) * 6144 + (EK == 1 ? 4 : 1) * DM + col0;
;         float* ssp = p.ss + (size_t)(ln * 2 + (EK == 1 ? 1 : 0)) * NTOK * 16 + (tc.bcol >> 8) * 4 + tc.wc;
;         f32x4 gv[4], av[4];
; #pragma unroll
;         for (int n = 0; n < 4; ++n) {
;             gv[n] = *(const f32x4*)(gate + col0 + n * 16);
;             const f32x4 g1 = *(const f32x4*)(gnx + n * 16), s1 = *(const f32x4*)(scn + n * 16);
;             av[n] = g1 * (1.f + s1);
;         }
; #pragma unroll
;         for (int h = 0; h < 2; ++h) {
; #pragma unroll
;             for (int mm = 0; mm < 4; ++mm) { __builtin_amdgcn_sched_barrier(0);
;                 const int m = h * 4 + mm;
;                 const int row = tc.brow + tc.wr * 128 + m * 16 + tc.fr;
;                 float* xr = xrow_ptr(p, row) + col0;
;                 const float* xs = (EK == 1 && tc.l == 0) ? p.x + (size_t)row * DM + col0 : xr;
;                 float part = 0.f;
; #pragma unroll
;                 for (int n = 0; n < 4; ++n) {
;                     f32x4 xv = *(const f32x4*)(xs + n * 16);
;                     xv += gv[n] * acc[m][n];
;                     *(f32x4*)(xr + n * 16) = xv;
	s_setprio 1
	v_mfma_f32_16x16x32_bf16 v[76:79], v[176:179], v[64:67], v[140:143]
	v_mfma_f32_16x16x32_bf16 v[72:75], v[180:183], v[64:67], v[194:197]
	v_mfma_f32_16x16x32_bf16 v[194:197], v[184:187], v[64:67], v[198:201]
	v_mfma_f32_16x16x32_bf16 v[64:67], v[188:191], v[64:67], v[204:207]
	v_mfma_f32_16x16x32_bf16 v[60:63], v[176:179], v[244:247], v[210:213]
	v_mfma_f32_16x16x32_bf16 v[56:59], v[180:183], v[244:247], v[214:217]
	v_mfma_f32_16x16x32_bf16 v[52:55], v[184:187], v[244:247], v[220:223]
	v_mfma_f32_16x16x32_bf16 v[48:51], v[188:191], v[244:247], v[224:227]
	v_mfma_f32_16x16x32_bf16 v[44:47], v[176:179], v[248:251], v[228:231]
	v_mfma_f32_16x16x32_bf16 v[40:43], v[180:183], v[248:251], v[232:235]
	v_mfma_f32_16x16x32_bf16 v[36:39], v[184:187], v[248:251], v[236:239]
	v_mfma_f32_16x16x32_bf16 v[32:35], v[188:191], v[248:251], v[240:243]
	v_mfma_f32_16x16x32_bf16 v[24:27], v[176:179], v[68:71], v[160:163]
	v_mfma_f32_16x16x32_bf16 v[16:19], v[180:183], v[68:71], v[164:167]
	v_mfma_f32_16x16x32_bf16 v[8:11], v[184:187], v[68:71], v[168:171]
	v_mfma_f32_16x16x32_bf16 v[68:71], v[188:191], v[68:71], v[172:175]
	s_setprio 0
	v_mov_b32_e32 v179, v252
	s_lshl_b32 s43, s45, 8
	s_min_i32 s4, s43, 0x4000
	s_ashr_i32 s35, s4, 12
	s_lshl_b32 s34, s44, 8
	s_ashr_i32 s45, s35, 31
	s_mul_i32 s4, s48, 5
	s_add_u32 s4, s4, s35
	s_mul_hi_i32 s5, s48, 5
	v_ashrrev_i32_e32 v186, 6, v179
	s_addc_u32 s5, s5, s45
	v_mov_b64_e32 v[4:5], s[66:67]
	v_mov_b32_e32 v13, 0x6000
	v_and_b32_e32 v190, 3, v186
	v_bfe_u32 v189, v179, 4, 2
	s_mul_i32 s47, s5, 0x6000
	v_mad_u64_u32 v[6:7], s[4:5], s4, v13, v[4:5]
	v_lshlrev_b32_e32 v184, 6, v190
	v_lshlrev_b32_e32 v12, 2, v189
	s_add_u32 s4, s98, s35
	v_or3_b32 v176, v12, s34, v184
	s_addc_u32 s5, s93, s45
	v_ashrrev_i32_e32 v177, 31, v176
	s_mul_i32 s35, s5, 0x6000
	v_mad_u64_u32 v[4:5], s[4:5], s4, v13, v[4:5]
	v_lshlrev_b64 v[168:169], 2, v[176:177]
	v_add_u32_e32 v5, s35, v5
	v_add_u32_e32 v7, s47, v7
	v_lshl_add_u64 v[4:5], v[4:5], 0, v[168:169]
	s_mov_b64 s[4:5], 0x1000
	v_lshl_add_u64 v[144:145], v[4:5], 0, s[4:5]
	v_lshl_add_u64 v[6:7], v[6:7], 0, v[168:169]
	s_mov_b64 s[4:5], 0x5000
	v_lshl_add_u64 v[22:23], v[6:7], 0, s[4:5]
	s_movk_i32 s4, 0x5000
	v_add_co_u32_e32 v6, vcc, s4, v6
	v_lshl_add_u64 v[20:21], s[38:39], 0, v[168:169]
	s_nop 0
	v_addc_co_u32_e32 v7, vcc, 0, v7, vcc
	v_add_co_u32_e32 v4, vcc, s29, v4
	s_lshl_b32 s4, s44, 2
	s_nop 0
	v_addc_co_u32_e32 v5, vcc, 0, v5, vcc
	global_load_dwordx4 v[28:31], v[6:7], off
	global_load_dwordx4 v[172:175], v[4:5], off
	global_load_dwordx4 v[164:167], v[20:21], off
	global_load_dwordx4 v[156:159], v[20:21], off offset:64
	global_load_dwordx4 v[160:163], v[144:145], off offset:64
	global_load_dwordx4 v[152:155], v[144:145], off offset:128
	global_load_dwordx4 v[12:15], v[22:23], off offset:128
	global_load_dwordx4 v[4:7], v[22:23], off offset:192
	global_load_dwordx4 v[148:151], v[20:21], off offset:128
	global_load_dwordx4 v[140:143], v[20:21], off offset:192
	s_nop 0
	global_load_dwordx4 v[20:23], v[22:23], off offset:64
	s_nop 0
	global_load_dwordx4 v[144:147], v[144:145], off offset:192
	s_ashr_i32 s5, s4, 31
	s_lshl_b64 s[4:5], s[4:5], 2
	s_add_u32 s4, s10, s4
	v_and_b32_e32 v187, 15, v179
	s_addc_u32 s5, s11, s5
	v_ashrrev_i32_e32 v170, 1, v179
	v_and_b32_e32 v188, 0xffffff80, v170
	v_add_u32_e32 v178, s43, v188
	v_or_b32_e32 v180, v178, v187
	v_add_u32_e32 v170, 0xffffc000, v180
	v_ashrrev_i32_e32 v181, 31, v180
	v_cmp_gt_i32_e32 vcc, s33, v180
	v_mov_b32_e32 v182, s71
	v_mov_b32_e32 v183, s55
	v_cndmask_b32_e32 v171, 0, v181, vcc
	v_cndmask_b32_e32 v170, v170, v180, vcc
	v_cndmask_b32_e32 v183, v182, v183, vcc
	v_mov_b32_e32 v182, s70
	v_mov_b32_e32 v185, s54
	v_cndmask_b32_e32 v182, v182, v185, vcc
	v_lshlrev_b64 v[170:171], 12, v[170:171]
	v_lshl_add_u64 v[170:171], v[182:183], 0, v[170:171]
	v_lshl_add_u64 v[182:183], v[170:171], 0, v[168:169]
	global_load_dwordx4 v[168:171], v[182:183], off
	global_load_dwordx4 v[232:235], v[182:183], off offset:64
	global_load_dwordx4 v[236:239], v[182:183], off offset:128
	global_load_dwordx4 v[240:243], v[182:183], off offset:192
	s_mov_b64 s[44:45], -1
	s_and_b64 vcc, exec, s[36:37]
	s_waitcnt vmcnt(3)
	v_pk_fma_f32 v[170:171], v[2:3], v[30:31], v[170:171]
	v_pk_fma_f32 v[168:169], v[0:1], v[28:29], v[168:169]
	global_store_dwordx4 v[182:183], v[168:171], off
	s_cbranch_vccz .LBB0_198
	s_nop 1
	s_mov_b64 s[44:45], 0
	s_waitcnt vmcnt(3)
	v_pk_fma_f32 v[2:3], v[138:139], v[22:23], v[234:235]
	v_pk_fma_f32 v[0:1], v[136:137], v[20:21], v[232:233]
	global_store_dwordx4 v[182:183], v[0:3], off offset:64
	s_nop 1
	s_waitcnt vmcnt(3)
	v_pk_fma_f32 v[2:3], v[134:135], v[14:15], v[238:239]
	v_pk_fma_f32 v[0:1], v[132:133], v[12:13], v[236:237]
	global_store_dwordx4 v[182:183], v[0:3], off offset:128
	s_nop 1
	s_waitcnt vmcnt(3)
	v_pk_fma_f32 v[2:3], v[130:131], v[6:7], v[242:243]
	v_pk_fma_f32 v[0:1], v[128:129], v[4:5], v[240:241]
	global_store_dwordx4 v[182:183], v[0:3], off offset:192
; DI unsigned pk2(float a, float b) { f32x2 v = {a, b}; bf2_t r = __builtin_convertvector(v, bf2_t); return __builtin_bit_cast(unsigned, r); }
;     static DI void run(const f32x4 (&acc)[8][4], const TileCtx& tc, const Params& p, ldsp_t wb) {
;     ...
;         f32x4 gv[4], av[4];
; #pragma unroll
;         for (int n = 0; n < 4; ++n) {
;             gv[n] = *(const f32x4*)(gate + col0 + n * 16);
;             const f32x4 g1 = *(const f32x4*)(gnx + n * 16), s1 = *(const f32x4*)(scn + n * 16);
;             av[n] = g1 * (1.f + s1);
;         }
; #pragma unroll
;         for (int h = 0; h < 2; ++h) {
; #pragma unroll
;             for (int mm = 0; mm < 4; ++mm) { __builtin_amdgcn_sched_barrier(0);
;                 const int m = h * 4 + mm;
;                 const int row = tc.brow + tc.wr * 128 + m * 16 + tc.fr;
;                 float* xr = xrow_ptr(p, row) + col0;
;                 const float* xs = (EK == 1 && tc.l == 0) ? p.x + (size_t)row * DM + col0 : xr;
;                 float part = 0.f;
; #pragma unroll
;                 for (int n = 0; n < 4; ++n) {
;                     f32x4 xv = *(const f32x4*)(xs + n * 16);
;                     xv += gv[n] * acc[m][n];
;                     *(f32x4*)(xr + n * 16) = xv;
;                     if (has_next) {
;                         part += xv[0] * xv[0] + xv[1] * xv[1] + xv[2] * xv[2] + xv[3] * xv[3];
;                         const f32x4 hv = xv * av[n];
;                         u32x2 w; w[0] = pk2(hv[0], hv[1]); w[1] = pk2(hv[2], hv[3]);
;                         wave_put(wb, mm * 16 + tc.fr, n, tc.fq, w);
;                     }
;                 }
;                 if (has_next) {
;                     part += __shfl_xor(part, 16);
;                     part += __shfl_xor(part, 32);
;                     if (tc.fq == 0) ssp[(size_t)row * 16] = part;
;                 }
.LBB0_198:
	s_nop 1
	v_mov_b32_e32 v0, 0x10000
	v_lshl_add_u32 v186, v186, 13, v0
	v_pk_add_f32 v[0:1], v[174:175], 1.0 op_sel_hi:[1,0]
	v_pk_add_f32 v[2:3], v[172:173], 1.0 op_sel_hi:[1,0]
	v_pk_mul_f32 v[166:167], v[166:167], v[0:1]
	v_pk_mul_f32 v[164:165], v[164:165], v[2:3]
	v_pk_add_f32 v[0:1], v[162:163], 1.0 op_sel_hi:[1,0]
	v_pk_add_f32 v[2:3], v[160:161], 1.0 op_sel_hi:[1,0]
	v_pk_mul_f32 v[158:159], v[158:159], v[0:1]
	v_pk_mul_f32 v[156:157], v[156:157], v[2:3]
	v_pk_add_f32 v[0:1], v[154:155], 1.0 op_sel_hi:[1,0]
	v_pk_add_f32 v[2:3], v[152:153], 1.0 op_sel_hi:[1,0]
	v_and_b32_e32 v185, 63, v179
	v_pk_mul_f32 v[150:151], v[150:151], v[0:1]
	v_pk_mul_f32 v[148:149], v[148:149], v[2:3]
	v_pk_add_f32 v[0:1], v[146:147], 1.0 op_sel_hi:[1,0]
	v_pk_add_f32 v[2:3], v[144:145], 1.0 op_sel_hi:[1,0]
	v_pk_mul_f32 v[142:143], v[142:143], v[0:1]
	v_pk_mul_f32 v[144:145], v[140:141], v[2:3]
	v_lshlrev_b32_e32 v192, 2, v190
	v_lshrrev_b32_e32 v0, 5, v185
	v_and_b32_e32 v1, 7, v179
	v_lshlrev_b32_e32 v2, 3, v189
	v_lshl_add_u64 v[140:141], s[4:5], 0, v[192:193]
	s_andn2_b64 vcc, exec, s[44:45]
	v_lshl_add_u32 v146, v187, 7, v186
	v_cmp_gt_u32_e64 s[4:5], 16, v185
	v_bitop3_b32 v155, v0, v179, 7 bitop3:0x78
	v_and_b32_e32 v147, 8, v2
	v_bitop3_b32 v154, v0, v1, 2 bitop3:0x36
	v_bitop3_b32 v153, v0, v1, 4 bitop3:0x36
	v_bitop3_b32 v152, v0, v1, 6 bitop3:0x36
	v_xor_b32_e32 v230, 16, v202
	s_cbranch_vccnz .LBB0_202
	v_pk_mul_f32 v[0:1], v[166:167], v[170:171]
	v_pk_mul_f32 v[2:3], v[164:165], v[168:169]
	v_mul_f32_e32 v160, v169, v169
	v_cvt_pk_bf16_f32 v2, v2, v3
	v_cvt_pk_bf16_f32 v3, v0, v1
	v_lshlrev_b32_e32 v0, 4, v155
	v_add3_u32 v0, v146, v0, v147
	ds_write_b64 v0, v[2:3]
	s_nop 1
	v_fmac_f32_e32 v160, v168, v168
	v_fmac_f32_e32 v160, v170, v170
	v_fmac_f32_e32 v160, v171, v171
	v_cmp_lt_i32_e32 vcc, v230, v203
	s_waitcnt vmcnt(3)
	v_pk_fma_f32 v[0:1], v[136:137], v[20:21], v[232:233]
	s_nop 0
	v_mul_f32_e32 v136, v1, v1
	v_pk_fma_f32 v[2:3], v[138:139], v[22:23], v[234:235]
	v_fmac_f32_e32 v136, v0, v0
	v_fmac_f32_e32 v136, v2, v2
	global_store_dwordx4 v[182:183], v[0:3], off offset:64
	v_fmac_f32_e32 v136, v3, v3
	v_add_f32_e32 v136, v160, v136
	v_pk_mul_f32 v[2:3], v[158:159], v[2:3]
	v_pk_mul_f32 v[0:1], v[156:157], v[0:1]
	s_nop 0
	v_cvt_pk_bf16_f32 v0, v0, v1
	v_cvt_pk_bf16_f32 v1, v2, v3
	v_lshlrev_b32_e32 v2, 4, v154
	v_add3_u32 v2, v146, v2, v147
	ds_write_b64 v2, v[0:1]
	s_nop 1
	s_waitcnt vmcnt(3)
	v_pk_fma_f32 v[0:1], v[132:133], v[12:13], v[236:237]
	s_nop 0
	v_mul_f32_e32 v132, v1, v1
	v_pk_fma_f32 v[2:3], v[134:135], v[14:15], v[238:239]
	v_fmac_f32_e32 v132, v0, v0
	v_fmac_f32_e32 v132, v2, v2
	global_store_dwordx4 v[182:183], v[0:3], off offset:128
	v_fmac_f32_e32 v132, v3, v3
	v_add_f32_e32 v132, v136, v132
	v_pk_mul_f32 v[2:3], v[150:151], v[2:3]
	v_pk_mul_f32 v[0:1], v[148:149], v[0:1]
	s_nop 0
	v_cvt_pk_bf16_f32 v0, v0, v1
	v_cvt_pk_bf16_f32 v1, v2, v3
	v_lshlrev_b32_e32 v2, 4, v153
	v_add3_u32 v2, v146, v2, v147
	ds_write_b64 v2, v[0:1]
	s_nop 1
	s_waitcnt vmcnt(3)
	v_pk_fma_f32 v[0:1], v[128:129], v[4:5], v[240:241]
	s_nop 0
	v_mul_f32_e32 v128, v1, v1
	v_pk_fma_f32 v[2:3], v[130:131], v[6:7], v[242:243]
	v_fmac_f32_e32 v128, v0, v0
	v_fmac_f32_e32 v128, v2, v2
	global_store_dwordx4 v[182:183], v[0:3], off offset:192
	v_fmac_f32_e32 v128, v3, v3
	v_add_f32_e32 v128, v132, v128
	v_pk_mul_f32 v[2:3], v[142:143], v[2:3]
	v_pk_mul_f32 v[0:1], v[144:145], v[0:1]
	s_nop 0
	v_cvt_pk_bf16_f32 v0, v0, v1
	v_cvt_pk_bf16_f32 v1, v2, v3
	v_lshlrev_b32_e32 v2, 4, v152
	v_add3_u32 v2, v146, v2, v147
	ds_write_b64 v2, v[0:1]
	v_cndmask_b32_e32 v0, v202, v230, vcc
	v_lshlrev_b32_e32 v0, 2, v0
	ds_bpermute_b32 v0, v0, v128
	v_cmp_lt_i32_e32 vcc, v209, v203
	s_waitcnt lgkmcnt(0)
	v_add_f32_e32 v128, v128, v0
	v_cndmask_b32_e32 v0, v202, v209, vcc
	v_lshlrev_b32_e32 v0, 2, v0
	ds_bpermute_b32 v129, v0, v128
	s_and_saveexec_b64 s[44:45], s[4:5]
	s_cbranch_execz .LBB0_201
	v_lshlrev_b64 v[0:1], 6, v[180:181]
	s_waitcnt lgkmcnt(0)
	v_add_f32_e32 v2, v128, v129
	v_lshl_add_u64 v[0:1], v[140:141], 0, v[0:1]
	global_store_dword v[0:1], v2, off

; DI unsigned pk2(float a, float b) { f32x2 v = {a, b}; bf2_t r = __builtin_convertvector(v, bf2_t); return __builtin_bit_cast(unsigned, r); }
;     static DI void run(const f32x4 (&acc)[8][4], const TileCtx& tc, const Params& p, ldsp_t wb) {
;     ...
;             for (int mm = 0; mm < 4; ++mm) { __builtin_amdgcn_sched_barrier(0);
;                 const int m = h * 4 + mm;
;                 const int row = tc.brow + tc.wr * 128 + m * 16 + tc.fr;
;                 float* xr = xrow_ptr(p, row) + col0;
;                 const float* xs = (EK == 1 && tc.l == 0) ? p.x + (size_t)row * DM + col0 : xr;
;                 float part = 0.f;
; #pragma unroll
;                 for (int n = 0; n < 4; ++n) {
;                     f32x4 xv = *(const f32x4*)(xs + n * 16);
;                     xv += gv[n] * acc[m][n];
;                     *(f32x4*)(xr + n * 16) = xv;
;                     if (has_next) {
;                         part += xv[0] * xv[0] + xv[1] * xv[1] + xv[2] * xv[2] + xv[3] * xv[3];
;                         const f32x4 hv = xv * av[n];
;                         u32x2 w; w[0] = pk2(hv[0], hv[1]); w[1] = pk2(hv[2], hv[3]);
;                         wave_put(wb, mm * 16 + tc.fr, n, tc.fq, w);
;                     }
;                 }
;                 if (has_next) {
;                     part += __shfl_xor(part, 16);
;                     part += __shfl_xor(part, 32);
;                     if (tc.fq == 0) ssp[(size_t)row * 16] = part;
;                 }
.LBB0_202:
	v_or_b32_e32 v0, s43, v187
	v_add_u32_e32 v132, v188, v0
	v_add_u32_e32 v128, 16, v132
	v_add_u32_e32 v0, 0xffffc010, v132
	s_waitcnt lgkmcnt(0)
	v_ashrrev_i32_e32 v129, 31, v128
	v_cmp_gt_i32_e32 vcc, s33, v128
	v_mov_b32_e32 v2, s71
	v_mov_b32_e32 v3, s55
	v_cndmask_b32_e32 v1, 0, v129, vcc
	v_cndmask_b32_e32 v0, v0, v128, vcc
	v_cndmask_b32_e32 v3, v2, v3, vcc
	v_mov_b32_e32 v2, s70
	v_mov_b32_e32 v130, s54
	v_cndmask_b32_e32 v2, v2, v130, vcc
	v_lshlrev_b64 v[0:1], 12, v[0:1]
	v_lshl_add_u64 v[0:1], v[2:3], 0, v[0:1]
	v_lshl_add_u64 v[130:131], v[176:177], 2, v[0:1]
	global_load_dwordx4 v[0:3], v[130:131], off
	global_load_dwordx4 v[232:235], v[130:131], off offset:64
	global_load_dwordx4 v[236:239], v[130:131], off offset:128
	global_load_dwordx4 v[240:243], v[130:131], off offset:192
	s_mov_b64 s[4:5], -1
	s_and_b64 vcc, exec, s[36:37]
	s_waitcnt vmcnt(3)
	v_pk_fma_f32 v[126:127], v[126:127], v[30:31], v[2:3]
	v_pk_fma_f32 v[124:125], v[124:125], v[28:29], v[0:1]
	global_store_dwordx4 v[130:131], v[124:127], off
	s_cbranch_vccz .LBB0_204
	s_nop 1
	s_mov_b64 s[4:5], 0
	s_waitcnt vmcnt(3)
	v_pk_fma_f32 v[2:3], v[122:123], v[22:23], v[234:235]
	v_pk_fma_f32 v[0:1], v[120:121], v[20:21], v[232:233]
	global_store_dwordx4 v[130:131], v[0:3], off offset:64
	s_nop 1
	s_waitcnt vmcnt(3)
	v_pk_fma_f32 v[2:3], v[118:119], v[14:15], v[238:239]
	v_pk_fma_f32 v[0:1], v[116:117], v[12:13], v[236:237]
	global_store_dwordx4 v[130:131], v[0:3], off offset:128
	s_nop 1
	s_waitcnt vmcnt(3)
	v_pk_fma_f32 v[2:3], v[114:115], v[6:7], v[242:243]
	v_pk_fma_f32 v[0:1], v[112:113], v[4:5], v[240:241]
	global_store_dwordx4 v[130:131], v[0:3], off offset:192
.LBB0_204:
	s_andn2_b64 vcc, exec, s[4:5]
	v_xor_b32_e32 v134, 1, v202
	v_xor_b32_e32 v135, 2, v202
	s_cbranch_vccnz .LBB0_208
	v_pk_mul_f32 v[0:1], v[166:167], v[126:127]
	v_pk_mul_f32 v[2:3], v[164:165], v[124:125]
	v_mul_f32_e32 v133, v125, v125
	v_cvt_pk_bf16_f32 v2, v2, v3
	v_cvt_pk_bf16_f32 v3, v0, v1
	v_lshlrev_b32_e32 v0, 4, v155
	v_add3_u32 v0, v146, v0, v147
	ds_write_b64 v0, v[2:3] offset:2048
	s_nop 1
	v_fmac_f32_e32 v133, v124, v124
	v_fmac_f32_e32 v133, v126, v126
	v_fmac_f32_e32 v133, v127, v127
	v_cmp_lt_i32_e32 vcc, v230, v203
	s_waitcnt vmcnt(3)
	v_pk_fma_f32 v[0:1], v[120:121], v[20:21], v[232:233]
	s_nop 0
	v_mul_f32_e32 v120, v1, v1
	v_pk_fma_f32 v[2:3], v[122:123], v[22:23], v[234:235]
	v_fmac_f32_e32 v120, v0, v0
	v_fmac_f32_e32 v120, v2, v2
	global_store_dwordx4 v[130:131], v[0:3], off offset:64
	v_fmac_f32_e32 v120, v3, v3
	v_add_f32_e32 v120, v133, v120
	v_pk_mul_f32 v[2:3], v[158:159], v[2:3]
	v_pk_mul_f32 v[0:1], v[156:157], v[0:1]
	s_nop 0
	v_cvt_pk_bf16_f32 v0, v0, v1
	v_cvt_pk_bf16_f32 v1, v2, v3
	v_lshlrev_b32_e32 v2, 4, v154
	v_add3_u32 v2, v146, v2, v147
	ds_write_b64 v2, v[0:1] offset:2048
	s_nop 1
	s_waitcnt vmcnt(3)
	v_pk_fma_f32 v[0:1], v[116:117], v[12:13], v[236:237]
	s_nop 0
	v_mul_f32_e32 v116, v1, v1
	v_pk_fma_f32 v[2:3], v[118:119], v[14:15], v[238:239]
	v_fmac_f32_e32 v116, v0, v0
	v_fmac_f32_e32 v116, v2, v2
	global_store_dwordx4 v[130:131], v[0:3], off offset:128
	v_fmac_f32_e32 v116, v3, v3
	v_add_f32_e32 v116, v120, v116
	v_pk_mul_f32 v[2:3], v[150:151], v[2:3]
	v_pk_mul_f32 v[0:1], v[148:149], v[0:1]
	s_nop 0
	v_cvt_pk_bf16_f32 v0, v0, v1
	v_cvt_pk_bf16_f32 v1, v2, v3
	v_lshlrev_b32_e32 v2, 4, v153
	v_add3_u32 v2, v146, v2, v147
	ds_write_b64 v2, v[0:1] offset:2048
	s_nop 1
	s_waitcnt vmcnt(3)
	v_pk_fma_f32 v[0:1], v[112:113], v[4:5], v[240:241]
	s_nop 0
	v_mul_f32_e32 v112, v1, v1
	v_pk_fma_f32 v[2:3], v[114:115], v[6:7], v[242:243]
	v_fmac_f32_e32 v112, v0, v0
	v_fmac_f32_e32 v112, v2, v2
	global_store_dwordx4 v[130:131], v[0:3], off offset:192
	v_fmac_f32_e32 v112, v3, v3
	v_add_f32_e32 v112, v116, v112
	v_pk_mul_f32 v[2:3], v[142:143], v[2:3]
	v_pk_mul_f32 v[0:1], v[144:145], v[0:1]
	s_nop 0
	v_cvt_pk_bf16_f32 v0, v0, v1
	v_cvt_pk_bf16_f32 v1, v2, v3
	v_lshlrev_b32_e32 v2, 4, v152
	v_add3_u32 v2, v146, v2, v147
	ds_write_b64 v2, v[0:1] offset:2048
	v_cndmask_b32_e32 v0, v202, v230, vcc
	v_lshlrev_b32_e32 v0, 2, v0
	ds_bpermute_b32 v0, v0, v112
	v_cmp_lt_i32_e32 vcc, v209, v203
	s_waitcnt lgkmcnt(0)
	v_add_f32_e32 v112, v112, v0
	v_cndmask_b32_e32 v0, v202, v209, vcc
	v_lshlrev_b32_e32 v0, 2, v0
	ds_bpermute_b32 v113, v0, v112
	v_cmp_gt_u32_e32 vcc, 16, v185
	s_and_saveexec_b64 s[4:5], vcc
	s_cbranch_execz .LBB0_207
	v_lshlrev_b64 v[0:1], 6, v[128:129]
	s_waitcnt lgkmcnt(0)
	v_add_f32_e32 v2, v112, v113
	v_lshl_add_u64 v[0:1], v[140:141], 0, v[0:1]
	global_store_dword v[0:1], v2, off

; DI unsigned pk2(float a, float b) { f32x2 v = {a, b}; bf2_t r = __builtin_convertvector(v, bf2_t); return __builtin_bit_cast(unsigned, r); }
;     static DI void run(const f32x4 (&acc)[8][4], const TileCtx& tc, const Params& p, ldsp_t wb) {
;     ...
;             for (int mm = 0; mm < 4; ++mm) { __builtin_amdgcn_sched_barrier(0);
;                 const int m = h * 4 + mm;
;                 const int row = tc.brow + tc.wr * 128 + m * 16 + tc.fr;
;                 float* xr = xrow_ptr(p, row) + col0;
;                 const float* xs = (EK == 1 && tc.l == 0) ? p.x + (size_t)row * DM + col0 : xr;
;                 float part = 0.f;
; #pragma unroll
;                 for (int n = 0; n < 4; ++n) {
;                     f32x4 xv = *(const f32x4*)(xs + n * 16);
;                     xv += gv[n] * acc[m][n];
;                     *(f32x4*)(xr + n * 16) = xv;
;                     if (has_next) {
;                         part += xv[0] * xv[0] + xv[1] * xv[1] + xv[2] * xv[2] + xv[3] * xv[3];
;                         const f32x4 hv = xv * av[n];
;                         u32x2 w; w[0] = pk2(hv[0], hv[1]); w[1] = pk2(hv[2], hv[3]);
;                         wave_put(wb, mm * 16 + tc.fr, n, tc.fq, w);
;                     }
;                 }
;                 if (has_next) {
;                     part += __shfl_xor(part, 16);
;                     part += __shfl_xor(part, 32);
;                     if (tc.fq == 0) ssp[(size_t)row * 16] = part;
;                 }
.LBB0_208:
	v_add_u32_e32 v112, 32, v132
	v_add_u32_e32 v0, 0xffffc020, v132
	s_waitcnt lgkmcnt(0)
	v_ashrrev_i32_e32 v113, 31, v112
	v_cmp_gt_i32_e32 vcc, s33, v112
	v_mov_b32_e32 v2, s71
	v_mov_b32_e32 v3, s55
	v_cndmask_b32_e32 v1, 0, v113, vcc
	v_cndmask_b32_e32 v0, v0, v112, vcc
	v_cndmask_b32_e32 v3, v2, v3, vcc
	v_mov_b32_e32 v2, s70
	v_mov_b32_e32 v114, s54
	v_cndmask_b32_e32 v2, v2, v114, vcc
	v_lshlrev_b64 v[0:1], 12, v[0:1]
	v_lshl_add_u64 v[0:1], v[2:3], 0, v[0:1]
	v_lshl_add_u64 v[114:115], v[176:177], 2, v[0:1]
	global_load_dwordx4 v[0:3], v[114:115], off
	global_load_dwordx4 v[232:235], v[114:115], off offset:64
	global_load_dwordx4 v[236:239], v[114:115], off offset:128
	global_load_dwordx4 v[240:243], v[114:115], off offset:192
	s_mov_b64 s[4:5], -1
	s_and_b64 vcc, exec, s[36:37]
	s_waitcnt vmcnt(3)
	v_pk_fma_f32 v[110:111], v[110:111], v[30:31], v[2:3]
	v_pk_fma_f32 v[108:109], v[108:109], v[28:29], v[0:1]
	global_store_dwordx4 v[114:115], v[108:111], off
	s_cbranch_vccz .LBB0_210
	s_nop 1
	s_mov_b64 s[4:5], 0
	s_waitcnt vmcnt(3)
	v_pk_fma_f32 v[2:3], v[106:107], v[22:23], v[234:235]
	v_pk_fma_f32 v[0:1], v[104:105], v[20:21], v[232:233]
	global_store_dwordx4 v[114:115], v[0:3], off offset:64
	s_nop 1
	s_waitcnt vmcnt(3)
	v_pk_fma_f32 v[2:3], v[102:103], v[14:15], v[238:239]
	v_pk_fma_f32 v[0:1], v[100:101], v[12:13], v[236:237]
	global_store_dwordx4 v[114:115], v[0:3], off offset:128
	s_nop 1
	s_waitcnt vmcnt(3)
	v_pk_fma_f32 v[2:3], v[98:99], v[6:7], v[242:243]
	v_pk_fma_f32 v[0:1], v[96:97], v[4:5], v[240:241]
	global_store_dwordx4 v[114:115], v[0:3], off offset:192
.LBB0_210:
	s_andn2_b64 vcc, exec, s[4:5]
	s_cbranch_vccnz .LBB0_214
	v_pk_mul_f32 v[0:1], v[166:167], v[110:111]
	v_pk_mul_f32 v[2:3], v[164:165], v[108:109]
	v_mul_f32_e32 v116, v109, v109
	v_cvt_pk_bf16_f32 v2, v2, v3
	v_cvt_pk_bf16_f32 v3, v0, v1
	v_lshlrev_b32_e32 v0, 4, v155
	v_add3_u32 v0, v146, v0, v147
	ds_write_b64 v0, v[2:3] offset:4096
	s_nop 1
	v_fmac_f32_e32 v116, v108, v108
	v_fmac_f32_e32 v116, v110, v110
	v_fmac_f32_e32 v116, v111, v111
	v_cmp_lt_i32_e32 vcc, v230, v203
	s_waitcnt vmcnt(3)
	v_pk_fma_f32 v[0:1], v[104:105], v[20:21], v[232:233]
	s_nop 0
	v_mul_f32_e32 v104, v1, v1
	v_pk_fma_f32 v[2:3], v[106:107], v[22:23], v[234:235]
	v_fmac_f32_e32 v104, v0, v0
	v_fmac_f32_e32 v104, v2, v2
	global_store_dwordx4 v[114:115], v[0:3], off offset:64
	v_fmac_f32_e32 v104, v3, v3
	v_add_f32_e32 v104, v116, v104
	v_pk_mul_f32 v[2:3], v[158:159], v[2:3]
	v_pk_mul_f32 v[0:1], v[156:157], v[0:1]
	s_nop 0
	v_cvt_pk_bf16_f32 v0, v0, v1
	v_cvt_pk_bf16_f32 v1, v2, v3
	v_lshlrev_b32_e32 v2, 4, v154
	v_add3_u32 v2, v146, v2, v147
	ds_write_b64 v2, v[0:1] offset:4096
	s_nop 1
	s_waitcnt vmcnt(3)
	v_pk_fma_f32 v[0:1], v[100:101], v[12:13], v[236:237]
	s_nop 0
	v_mul_f32_e32 v100, v1, v1
	v_pk_fma_f32 v[2:3], v[102:103], v[14:15], v[238:239]
	v_fmac_f32_e32 v100, v0, v0
	v_fmac_f32_e32 v100, v2, v2
	global_store_dwordx4 v[114:115], v[0:3], off offset:128
	v_fmac_f32_e32 v100, v3, v3
	v_add_f32_e32 v100, v104, v100
	v_pk_mul_f32 v[2:3], v[150:151], v[2:3]
	v_pk_mul_f32 v[0:1], v[148:149], v[0:1]
	s_nop 0
	v_cvt_pk_bf16_f32 v0, v0, v1
	v_cvt_pk_bf16_f32 v1, v2, v3
	v_lshlrev_b32_e32 v2, 4, v153
	v_add3_u32 v2, v146, v2, v147
	ds_write_b64 v2, v[0:1] offset:4096
	s_nop 1
	s_waitcnt vmcnt(3)
	v_pk_fma_f32 v[0:1], v[96:97], v[4:5], v[240:241]
	s_nop 0
	v_mul_f32_e32 v96, v1, v1
	v_pk_fma_f32 v[2:3], v[98:99], v[6:7], v[242:243]
	v_fmac_f32_e32 v96, v0, v0
	v_fmac_f32_e32 v96, v2, v2
	global_store_dwordx4 v[114:115], v[0:3], off offset:192
	v_fmac_f32_e32 v96, v3, v3
	v_add_f32_e32 v96, v100, v96
	v_pk_mul_f32 v[2:3], v[142:143], v[2:3]
	v_pk_mul_f32 v[0:1], v[144:145], v[0:1]
	s_nop 0
	v_cvt_pk_bf16_f32 v0, v0, v1
	v_cvt_pk_bf16_f32 v1, v2, v3
	v_lshlrev_b32_e32 v2, 4, v152
	v_add3_u32 v2, v146, v2, v147
	ds_write_b64 v2, v[0:1] offset:4096
	v_cndmask_b32_e32 v0, v202, v230, vcc
	v_lshlrev_b32_e32 v0, 2, v0
	ds_bpermute_b32 v0, v0, v96
	v_cmp_lt_i32_e32 vcc, v209, v203
	s_waitcnt lgkmcnt(0)
	v_add_f32_e32 v96, v96, v0
	v_cndmask_b32_e32 v0, v202, v209, vcc
	v_lshlrev_b32_e32 v0, 2, v0
	ds_bpermute_b32 v97, v0, v96
	v_cmp_gt_u32_e32 vcc, 16, v185
	s_and_saveexec_b64 s[4:5], vcc
	s_cbranch_execz .LBB0_213
	v_lshlrev_b64 v[0:1], 6, v[112:113]
	s_waitcnt lgkmcnt(0)
	v_add_f32_e32 v2, v96, v97
	v_lshl_add_u64 v[0:1], v[140:141], 0, v[0:1]
	global_store_dword v[0:1], v2, off

; DI unsigned pk2(float a, float b) { f32x2 v = {a, b}; bf2_t r = __builtin_convertvector(v, bf2_t); return __builtin_bit_cast(unsigned, r); }
;     static DI void run(const f32x4 (&acc)[8][4], const TileCtx& tc, const Params& p, ldsp_t wb) {
;     ...
;             for (int mm = 0; mm < 4; ++mm) { __builtin_amdgcn_sched_barrier(0);
;                 const int m = h * 4 + mm;
;                 const int row = tc.brow + tc.wr * 128 + m * 16 + tc.fr;
;                 float* xr = xrow_ptr(p, row) + col0;
;                 const float* xs = (EK == 1 && tc.l == 0) ? p.x + (size_t)row * DM + col0 : xr;
;                 float part = 0.f;
; #pragma unroll
;                 for (int n = 0; n < 4; ++n) {
;                     f32x4 xv = *(const f32x4*)(xs + n * 16);
;                     xv += gv[n] * acc[m][n];
;                     *(f32x4*)(xr + n * 16) = xv;
;                     if (has_next) {
;                         part += xv[0] * xv[0] + xv[1] * xv[1] + xv[2] * xv[2] + xv[3] * xv[3];
;                         const f32x4 hv = xv * av[n];
;                         u32x2 w; w[0] = pk2(hv[0], hv[1]); w[1] = pk2(hv[2], hv[3]);
;                         wave_put(wb, mm * 16 + tc.fr, n, tc.fq, w);
;                     }
;                 }
;                 if (has_next) {
;                     part += __shfl_xor(part, 16);
;                     part += __shfl_xor(part, 32);
;                     if (tc.fq == 0) ssp[(size_t)row * 16] = part;
;                 }
.LBB0_214:
	v_add_u32_e32 v96, 48, v132
	v_add_u32_e32 v0, 0xffffc030, v132
	s_waitcnt lgkmcnt(0)
	v_ashrrev_i32_e32 v97, 31, v96
	v_cmp_gt_i32_e32 vcc, s33, v96
	v_mov_b32_e32 v2, s71
	v_mov_b32_e32 v3, s55
	v_cndmask_b32_e32 v1, 0, v97, vcc
	v_cndmask_b32_e32 v0, v0, v96, vcc
	v_cndmask_b32_e32 v3, v2, v3, vcc
	v_mov_b32_e32 v2, s70
	v_mov_b32_e32 v98, s54
	v_cndmask_b32_e32 v2, v2, v98, vcc
	v_lshlrev_b64 v[0:1], 12, v[0:1]
	v_lshl_add_u64 v[0:1], v[2:3], 0, v[0:1]
	v_lshl_add_u64 v[98:99], v[176:177], 2, v[0:1]
	global_load_dwordx4 v[0:3], v[98:99], off
	global_load_dwordx4 v[232:235], v[98:99], off offset:64
	global_load_dwordx4 v[236:239], v[98:99], off offset:128
	global_load_dwordx4 v[240:243], v[98:99], off offset:192
	s_mov_b64 s[4:5], -1
	s_and_b64 vcc, exec, s[36:37]
	s_waitcnt vmcnt(3)
	v_pk_fma_f32 v[94:95], v[94:95], v[30:31], v[2:3]
	v_pk_fma_f32 v[92:93], v[92:93], v[28:29], v[0:1]
	global_store_dwordx4 v[98:99], v[92:95], off
	s_cbranch_vccz .LBB0_216
	s_nop 1
	s_mov_b64 s[4:5], 0
	s_waitcnt vmcnt(3)
	v_pk_fma_f32 v[2:3], v[90:91], v[22:23], v[234:235]
	v_pk_fma_f32 v[0:1], v[88:89], v[20:21], v[232:233]
	global_store_dwordx4 v[98:99], v[0:3], off offset:64
	s_nop 1
	s_waitcnt vmcnt(3)
	v_pk_fma_f32 v[2:3], v[86:87], v[14:15], v[238:239]
	v_pk_fma_f32 v[0:1], v[84:85], v[12:13], v[236:237]
	global_store_dwordx4 v[98:99], v[0:3], off offset:128
	s_nop 1
	s_waitcnt vmcnt(3)
	v_pk_fma_f32 v[2:3], v[82:83], v[6:7], v[242:243]
	v_pk_fma_f32 v[0:1], v[80:81], v[4:5], v[240:241]
	global_store_dwordx4 v[98:99], v[0:3], off offset:192
.LBB0_216:
	s_andn2_b64 vcc, exec, s[4:5]
	s_cbranch_vccnz .LBB0_220
	v_pk_mul_f32 v[0:1], v[166:167], v[94:95]
	v_pk_mul_f32 v[2:3], v[164:165], v[92:93]
	v_mul_f32_e32 v100, v93, v93
	v_cvt_pk_bf16_f32 v2, v2, v3
	v_cvt_pk_bf16_f32 v3, v0, v1
	v_lshlrev_b32_e32 v0, 4, v155
	v_add3_u32 v0, v146, v0, v147
	ds_write_b64 v0, v[2:3] offset:6144
	s_nop 1
	v_fmac_f32_e32 v100, v92, v92
	v_fmac_f32_e32 v100, v94, v94
	v_fmac_f32_e32 v100, v95, v95
	v_cmp_lt_i32_e32 vcc, v230, v203
	s_waitcnt vmcnt(3)
	v_pk_fma_f32 v[0:1], v[88:89], v[20:21], v[232:233]
	s_nop 0
	v_mul_f32_e32 v88, v1, v1
	v_pk_fma_f32 v[2:3], v[90:91], v[22:23], v[234:235]
	v_fmac_f32_e32 v88, v0, v0
	v_fmac_f32_e32 v88, v2, v2
	global_store_dwordx4 v[98:99], v[0:3], off offset:64
	v_fmac_f32_e32 v88, v3, v3
	v_add_f32_e32 v88, v100, v88
	v_pk_mul_f32 v[2:3], v[158:159], v[2:3]
	v_pk_mul_f32 v[0:1], v[156:157], v[0:1]
	s_nop 0
	v_cvt_pk_bf16_f32 v0, v0, v1
	v_cvt_pk_bf16_f32 v1, v2, v3
	v_lshlrev_b32_e32 v2, 4, v154
	v_add3_u32 v2, v146, v2, v147
	ds_write_b64 v2, v[0:1] offset:6144
	s_nop 1
	s_waitcnt vmcnt(3)
	v_pk_fma_f32 v[0:1], v[84:85], v[12:13], v[236:237]
	s_nop 0
	v_mul_f32_e32 v84, v1, v1
	v_pk_fma_f32 v[2:3], v[86:87], v[14:15], v[238:239]
	v_fmac_f32_e32 v84, v0, v0
	v_fmac_f32_e32 v84, v2, v2
	global_store_dwordx4 v[98:99], v[0:3], off offset:128
	v_fmac_f32_e32 v84, v3, v3
	v_add_f32_e32 v84, v88, v84
	v_pk_mul_f32 v[2:3], v[150:151], v[2:3]
	v_pk_mul_f32 v[0:1], v[148:149], v[0:1]
	s_nop 0
	v_cvt_pk_bf16_f32 v0, v0, v1
	v_cvt_pk_bf16_f32 v1, v2, v3
	v_lshlrev_b32_e32 v2, 4, v153
	v_add3_u32 v2, v146, v2, v147
	ds_write_b64 v2, v[0:1] offset:6144
	s_nop 1
	s_waitcnt vmcnt(3)
	v_pk_fma_f32 v[0:1], v[80:81], v[4:5], v[240:241]
	s_nop 0
	v_mul_f32_e32 v80, v1, v1
	v_pk_fma_f32 v[2:3], v[82:83], v[6:7], v[242:243]
	v_fmac_f32_e32 v80, v0, v0
	v_fmac_f32_e32 v80, v2, v2
	global_store_dwordx4 v[98:99], v[0:3], off offset:192
	v_fmac_f32_e32 v80, v3, v3
	v_add_f32_e32 v80, v84, v80
	v_pk_mul_f32 v[2:3], v[142:143], v[2:3]
	v_pk_mul_f32 v[0:1], v[144:145], v[0:1]
	s_nop 0
	v_cvt_pk_bf16_f32 v0, v0, v1
	v_cvt_pk_bf16_f32 v1, v2, v3
	v_lshlrev_b32_e32 v2, 4, v152
	v_add3_u32 v2, v146, v2, v147
	ds_write_b64 v2, v[0:1] offset:6144
	v_cndmask_b32_e32 v0, v202, v230, vcc
	v_lshlrev_b32_e32 v0, 2, v0
	ds_bpermute_b32 v0, v0, v80
	v_cmp_lt_i32_e32 vcc, v209, v203
	s_waitcnt lgkmcnt(0)
	v_add_f32_e32 v80, v80, v0
	v_cndmask_b32_e32 v0, v202, v209, vcc
	v_lshlrev_b32_e32 v0, 2, v0
	ds_bpermute_b32 v81, v0, v80
	v_cmp_gt_u32_e32 vcc, 16, v185
	s_and_saveexec_b64 s[4:5], vcc
	s_cbranch_execz .LBB0_219
	v_lshlrev_b64 v[0:1], 6, v[96:97]
	s_waitcnt lgkmcnt(0)
	v_add_f32_e32 v2, v80, v81
	v_lshl_add_u64 v[0:1], v[140:141], 0, v[0:1]
	global_store_dword v[0:1], v2, off

; DI unsigned pk2(float a, float b) { f32x2 v = {a, b}; bf2_t r = __builtin_convertvector(v, bf2_t); return __builtin_bit_cast(unsigned, r); }
;     static DI void run(const f32x4 (&acc)[8][4], const TileCtx& tc, const Params& p, ldsp_t wb) {
;     ...
;             for (int mm = 0; mm < 4; ++mm) { __builtin_amdgcn_sched_barrier(0);
;                 const int m = h * 4 + mm;
;                 const int row = tc.brow + tc.wr * 128 + m * 16 + tc.fr;
;                 float* xr = xrow_ptr(p, row) + col0;
;                 const float* xs = (EK == 1 && tc.l == 0) ? p.x + (size_t)row * DM + col0 : xr;
;                 float part = 0.f;
; #pragma unroll
;                 for (int n = 0; n < 4; ++n) {
;                     f32x4 xv = *(const f32x4*)(xs + n * 16);
;                     xv += gv[n] * acc[m][n];
;                     *(f32x4*)(xr + n * 16) = xv;
;                     if (has_next) {
;                         part += xv[0] * xv[0] + xv[1] * xv[1] + xv[2] * xv[2] + xv[3] * xv[3];
;                         const f32x4 hv = xv * av[n];
;                         u32x2 w; w[0] = pk2(hv[0], hv[1]); w[1] = pk2(hv[2], hv[3]);
;                         wave_put(wb, mm * 16 + tc.fr, n, tc.fq, w);
;                     }
;                 }
;                 if (has_next) {
;                     part += __shfl_xor(part, 16);
;                     part += __shfl_xor(part, 32);
;                     if (tc.fq == 0) ssp[(size_t)row * 16] = part;
;                 }
.LBB0_220:
	v_add3_u32 v80, v188, s43, 64
	v_or_b32_e32 v82, v80, v187
	v_add_u32_e32 v0, 0xffffc000, v82
	v_ashrrev_i32_e32 v83, 31, v82
	v_cmp_gt_i32_e32 vcc, s33, v82
	v_mov_b32_e32 v2, s71
	v_mov_b32_e32 v3, s55
	v_cndmask_b32_e32 v1, 0, v83, vcc
	v_cndmask_b32_e32 v0, v0, v82, vcc
	v_cndmask_b32_e32 v3, v2, v3, vcc
	v_mov_b32_e32 v2, s70
	v_mov_b32_e32 v81, s54
	v_cndmask_b32_e32 v2, v2, v81, vcc
	v_lshlrev_b64 v[0:1], 12, v[0:1]
	v_lshl_add_u64 v[0:1], v[2:3], 0, v[0:1]
	v_lshl_add_u64 v[84:85], v[176:177], 2, v[0:1]
	global_load_dwordx4 v[0:3], v[84:85], off
	global_load_dwordx4 v[232:235], v[84:85], off offset:64
	global_load_dwordx4 v[236:239], v[84:85], off offset:128
	global_load_dwordx4 v[240:243], v[84:85], off offset:192
	s_mov_b64 s[4:5], -1
	s_and_b64 vcc, exec, s[36:37]
	s_waitcnt vmcnt(3)
	v_pk_fma_f32 v[78:79], v[78:79], v[30:31], v[2:3]
	v_pk_fma_f32 v[76:77], v[76:77], v[28:29], v[0:1]
	global_store_dwordx4 v[84:85], v[76:79], off
	s_cbranch_vccz .LBB0_222
	s_nop 1
	s_mov_b64 s[4:5], 0
	s_waitcnt vmcnt(3)
	v_pk_fma_f32 v[2:3], v[74:75], v[22:23], v[234:235]
	v_pk_fma_f32 v[0:1], v[72:73], v[20:21], v[232:233]
	global_store_dwordx4 v[84:85], v[0:3], off offset:64
	s_nop 1
	s_waitcnt vmcnt(3)
	v_pk_fma_f32 v[2:3], v[196:197], v[14:15], v[238:239]
	v_pk_fma_f32 v[0:1], v[194:195], v[12:13], v[236:237]
	global_store_dwordx4 v[84:85], v[0:3], off offset:128
	s_nop 1
	s_waitcnt vmcnt(3)
	v_pk_fma_f32 v[2:3], v[66:67], v[6:7], v[242:243]
	v_pk_fma_f32 v[0:1], v[64:65], v[4:5], v[240:241]
	global_store_dwordx4 v[84:85], v[0:3], off offset:192
.LBB0_222:
	s_andn2_b64 vcc, exec, s[4:5]
	s_cbranch_vccnz .LBB0_226
	v_pk_mul_f32 v[0:1], v[166:167], v[78:79]
	v_pk_mul_f32 v[2:3], v[164:165], v[76:77]
	v_mul_f32_e32 v81, v77, v77
	v_cvt_pk_bf16_f32 v2, v2, v3
	v_cvt_pk_bf16_f32 v3, v0, v1
	v_lshlrev_b32_e32 v0, 4, v155
	v_add3_u32 v0, v146, v0, v147
	ds_write_b64 v0, v[2:3]
	s_nop 1
	v_fmac_f32_e32 v81, v76, v76
	v_fmac_f32_e32 v81, v78, v78
	v_fmac_f32_e32 v81, v79, v79
	v_cmp_lt_i32_e32 vcc, v230, v203
	s_waitcnt vmcnt(3)
	v_pk_fma_f32 v[0:1], v[72:73], v[20:21], v[232:233]
	s_nop 0
	v_mul_f32_e32 v72, v1, v1
	v_pk_fma_f32 v[2:3], v[74:75], v[22:23], v[234:235]
	v_fmac_f32_e32 v72, v0, v0
	v_fmac_f32_e32 v72, v2, v2
	global_store_dwordx4 v[84:85], v[0:3], off offset:64
	v_fmac_f32_e32 v72, v3, v3
	v_add_f32_e32 v72, v81, v72
	v_pk_mul_f32 v[2:3], v[158:159], v[2:3]
	v_pk_mul_f32 v[0:1], v[156:157], v[0:1]
	s_nop 0
	v_cvt_pk_bf16_f32 v0, v0, v1
	v_cvt_pk_bf16_f32 v1, v2, v3
	v_lshlrev_b32_e32 v2, 4, v154
	v_add3_u32 v2, v146, v2, v147
	ds_write_b64 v2, v[0:1]
	s_nop 1
	s_waitcnt vmcnt(3)
	v_pk_fma_f32 v[0:1], v[194:195], v[12:13], v[236:237]
	s_nop 0
	v_mul_f32_e32 v73, v1, v1
	v_pk_fma_f32 v[2:3], v[196:197], v[14:15], v[238:239]
	v_fmac_f32_e32 v73, v0, v0
	v_fmac_f32_e32 v73, v2, v2
	global_store_dwordx4 v[84:85], v[0:3], off offset:128
	v_fmac_f32_e32 v73, v3, v3
	v_add_f32_e32 v72, v72, v73
	v_pk_mul_f32 v[2:3], v[150:151], v[2:3]
	v_pk_mul_f32 v[0:1], v[148:149], v[0:1]
	s_nop 0
	v_cvt_pk_bf16_f32 v0, v0, v1
	v_cvt_pk_bf16_f32 v1, v2, v3
	v_lshlrev_b32_e32 v2, 4, v153
	v_add3_u32 v2, v146, v2, v147
	ds_write_b64 v2, v[0:1]
	s_nop 1
	s_waitcnt vmcnt(3)
	v_pk_fma_f32 v[0:1], v[64:65], v[4:5], v[240:241]
	s_nop 0
	v_mul_f32_e32 v64, v1, v1
	v_pk_fma_f32 v[2:3], v[66:67], v[6:7], v[242:243]
	v_fmac_f32_e32 v64, v0, v0
	v_fmac_f32_e32 v64, v2, v2
	global_store_dwordx4 v[84:85], v[0:3], off offset:192
	v_fmac_f32_e32 v64, v3, v3
	v_add_f32_e32 v64, v72, v64
	v_pk_mul_f32 v[2:3], v[142:143], v[2:3]
	v_pk_mul_f32 v[0:1], v[144:145], v[0:1]
	s_nop 0
	v_cvt_pk_bf16_f32 v0, v0, v1
	v_cvt_pk_bf16_f32 v1, v2, v3
	v_lshlrev_b32_e32 v2, 4, v152
	v_add3_u32 v2, v146, v2, v147
	ds_write_b64 v2, v[0:1]
	v_cndmask_b32_e32 v0, v202, v230, vcc
	v_lshlrev_b32_e32 v0, 2, v0
	ds_bpermute_b32 v0, v0, v64
	v_cmp_lt_i32_e32 vcc, v209, v203
	s_waitcnt lgkmcnt(0)
	v_add_f32_e32 v64, v64, v0
	v_cndmask_b32_e32 v0, v202, v209, vcc
	v_lshlrev_b32_e32 v0, 2, v0
	ds_bpermute_b32 v65, v0, v64
	v_cmp_gt_u32_e32 vcc, 16, v185
	s_and_saveexec_b64 s[4:5], vcc
	s_cbranch_execz .LBB0_225
	v_lshlrev_b64 v[0:1], 6, v[82:83]
	s_waitcnt lgkmcnt(0)
	v_add_f32_e32 v2, v64, v65
	v_lshl_add_u64 v[0:1], v[140:141], 0, v[0:1]
	global_store_dword v[0:1], v2, off

; DI unsigned pk2(float a, float b) { f32x2 v = {a, b}; bf2_t r = __builtin_convertvector(v, bf2_t); return __builtin_bit_cast(unsigned, r); }
;     static DI void run(const f32x4 (&acc)[8][4], const TileCtx& tc, const Params& p, ldsp_t wb) {
;     ...
;             for (int mm = 0; mm < 4; ++mm) { __builtin_amdgcn_sched_barrier(0);
;                 const int m = h * 4 + mm;
;                 const int row = tc.brow + tc.wr * 128 + m * 16 + tc.fr;
;                 float* xr = xrow_ptr(p, row) + col0;
;                 const float* xs = (EK == 1 && tc.l == 0) ? p.x + (size_t)row * DM + col0 : xr;
;                 float part = 0.f;
; #pragma unroll
;                 for (int n = 0; n < 4; ++n) {
;                     f32x4 xv = *(const f32x4*)(xs + n * 16);
;                     xv += gv[n] * acc[m][n];
;                     *(f32x4*)(xr + n * 16) = xv;
;                     if (has_next) {
;                         part += xv[0] * xv[0] + xv[1] * xv[1] + xv[2] * xv[2] + xv[3] * xv[3];
;                         const f32x4 hv = xv * av[n];
;                         u32x2 w; w[0] = pk2(hv[0], hv[1]); w[1] = pk2(hv[2], hv[3]);
;                         wave_put(wb, mm * 16 + tc.fr, n, tc.fq, w);
;                     }
;                 }
;                 if (has_next) {
;                     part += __shfl_xor(part, 16);
;                     part += __shfl_xor(part, 32);
;                     if (tc.fq == 0) ssp[(size_t)row * 16] = part;
;                 }
.LBB0_226:
	v_add_u32_e32 v64, 0x50, v132
	v_add_u32_e32 v0, 0xffffc050, v132
	s_waitcnt lgkmcnt(0)
	v_ashrrev_i32_e32 v65, 31, v64
	v_cmp_gt_i32_e32 vcc, s33, v64
	v_mov_b32_e32 v2, s71
	v_mov_b32_e32 v3, s55
	v_cndmask_b32_e32 v1, 0, v65, vcc
	v_cndmask_b32_e32 v0, v0, v64, vcc
	v_cndmask_b32_e32 v3, v2, v3, vcc
	v_mov_b32_e32 v2, s70
	v_mov_b32_e32 v66, s54
	v_cndmask_b32_e32 v2, v2, v66, vcc
	v_lshlrev_b64 v[0:1], 12, v[0:1]
	v_lshl_add_u64 v[0:1], v[2:3], 0, v[0:1]
	v_lshl_add_u64 v[66:67], v[176:177], 2, v[0:1]
	global_load_dwordx4 v[0:3], v[66:67], off
	global_load_dwordx4 v[232:235], v[66:67], off offset:64
	global_load_dwordx4 v[236:239], v[66:67], off offset:128
	global_load_dwordx4 v[240:243], v[66:67], off offset:192
	s_mov_b64 s[4:5], -1
	s_and_b64 vcc, exec, s[36:37]
	s_waitcnt vmcnt(3)
	v_pk_fma_f32 v[62:63], v[62:63], v[30:31], v[2:3]
	v_pk_fma_f32 v[60:61], v[60:61], v[28:29], v[0:1]
	global_store_dwordx4 v[66:67], v[60:63], off
	s_cbranch_vccz .LBB0_228
	s_nop 1
	s_mov_b64 s[4:5], 0
	s_waitcnt vmcnt(3)
	v_pk_fma_f32 v[2:3], v[58:59], v[22:23], v[234:235]
	v_pk_fma_f32 v[0:1], v[56:57], v[20:21], v[232:233]
	global_store_dwordx4 v[66:67], v[0:3], off offset:64
	s_nop 1
	s_waitcnt vmcnt(3)
	v_pk_fma_f32 v[2:3], v[54:55], v[14:15], v[238:239]
	v_pk_fma_f32 v[0:1], v[52:53], v[12:13], v[236:237]
	global_store_dwordx4 v[66:67], v[0:3], off offset:128
	s_nop 1
	s_waitcnt vmcnt(3)
	v_pk_fma_f32 v[2:3], v[50:51], v[6:7], v[242:243]
	v_pk_fma_f32 v[0:1], v[48:49], v[4:5], v[240:241]
	global_store_dwordx4 v[66:67], v[0:3], off offset:192
.LBB0_228:
	s_andn2_b64 vcc, exec, s[4:5]
	s_cbranch_vccnz .LBB0_232
	v_pk_mul_f32 v[0:1], v[166:167], v[62:63]
	v_pk_mul_f32 v[2:3], v[164:165], v[60:61]
	v_mul_f32_e32 v72, v61, v61
	v_cvt_pk_bf16_f32 v2, v2, v3
	v_cvt_pk_bf16_f32 v3, v0, v1
	v_lshlrev_b32_e32 v0, 4, v155
	v_add3_u32 v0, v146, v0, v147
	ds_write_b64 v0, v[2:3] offset:2048
	s_nop 1
	v_fmac_f32_e32 v72, v60, v60
	v_fmac_f32_e32 v72, v62, v62
	v_fmac_f32_e32 v72, v63, v63
	v_cmp_lt_i32_e32 vcc, v230, v203
	s_waitcnt vmcnt(3)
	v_pk_fma_f32 v[0:1], v[56:57], v[20:21], v[232:233]
	s_nop 0
	v_mul_f32_e32 v56, v1, v1
	v_pk_fma_f32 v[2:3], v[58:59], v[22:23], v[234:235]
	v_fmac_f32_e32 v56, v0, v0
	v_fmac_f32_e32 v56, v2, v2
	global_store_dwordx4 v[66:67], v[0:3], off offset:64
	v_fmac_f32_e32 v56, v3, v3
	v_add_f32_e32 v56, v72, v56
	v_pk_mul_f32 v[2:3], v[158:159], v[2:3]
	v_pk_mul_f32 v[0:1], v[156:157], v[0:1]
	s_nop 0
	v_cvt_pk_bf16_f32 v0, v0, v1
	v_cvt_pk_bf16_f32 v1, v2, v3
	v_lshlrev_b32_e32 v2, 4, v154
	v_add3_u32 v2, v146, v2, v147
	ds_write_b64 v2, v[0:1] offset:2048
	s_nop 1
	s_waitcnt vmcnt(3)
	v_pk_fma_f32 v[0:1], v[52:53], v[12:13], v[236:237]
	s_nop 0
	v_mul_f32_e32 v52, v1, v1
	v_pk_fma_f32 v[2:3], v[54:55], v[14:15], v[238:239]
	v_fmac_f32_e32 v52, v0, v0
	v_fmac_f32_e32 v52, v2, v2
	global_store_dwordx4 v[66:67], v[0:3], off offset:128
	v_fmac_f32_e32 v52, v3, v3
	v_add_f32_e32 v52, v56, v52
	v_pk_mul_f32 v[2:3], v[150:151], v[2:3]
	v_pk_mul_f32 v[0:1], v[148:149], v[0:1]
	s_nop 0
	v_cvt_pk_bf16_f32 v0, v0, v1
	v_cvt_pk_bf16_f32 v1, v2, v3
	v_lshlrev_b32_e32 v2, 4, v153
	v_add3_u32 v2, v146, v2, v147
	ds_write_b64 v2, v[0:1] offset:2048
	s_nop 1
	s_waitcnt vmcnt(3)
	v_pk_fma_f32 v[0:1], v[48:49], v[4:5], v[240:241]
	s_nop 0
	v_mul_f32_e32 v48, v1, v1
	v_pk_fma_f32 v[2:3], v[50:51], v[6:7], v[242:243]
	v_fmac_f32_e32 v48, v0, v0
	v_fmac_f32_e32 v48, v2, v2
	global_store_dwordx4 v[66:67], v[0:3], off offset:192
	v_fmac_f32_e32 v48, v3, v3
	v_add_f32_e32 v48, v52, v48
	v_pk_mul_f32 v[2:3], v[142:143], v[2:3]
	v_pk_mul_f32 v[0:1], v[144:145], v[0:1]
	s_nop 0
	v_cvt_pk_bf16_f32 v0, v0, v1
	v_cvt_pk_bf16_f32 v1, v2, v3
	v_lshlrev_b32_e32 v2, 4, v152
	v_add3_u32 v2, v146, v2, v147
	ds_write_b64 v2, v[0:1] offset:2048
	v_cndmask_b32_e32 v0, v202, v230, vcc
	v_lshlrev_b32_e32 v0, 2, v0
	ds_bpermute_b32 v0, v0, v48
	v_cmp_lt_i32_e32 vcc, v209, v203
	s_waitcnt lgkmcnt(0)
	v_add_f32_e32 v48, v48, v0
	v_cndmask_b32_e32 v0, v202, v209, vcc
	v_lshlrev_b32_e32 v0, 2, v0
	ds_bpermute_b32 v49, v0, v48
	v_cmp_gt_u32_e32 vcc, 16, v185
	s_and_saveexec_b64 s[4:5], vcc
	s_cbranch_execz .LBB0_231
	v_lshlrev_b64 v[0:1], 6, v[64:65]
	s_waitcnt lgkmcnt(0)
	v_add_f32_e32 v2, v48, v49
	v_lshl_add_u64 v[0:1], v[140:141], 0, v[0:1]
	global_store_dword v[0:1], v2, off

; DI unsigned pk2(float a, float b) { f32x2 v = {a, b}; bf2_t r = __builtin_convertvector(v, bf2_t); return __builtin_bit_cast(unsigned, r); }
;     static DI void run(const f32x4 (&acc)[8][4], const TileCtx& tc, const Params& p, ldsp_t wb) {
;     ...
;             for (int mm = 0; mm < 4; ++mm) { __builtin_amdgcn_sched_barrier(0);
;                 const int m = h * 4 + mm;
;                 const int row = tc.brow + tc.wr * 128 + m * 16 + tc.fr;
;                 float* xr = xrow_ptr(p, row) + col0;
;                 const float* xs = (EK == 1 && tc.l == 0) ? p.x + (size_t)row * DM + col0 : xr;
;                 float part = 0.f;
; #pragma unroll
;                 for (int n = 0; n < 4; ++n) {
;                     f32x4 xv = *(const f32x4*)(xs + n * 16);
;                     xv += gv[n] * acc[m][n];
;                     *(f32x4*)(xr + n * 16) = xv;
;                     if (has_next) {
;                         part += xv[0] * xv[0] + xv[1] * xv[1] + xv[2] * xv[2] + xv[3] * xv[3];
;                         const f32x4 hv = xv * av[n];
;                         u32x2 w; w[0] = pk2(hv[0], hv[1]); w[1] = pk2(hv[2], hv[3]);
;                         wave_put(wb, mm * 16 + tc.fr, n, tc.fq, w);
;                     }
;                 }
;                 if (has_next) {
;                     part += __shfl_xor(part, 16);
;                     part += __shfl_xor(part, 32);
;                     if (tc.fq == 0) ssp[(size_t)row * 16] = part;
;                 }
.LBB0_232:
	v_add_u32_e32 v48, 0x60, v132
	v_add_u32_e32 v0, 0xffffc060, v132
	s_waitcnt lgkmcnt(0)
	v_ashrrev_i32_e32 v49, 31, v48
	v_cmp_gt_i32_e32 vcc, s33, v48
	v_mov_b32_e32 v2, s71
	v_mov_b32_e32 v3, s55
	v_cndmask_b32_e32 v1, 0, v49, vcc
	v_cndmask_b32_e32 v0, v0, v48, vcc
	v_cndmask_b32_e32 v3, v2, v3, vcc
	v_mov_b32_e32 v2, s70
	v_mov_b32_e32 v50, s54
	v_cndmask_b32_e32 v2, v2, v50, vcc
	v_lshlrev_b64 v[0:1], 12, v[0:1]
	v_lshl_add_u64 v[0:1], v[2:3], 0, v[0:1]
	v_lshl_add_u64 v[50:51], v[176:177], 2, v[0:1]
	global_load_dwordx4 v[0:3], v[50:51], off
	global_load_dwordx4 v[232:235], v[50:51], off offset:64
	global_load_dwordx4 v[236:239], v[50:51], off offset:128
	global_load_dwordx4 v[240:243], v[50:51], off offset:192
	s_mov_b64 s[4:5], -1
	s_and_b64 vcc, exec, s[36:37]
	s_waitcnt vmcnt(3)
	v_pk_fma_f32 v[46:47], v[46:47], v[30:31], v[2:3]
	v_pk_fma_f32 v[44:45], v[44:45], v[28:29], v[0:1]
	global_store_dwordx4 v[50:51], v[44:47], off
	s_cbranch_vccz .LBB0_234
	s_nop 1
	s_mov_b64 s[4:5], 0
	s_waitcnt vmcnt(3)
	v_pk_fma_f32 v[2:3], v[42:43], v[22:23], v[234:235]
	v_pk_fma_f32 v[0:1], v[40:41], v[20:21], v[232:233]
	global_store_dwordx4 v[50:51], v[0:3], off offset:64
	s_nop 1
	s_waitcnt vmcnt(3)
	v_pk_fma_f32 v[2:3], v[38:39], v[14:15], v[238:239]
	v_pk_fma_f32 v[0:1], v[36:37], v[12:13], v[236:237]
	global_store_dwordx4 v[50:51], v[0:3], off offset:128
	s_nop 1
	s_waitcnt vmcnt(3)
	v_pk_fma_f32 v[2:3], v[34:35], v[6:7], v[242:243]
	v_pk_fma_f32 v[0:1], v[32:33], v[4:5], v[240:241]
	global_store_dwordx4 v[50:51], v[0:3], off offset:192
.LBB0_234:
	s_andn2_b64 vcc, exec, s[4:5]
	s_cbranch_vccnz .LBB0_238
	v_pk_mul_f32 v[0:1], v[166:167], v[46:47]
	v_pk_mul_f32 v[2:3], v[164:165], v[44:45]
	v_mul_f32_e32 v52, v45, v45
	v_cvt_pk_bf16_f32 v2, v2, v3
	v_cvt_pk_bf16_f32 v3, v0, v1
	v_lshlrev_b32_e32 v0, 4, v155
	v_add3_u32 v0, v146, v0, v147
	ds_write_b64 v0, v[2:3] offset:4096
	s_nop 1
	v_fmac_f32_e32 v52, v44, v44
	v_fmac_f32_e32 v52, v46, v46
	v_fmac_f32_e32 v52, v47, v47
	v_cmp_lt_i32_e32 vcc, v230, v203
	s_waitcnt vmcnt(3)
	v_pk_fma_f32 v[0:1], v[40:41], v[20:21], v[232:233]
	s_nop 0
	v_mul_f32_e32 v40, v1, v1
	v_pk_fma_f32 v[2:3], v[42:43], v[22:23], v[234:235]
	v_fmac_f32_e32 v40, v0, v0
	v_fmac_f32_e32 v40, v2, v2
	global_store_dwordx4 v[50:51], v[0:3], off offset:64
	v_fmac_f32_e32 v40, v3, v3
	v_add_f32_e32 v40, v52, v40
	v_pk_mul_f32 v[2:3], v[158:159], v[2:3]
	v_pk_mul_f32 v[0:1], v[156:157], v[0:1]
	s_nop 0
	v_cvt_pk_bf16_f32 v0, v0, v1
	v_cvt_pk_bf16_f32 v1, v2, v3
	v_lshlrev_b32_e32 v2, 4, v154
	v_add3_u32 v2, v146, v2, v147
	ds_write_b64 v2, v[0:1] offset:4096
	s_nop 1
	s_waitcnt vmcnt(3)
	v_pk_fma_f32 v[0:1], v[36:37], v[12:13], v[236:237]
	s_nop 0
	v_mul_f32_e32 v36, v1, v1
	v_pk_fma_f32 v[2:3], v[38:39], v[14:15], v[238:239]
	v_fmac_f32_e32 v36, v0, v0
	v_fmac_f32_e32 v36, v2, v2
	global_store_dwordx4 v[50:51], v[0:3], off offset:128
	v_fmac_f32_e32 v36, v3, v3
	v_add_f32_e32 v36, v40, v36
	v_pk_mul_f32 v[2:3], v[150:151], v[2:3]
	v_pk_mul_f32 v[0:1], v[148:149], v[0:1]
	s_nop 0
	v_cvt_pk_bf16_f32 v0, v0, v1
	v_cvt_pk_bf16_f32 v1, v2, v3
	v_lshlrev_b32_e32 v2, 4, v153
	v_add3_u32 v2, v146, v2, v147
	ds_write_b64 v2, v[0:1] offset:4096
	s_nop 1
	s_waitcnt vmcnt(3)
	v_pk_fma_f32 v[0:1], v[32:33], v[4:5], v[240:241]
	s_nop 0
	v_mul_f32_e32 v32, v1, v1
	v_pk_fma_f32 v[2:3], v[34:35], v[6:7], v[242:243]
	v_fmac_f32_e32 v32, v0, v0
	v_fmac_f32_e32 v32, v2, v2
	global_store_dwordx4 v[50:51], v[0:3], off offset:192
	v_fmac_f32_e32 v32, v3, v3
	v_add_f32_e32 v32, v36, v32
	v_pk_mul_f32 v[2:3], v[142:143], v[2:3]
	v_pk_mul_f32 v[0:1], v[144:145], v[0:1]
	s_nop 0
	v_cvt_pk_bf16_f32 v0, v0, v1
	v_cvt_pk_bf16_f32 v1, v2, v3
	v_lshlrev_b32_e32 v2, 4, v152
	v_add3_u32 v2, v146, v2, v147
	ds_write_b64 v2, v[0:1] offset:4096
	v_cndmask_b32_e32 v0, v202, v230, vcc
	v_lshlrev_b32_e32 v0, 2, v0
	ds_bpermute_b32 v0, v0, v32
	v_cmp_lt_i32_e32 vcc, v209, v203
	s_waitcnt lgkmcnt(0)
	v_add_f32_e32 v32, v32, v0
	v_cndmask_b32_e32 v0, v202, v209, vcc
	v_lshlrev_b32_e32 v0, 2, v0
	ds_bpermute_b32 v33, v0, v32
	v_cmp_gt_u32_e32 vcc, 16, v185
	s_and_saveexec_b64 s[4:5], vcc
	s_cbranch_execz .LBB0_237
	v_lshlrev_b64 v[0:1], 6, v[48:49]
	s_waitcnt lgkmcnt(0)
	v_add_f32_e32 v2, v32, v33
	v_lshl_add_u64 v[0:1], v[140:141], 0, v[0:1]
	global_store_dword v[0:1], v2, off

; DI unsigned pk2(float a, float b) { f32x2 v = {a, b}; bf2_t r = __builtin_convertvector(v, bf2_t); return __builtin_bit_cast(unsigned, r); }
;     static DI void run(const f32x4 (&acc)[8][4], const TileCtx& tc, const Params& p, ldsp_t wb) {
;     ...
;             for (int mm = 0; mm < 4; ++mm) { __builtin_amdgcn_sched_barrier(0);
;                 const int m = h * 4 + mm;
;                 const int row = tc.brow + tc.wr * 128 + m * 16 + tc.fr;
;                 float* xr = xrow_ptr(p, row) + col0;
;                 const float* xs = (EK == 1 && tc.l == 0) ? p.x + (size_t)row * DM + col0 : xr;
;                 float part = 0.f;
; #pragma unroll
;                 for (int n = 0; n < 4; ++n) {
;                     f32x4 xv = *(const f32x4*)(xs + n * 16);
;                     xv += gv[n] * acc[m][n];
;                     *(f32x4*)(xr + n * 16) = xv;
;                     if (has_next) {
;                         part += xv[0] * xv[0] + xv[1] * xv[1] + xv[2] * xv[2] + xv[3] * xv[3];
;                         const f32x4 hv = xv * av[n];
;                         u32x2 w; w[0] = pk2(hv[0], hv[1]); w[1] = pk2(hv[2], hv[3]);
;                         wave_put(wb, mm * 16 + tc.fr, n, tc.fq, w);
;                     }
;                 }
;                 if (has_next) {
;                     part += __shfl_xor(part, 16);
;                     part += __shfl_xor(part, 32);
;                     if (tc.fq == 0) ssp[(size_t)row * 16] = part;
;                 }
;             }
.LBB0_238:
	v_add_u32_e32 v32, 0x70, v132
	v_add_u32_e32 v0, 0xffffc070, v132
	s_waitcnt lgkmcnt(0)
	v_ashrrev_i32_e32 v33, 31, v32
	v_cmp_gt_i32_e32 vcc, s33, v32
	v_mov_b32_e32 v2, s71
	v_mov_b32_e32 v3, s55
	v_cndmask_b32_e32 v1, 0, v33, vcc
	v_cndmask_b32_e32 v0, v0, v32, vcc
	v_cndmask_b32_e32 v3, v2, v3, vcc
	v_mov_b32_e32 v2, s70
	v_mov_b32_e32 v34, s54
	v_cndmask_b32_e32 v2, v2, v34, vcc
	v_lshlrev_b64 v[0:1], 12, v[0:1]
	v_lshl_add_u64 v[0:1], v[2:3], 0, v[0:1]
	v_lshl_add_u64 v[34:35], v[176:177], 2, v[0:1]
	global_load_dwordx4 v[0:3], v[34:35], off
	global_load_dwordx4 v[232:235], v[34:35], off offset:64
	global_load_dwordx4 v[236:239], v[34:35], off offset:128
	global_load_dwordx4 v[240:243], v[34:35], off offset:192
	s_mov_b64 s[4:5], -1
	s_and_b64 vcc, exec, s[36:37]
	s_waitcnt vmcnt(3)
	v_pk_fma_f32 v[26:27], v[26:27], v[30:31], v[2:3]
	v_pk_fma_f32 v[24:25], v[24:25], v[28:29], v[0:1]
	global_store_dwordx4 v[34:35], v[24:27], off
	s_cbranch_vccz .LBB0_240
	s_nop 1
	s_mov_b64 s[4:5], 0
	s_waitcnt vmcnt(3)
	v_pk_fma_f32 v[2:3], v[18:19], v[22:23], v[234:235]
	v_pk_fma_f32 v[0:1], v[16:17], v[20:21], v[232:233]
	global_store_dwordx4 v[34:35], v[0:3], off offset:64
	s_nop 1
	s_waitcnt vmcnt(3)
	v_pk_fma_f32 v[2:3], v[10:11], v[14:15], v[238:239]
	v_pk_fma_f32 v[0:1], v[8:9], v[12:13], v[236:237]
	global_store_dwordx4 v[34:35], v[0:3], off offset:128
	s_nop 1
	s_waitcnt vmcnt(3)
	v_pk_fma_f32 v[2:3], v[70:71], v[6:7], v[242:243]
	v_pk_fma_f32 v[0:1], v[68:69], v[4:5], v[240:241]
	global_store_dwordx4 v[34:35], v[0:3], off offset:192
.LBB0_240:
	s_andn2_b64 vcc, exec, s[4:5]
	s_cbranch_vccnz .LBB0_183
	v_pk_mul_f32 v[0:1], v[166:167], v[26:27]
	v_pk_mul_f32 v[2:3], v[164:165], v[24:25]
	v_mul_f32_e32 v28, v25, v25
	v_cvt_pk_bf16_f32 v2, v2, v3
	v_cvt_pk_bf16_f32 v3, v0, v1
	v_lshlrev_b32_e32 v0, 4, v155
	v_add3_u32 v0, v146, v0, v147
	ds_write_b64 v0, v[2:3] offset:6144
	s_nop 1
	v_fmac_f32_e32 v28, v24, v24
	v_fmac_f32_e32 v28, v26, v26
	v_fmac_f32_e32 v28, v27, v27
	v_cmp_lt_i32_e32 vcc, v230, v203
	s_waitcnt vmcnt(3)
	v_pk_fma_f32 v[0:1], v[16:17], v[20:21], v[232:233]
	s_nop 0
	v_mul_f32_e32 v16, v1, v1
	v_pk_fma_f32 v[2:3], v[18:19], v[22:23], v[234:235]
	v_fmac_f32_e32 v16, v0, v0
	v_fmac_f32_e32 v16, v2, v2
	global_store_dwordx4 v[34:35], v[0:3], off offset:64
	v_fmac_f32_e32 v16, v3, v3
	v_add_f32_e32 v16, v28, v16
	v_pk_mul_f32 v[2:3], v[158:159], v[2:3]
	v_pk_mul_f32 v[0:1], v[156:157], v[0:1]
	s_nop 0
	v_cvt_pk_bf16_f32 v0, v0, v1
	v_cvt_pk_bf16_f32 v1, v2, v3
	v_lshlrev_b32_e32 v2, 4, v154
	v_add3_u32 v2, v146, v2, v147
	ds_write_b64 v2, v[0:1] offset:6144
	s_nop 1
	s_waitcnt vmcnt(3)
	v_pk_fma_f32 v[0:1], v[8:9], v[12:13], v[236:237]
	s_nop 0
	v_mul_f32_e32 v8, v1, v1
	v_pk_fma_f32 v[2:3], v[10:11], v[14:15], v[238:239]
	v_fmac_f32_e32 v8, v0, v0
	v_fmac_f32_e32 v8, v2, v2
	global_store_dwordx4 v[34:35], v[0:3], off offset:128
	v_fmac_f32_e32 v8, v3, v3
	v_add_f32_e32 v8, v16, v8
	v_pk_mul_f32 v[2:3], v[150:151], v[2:3]
	v_pk_mul_f32 v[0:1], v[148:149], v[0:1]
	s_nop 0
	v_cvt_pk_bf16_f32 v0, v0, v1
	v_cvt_pk_bf16_f32 v1, v2, v3
	v_lshlrev_b32_e32 v2, 4, v153
	v_add3_u32 v2, v146, v2, v147
	ds_write_b64 v2, v[0:1] offset:6144
	s_nop 1
	s_waitcnt vmcnt(3)
	v_pk_fma_f32 v[0:1], v[68:69], v[4:5], v[240:241]
	s_nop 0
	v_mul_f32_e32 v4, v1, v1
	v_pk_fma_f32 v[2:3], v[70:71], v[6:7], v[242:243]
	v_fmac_f32_e32 v4, v0, v0
	v_fmac_f32_e32 v4, v2, v2
	global_store_dwordx4 v[34:35], v[0:3], off offset:192
	v_fmac_f32_e32 v4, v3, v3
	v_add_f32_e32 v4, v8, v4
	v_pk_mul_f32 v[2:3], v[142:143], v[2:3]
	v_pk_mul_f32 v[0:1], v[144:145], v[0:1]
	s_nop 0
	v_cvt_pk_bf16_f32 v0, v0, v1
	v_cvt_pk_bf16_f32 v1, v2, v3
	v_lshlrev_b32_e32 v2, 4, v152
	v_add3_u32 v2, v146, v2, v147
	ds_write_b64 v2, v[0:1] offset:6144
	v_cndmask_b32_e32 v0, v202, v230, vcc
	v_lshlrev_b32_e32 v0, 2, v0
	ds_bpermute_b32 v0, v0, v4
	v_cmp_lt_i32_e32 vcc, v209, v203
	s_waitcnt lgkmcnt(0)
	v_add_f32_e32 v0, v4, v0
	v_cndmask_b32_e32 v1, v202, v209, vcc
	v_lshlrev_b32_e32 v1, 2, v1
	ds_bpermute_b32 v1, v1, v0
	v_cmp_gt_u32_e32 vcc, 16, v185
	s_and_saveexec_b64 s[4:5], vcc
	s_cbranch_execz .LBB0_182
	s_waitcnt lgkmcnt(0)
	v_add_f32_e32 v2, v0, v1
	v_lshlrev_b64 v[0:1], 6, v[32:33]
	v_lshl_add_u64 v[0:1], v[140:141], 0, v[0:1]
	global_store_dword v[0:1], v2, off
	s_branch .LBB0_182

; #define G_STAGE_B(Bp, buf, kt) do { const char* bb_ = (const char*)(Bp) + (size_t)(kt) * 128; \
;       _Pragma("unroll") for (int i = 0; i < 4; ++i) \
;         __builtin_amdgcn_global_load_lds((const unsigned*)(bb_ + soff[i]), (LDSP unsigned*)(G_SB(buf) + wid * 1024 + i * 8192), 16, 0, 0); } while (0)
; template <bool COOP>
; __global__ void __launch_bounds__(512) mk_kernel(Params p, int ph_lo, int ph_hi) {
;     __shared__ __attribute__((aligned(1024))) char smem_raw[2 * G_STAGE_B + 8192];
	.amdhsa_kernel _Z9mk_kernelILb1EEv6Paramsii
		.amdhsa_group_segment_fixed_size 139264
		.amdhsa_private_segment_fixed_size 0
		.amdhsa_kernarg_size 576
		.amdhsa_user_sgpr_count 2
		.amdhsa_user_sgpr_dispatch_ptr 0
		.amdhsa_user_sgpr_queue_ptr 0
		.amdhsa_user_sgpr_kernarg_segment_ptr 1
		.amdhsa_user_sgpr_dispatch_id 0
		.amdhsa_user_sgpr_kernarg_preload_length 0
		.amdhsa_user_sgpr_kernarg_preload_offset 0
		.amdhsa_user_sgpr_private_segment_size 0
		.amdhsa_uses_dynamic_stack 0
		.amdhsa_enable_private_segment 0
		.amdhsa_system_sgpr_workgroup_id_x 1
		.amdhsa_system_sgpr_workgroup_id_y 0
		.amdhsa_system_sgpr_workgroup_id_z 0
		.amdhsa_system_sgpr_workgroup_info 0
		.amdhsa_system_vgpr_workitem_id 2
		.amdhsa_next_free_vgpr 256
		.amdhsa_next_free_sgpr 102
		.amdhsa_accum_offset 256
		.amdhsa_reserve_vcc 1
		.amdhsa_float_round_mode_32 0
		.amdhsa_float_round_mode_16_64 0
		.amdhsa_float_denorm_mode_32 3
		.amdhsa_float_denorm_mode_16_64 3
		.amdhsa_dx10_clamp 1
		.amdhsa_ieee_mode 1
		.amdhsa_fp16_overflow 0
		.amdhsa_tg_split 0
		.amdhsa_exception_fp_ieee_invalid_op 0
		.amdhsa_exception_fp_denorm_src 0
		.amdhsa_exception_fp_ieee_div_zero 0
		.amdhsa_exception_fp_ieee_overflow 0
		.amdhsa_exception_fp_ieee_underflow 0
		.amdhsa_exception_fp_ieee_inexact 0
		.amdhsa_exception_int_div_zero 0
	.end_amdhsa_kernel

; #define G_STAGE_B(Bp, buf, kt) do { const char* bb_ = (const char*)(Bp) + (size_t)(kt) * 128; \
;       _Pragma("unroll") for (int i = 0; i < 4; ++i) \
;         __builtin_amdgcn_global_load_lds((const unsigned*)(bb_ + soff[i]), (LDSP unsigned*)(G_SB(buf) + wid * 1024 + i * 8192), 16, 0, 0); } while (0)
; template <bool COOP>
; __global__ void __launch_bounds__(512) mk_kernel(Params p, int ph_lo, int ph_hi) {
;     __shared__ __attribute__((aligned(1024))) char smem_raw[2 * G_STAGE_B + 8192];
amdhsa.kernels:
  - .agpr_count:     0
    .args:
      - .offset:         0
        .size:           312
        .value_kind:     by_value
      - .offset:         312
        .size:           4
        .value_kind:     by_value
      - .offset:         316
        .size:           4
        .value_kind:     by_value
      - .offset:         320
        .size:           4
        .value_kind:     hidden_block_count_x
      - .offset:         324
        .size:           4
        .value_kind:     hidden_block_count_y
      - .offset:         328
        .size:           4
        .value_kind:     hidden_block_count_z
      - .offset:         332
        .size:           2
        .value_kind:     hidden_group_size_x
      - .offset:         334
        .size:           2
        .value_kind:     hidden_group_size_y
      - .offset:         336
        .size:           2
        .value_kind:     hidden_group_size_z
      - .offset:         338
        .size:           2
        .value_kind:     hidden_remainder_x
      - .offset:         340
        .size:           2
        .value_kind:     hidden_remainder_y
      - .offset:         342
        .size:           2
        .value_kind:     hidden_remainder_z
      - .offset:         360
        .size:           8
        .value_kind:     hidden_global_offset_x
      - .offset:         368
        .size:           8
        .value_kind:     hidden_global_offset_y
      - .offset:         376
        .size:           8
        .value_kind:     hidden_global_offset_z
      - .offset:         384
        .size:           2
        .value_kind:     hidden_grid_dims
      - .offset:         408
        .size:           8
        .value_kind:     hidden_multigrid_sync_arg
    .group_segment_fixed_size: 139264
    .kernarg_segment_align: 8
    .kernarg_segment_size: 576
    .language:       OpenCL C
    .language_version:
      - 2
      - 0
    .max_flat_workgroup_size: 512
    .name:           _Z9mk_kernelILb1EEv6Paramsii
    .private_segment_fixed_size: 0
    .sgpr_count:     108
    .sgpr_spill_count: 158
    .symbol:         _Z9mk_kernelILb1EEv6Paramsii.kd
    .uniform_work_group_size: 1
    .uses_dynamic_stack: false
    .vgpr_count:     256
    .vgpr_spill_count: 0
    .wavefront_size: 64
